# strategy 7.4 step (a) only: K-loop flips kept; waves 0-3 get s_setprio 1 at entry and again after every K-loop
# speedup vs baseline: 1.0092x; 1.0002x over previous
; #define PG8_STAGE(bufoff, gbase, voff) do { _Pragma("unroll") for (int _i = 0; _i < 2; ++_i) \
;         __builtin_amdgcn_global_load_lds((const unsigned*)((const char*)(gbase) + (voff)[_i]), (PG8_LAS unsigned*)(lds + (bufoff) + ldsw + _i * 8192), 16, 0, 0); } while (0)
; #define PG8_LDA(dst, b, h) do { _Pragma("unroll") for (int m = 0; m < 4; ++m) _Pragma("unroll") for (int k = 0; k < 2; ++k) dst[m][k] = *(const PG8_LAS bf16x8*)(lds + PG8_SA(b, h) + aoff + m * 2048 + k * 1024); } while (0)
; #define PG8_LDB(dst, b, h) do { _Pragma("unroll") for (int n = 0; n < 2; ++n) _Pragma("unroll") for (int k = 0; k < 2; ++k) dst[n][k] = *(const PG8_LAS bf16x8*)(lds + PG8_SB(b, h) + boff + n * 2048 + k * 1024); } while (0)
; #define PG8_MMA(ai, bj, At, Bt) do { __builtin_amdgcn_s_setprio(1); _Pragma("unroll") for (int m = 0; m < 4; ++m) _Pragma("unroll") for (int n = 0; n < 2; ++n) _Pragma("unroll") for (int k = 0; k < 2; ++k) \
;         acc[ai][bj][m][n] = __builtin_amdgcn_mfma_f32_16x16x32_bf16(Bt[n][k], At[m][k], acc[ai][bj][m][n], 0, 0, 0); __builtin_amdgcn_s_setprio(0); } while (0)
; #define PG8_WAIT_V(n) asm volatile("s_waitcnt vmcnt(" #n ")" ::: "memory")
; #define PG8_WAIT_L(n) asm volatile("s_waitcnt lgkmcnt(" #n ")" ::: "memory")
; template <class Epi, class Sched, bool ALIGN_EPI = false, bool SP2 = false>
; __device__ __forceinline__ void gemm_phase(PG8_LAS unsigned char* lds, const Gemm g, const Sched& S, const Epi& E) {
;     ...
;             const bool last = (t == nt - 2);
;             const char* a1 = cA + (size_t)(t + 1) * kstep;
;             const char* a2 = last ? nA : cA + (size_t)(t + 2) * kstep; const char* b2 = last ? nB : cB + (size_t)(t + 2) * kstep;
;             const char* a3 = a2 + kstep; const char* b3 = b2 + kstep;
;             if (last && has_next) S.a_ready(nxt);
;             if constexpr (SP2) {
;             PG8_LDB(B0, 0, 0); PG8_LDB(B1, 0, 1); PG8_SCHED; PG8_LDA(At, 0, 0); PG8_STAGE(PG8_SA(1, 1), a1 + hstep, voffA);
;             PG8_WAIT_V(8); PG8_WAIT_L(0); PG8_BAR; PG8_MMA(0, 0, At, B0); PG8_MMA(0, 1, At, B1); PG8_BAR; PG8_SCHED;
;             PG8_LDA(At, 0, 1); PG8_STAGE(PG8_SB(0, 0), b2, voffB); PG8_STAGE(PG8_SB(0, 1), b2 + hstep, voffB); PG8_STAGE(PG8_SA(0, 0), a2, voffA);
;             PG8_WAIT_V(8); PG8_WAIT_L(0); PG8_BAR; PG8_MMA(1, 0, At, B0); PG8_MMA(1, 1, At, B1); PG8_BAR; PG8_SCHED;
.LBB0_289:
	ds_read_b128 v[146:149], v156
	ds_read_b128 v[160:163], v156 offset:1024
	ds_read_b128 v[164:167], v156 offset:2048
	ds_read_b128 v[168:171], v156 offset:3072
	ds_read_b128 v[180:183], v157
	ds_read_b128 v[184:187], v157 offset:1024
	ds_read_b128 v[188:191], v157 offset:2048
	ds_read_b128 v[192:195], v157 offset:3072
	s_add_u32 s24, s22, 0xfff80080
	s_addc_u32 s25, s23, -1
	s_cmp_eq_u32 s50, 28
	s_cselect_b32 s27, s15, s25
	s_cselect_b32 s26, s46, s24
	s_cselect_b32 s25, s13, s49
	s_cselect_b32 s24, s47, s48
	v_lshl_add_u64 v[150:151], s[22:23], 0, v[138:139]
	s_add_i32 m0, s21, 0xc000
	ds_read_b128 v[196:199], v158
	ds_read_b128 v[200:203], v158 offset:1024
	ds_read_b128 v[204:207], v158 offset:2048
	ds_read_b128 v[208:211], v158 offset:3072
	ds_read_b128 v[212:215], v158 offset:4096
	ds_read_b128 v[216:219], v158 offset:5120
	ds_read_b128 v[220:223], v158 offset:6144
	ds_read_b128 v[224:227], v158 offset:7168
	global_load_lds_dwordx4 v[150:151], off
	v_lshl_add_u64 v[150:151], s[22:23], 0, v[140:141]
	s_add_i32 m0, s21, 0xe000
	s_nop 0
	global_load_lds_dwordx4 v[150:151], off
	s_waitcnt vmcnt(8)
	s_waitcnt lgkmcnt(0)
	s_barrier
	s_setprio 1
	s_waitcnt lgkmcnt(0)
	v_mfma_f32_16x16x32_bf16 v[124:127], v[146:149], v[196:199], v[124:127]
	v_mfma_f32_16x16x32_bf16 v[120:123], v[164:167], v[196:199], v[120:123]
	v_mfma_f32_16x16x32_bf16 v[116:119], v[146:149], v[204:207], v[116:119]
	v_mfma_f32_16x16x32_bf16 v[108:111], v[164:167], v[204:207], v[108:111]
	v_mfma_f32_16x16x32_bf16 v[100:103], v[146:149], v[212:215], v[100:103]
	v_mfma_f32_16x16x32_bf16 v[92:95], v[164:167], v[212:215], v[92:95]
	v_mfma_f32_16x16x32_bf16 v[84:87], v[146:149], v[220:223], v[84:87]
	v_mfma_f32_16x16x32_bf16 v[76:79], v[164:167], v[220:223], v[76:79]
	v_mfma_f32_16x16x32_bf16 v[124:127], v[160:163], v[200:203], v[124:127]
	v_mfma_f32_16x16x32_bf16 v[120:123], v[168:171], v[200:203], v[120:123]
	v_mfma_f32_16x16x32_bf16 v[116:119], v[160:163], v[208:211], v[116:119]
	v_mfma_f32_16x16x32_bf16 v[108:111], v[168:171], v[208:211], v[108:111]
	v_mfma_f32_16x16x32_bf16 v[100:103], v[160:163], v[216:219], v[100:103]
	v_mfma_f32_16x16x32_bf16 v[92:95], v[168:171], v[216:219], v[92:95]
	v_mfma_f32_16x16x32_bf16 v[84:87], v[160:163], v[224:227], v[84:87]
	v_mfma_f32_16x16x32_bf16 v[76:79], v[168:171], v[224:227], v[76:79]
	s_setprio 0
	s_setprio 1
	v_mfma_f32_16x16x32_bf16 v[112:115], v[180:183], v[196:199], v[112:115]
	v_mfma_f32_16x16x32_bf16 v[104:107], v[188:191], v[196:199], v[104:107]
	v_mfma_f32_16x16x32_bf16 v[96:99], v[180:183], v[204:207], v[96:99]
	v_mfma_f32_16x16x32_bf16 v[88:91], v[188:191], v[204:207], v[88:91]
	v_mfma_f32_16x16x32_bf16 v[80:83], v[180:183], v[212:215], v[80:83]
	v_mfma_f32_16x16x32_bf16 v[72:75], v[188:191], v[212:215], v[72:75]
	v_mfma_f32_16x16x32_bf16 v[68:71], v[180:183], v[220:223], v[68:71]
	v_mfma_f32_16x16x32_bf16 v[64:67], v[188:191], v[220:223], v[64:67]
	v_mfma_f32_16x16x32_bf16 v[112:115], v[184:187], v[200:203], v[112:115]
	v_mfma_f32_16x16x32_bf16 v[104:107], v[192:195], v[200:203], v[104:107]
	v_mfma_f32_16x16x32_bf16 v[96:99], v[184:187], v[208:211], v[96:99]
	v_mfma_f32_16x16x32_bf16 v[88:91], v[192:195], v[208:211], v[88:91]
	v_mfma_f32_16x16x32_bf16 v[80:83], v[184:187], v[216:219], v[80:83]
	v_mfma_f32_16x16x32_bf16 v[72:75], v[192:195], v[216:219], v[72:75]
	v_mfma_f32_16x16x32_bf16 v[68:71], v[184:187], v[224:227], v[68:71]
	v_mfma_f32_16x16x32_bf16 v[64:67], v[192:195], v[224:227], v[64:67]
	s_setprio 0
	s_barrier
	s_add_i32 s51, s40, s30
	v_lshl_add_u64 v[150:151], s[24:25], 0, v[134:135]
	s_mov_b32 m0, s51
	ds_read_b128 v[196:199], v158 offset:16384
	ds_read_b128 v[200:203], v158 offset:17408
	ds_read_b128 v[204:207], v158 offset:18432
	ds_read_b128 v[208:211], v158 offset:19456
	ds_read_b128 v[212:215], v158 offset:20480
	ds_read_b128 v[216:219], v158 offset:21504
	ds_read_b128 v[220:223], v158 offset:22528
	ds_read_b128 v[224:227], v158 offset:23552
	global_load_lds_dwordx4 v[150:151], off
	s_add_i32 m0, s51, 0x2000
	s_add_u32 s52, s24, 0x80000
	v_lshl_add_u64 v[228:229], s[24:25], 0, v[130:131]
	s_addc_u32 s53, s25, 0
	s_add_i32 s51, s41, s30
	global_load_lds_dwordx4 v[228:229], off
	v_lshl_add_u64 v[230:231], s[52:53], 0, v[134:135]
	s_mov_b32 m0, s51
	v_lshl_add_u64 v[232:233], s[26:27], 0, v[132:133]
	global_load_lds_dwordx4 v[230:231], off
	v_lshl_add_u64 v[230:231], s[52:53], 0, v[130:131]
	s_add_i32 m0, s51, 0x2000
	s_nop 0
	global_load_lds_dwordx4 v[230:231], off
	v_lshl_add_u64 v[230:231], s[26:27], 0, v[136:137]
	s_mov_b32 m0, s21
	s_nop 0
	global_load_lds_dwordx4 v[230:231], off
	s_mov_b32 m0, s33
	s_nop 0
	global_load_lds_dwordx4 v[232:233], off
	s_waitcnt vmcnt(8)
	s_waitcnt lgkmcnt(0)
	s_barrier
; #define PG8_STAGE(bufoff, gbase, voff) do { _Pragma("unroll") for (int _i = 0; _i < 2; ++_i) \
;         __builtin_amdgcn_global_load_lds((const unsigned*)((const char*)(gbase) + (voff)[_i]), (PG8_LAS unsigned*)(lds + (bufoff) + ldsw + _i * 8192), 16, 0, 0); } while (0)
; #define PG8_LDA(dst, b, h) do { _Pragma("unroll") for (int m = 0; m < 4; ++m) _Pragma("unroll") for (int k = 0; k < 2; ++k) dst[m][k] = *(const PG8_LAS bf16x8*)(lds + PG8_SA(b, h) + aoff + m * 2048 + k * 1024); } while (0)
; #define PG8_LDB(dst, b, h) do { _Pragma("unroll") for (int n = 0; n < 2; ++n) _Pragma("unroll") for (int k = 0; k < 2; ++k) dst[n][k] = *(const PG8_LAS bf16x8*)(lds + PG8_SB(b, h) + boff + n * 2048 + k * 1024); } while (0)
; #define PG8_MMA(ai, bj, At, Bt) do { __builtin_amdgcn_s_setprio(1); _Pragma("unroll") for (int m = 0; m < 4; ++m) _Pragma("unroll") for (int n = 0; n < 2; ++n) _Pragma("unroll") for (int k = 0; k < 2; ++k) \
;         acc[ai][bj][m][n] = __builtin_amdgcn_mfma_f32_16x16x32_bf16(Bt[n][k], At[m][k], acc[ai][bj][m][n], 0, 0, 0); __builtin_amdgcn_s_setprio(0); } while (0)
; #define PG8_WAIT_V(n) asm volatile("s_waitcnt vmcnt(" #n ")" ::: "memory")
; #define PG8_WAIT_L(n) asm volatile("s_waitcnt lgkmcnt(" #n ")" ::: "memory")
; #define PG8_BAR __builtin_amdgcn_s_barrier()
; #define PG8_SCHED __builtin_amdgcn_sched_barrier(0)
; template <class Epi, class Sched, bool ALIGN_EPI = false, bool SP2 = false>
; __device__ __forceinline__ void gemm_phase(PG8_LAS unsigned char* lds, const Gemm g, const Sched& S, const Epi& E) {
;     ...
;             PG8_WAIT_V(8); PG8_WAIT_L(0); PG8_BAR; PG8_MMA(1, 0, At, B0); PG8_MMA(1, 1, At, B1); PG8_BAR; PG8_SCHED;
;             PG8_LDB(B0, 1, 0); PG8_LDB(B1, 1, 1); PG8_SCHED; PG8_LDA(At, 1, 0); PG8_STAGE(PG8_SA(0, 1), a2 + hstep, voffA);
;             PG8_WAIT_V(8); PG8_WAIT_L(0); PG8_BAR; PG8_MMA(0, 0, At, B0); PG8_MMA(0, 1, At, B1); PG8_BAR; PG8_SCHED;
	s_setprio 1
	s_waitcnt lgkmcnt(0)
	v_mfma_f32_16x16x32_bf16 v[60:63], v[146:149], v[196:199], v[60:63]
	v_mfma_f32_16x16x32_bf16 v[56:59], v[164:167], v[196:199], v[56:59]
	v_mfma_f32_16x16x32_bf16 v[52:55], v[146:149], v[204:207], v[52:55]
	v_mfma_f32_16x16x32_bf16 v[44:47], v[164:167], v[204:207], v[44:47]
	v_mfma_f32_16x16x32_bf16 v[36:39], v[146:149], v[212:215], v[36:39]
	v_mfma_f32_16x16x32_bf16 v[28:31], v[164:167], v[212:215], v[28:31]
	v_mfma_f32_16x16x32_bf16 v[20:23], v[146:149], v[220:223], v[20:23]
	v_mfma_f32_16x16x32_bf16 v[12:15], v[164:167], v[220:223], v[12:15]
	v_mfma_f32_16x16x32_bf16 v[60:63], v[160:163], v[200:203], v[60:63]
	v_mfma_f32_16x16x32_bf16 v[56:59], v[168:171], v[200:203], v[56:59]
	v_mfma_f32_16x16x32_bf16 v[52:55], v[160:163], v[208:211], v[52:55]
	v_mfma_f32_16x16x32_bf16 v[44:47], v[168:171], v[208:211], v[44:47]
	v_mfma_f32_16x16x32_bf16 v[36:39], v[160:163], v[216:219], v[36:39]
	v_mfma_f32_16x16x32_bf16 v[28:31], v[168:171], v[216:219], v[28:31]
	v_mfma_f32_16x16x32_bf16 v[20:23], v[160:163], v[224:227], v[20:23]
	v_mfma_f32_16x16x32_bf16 v[12:15], v[168:171], v[224:227], v[12:15]
	s_setprio 0
	s_setprio 1
	v_mfma_f32_16x16x32_bf16 v[48:51], v[180:183], v[196:199], v[48:51]
	v_mfma_f32_16x16x32_bf16 v[40:43], v[188:191], v[196:199], v[40:43]
	v_mfma_f32_16x16x32_bf16 v[32:35], v[180:183], v[204:207], v[32:35]
	v_mfma_f32_16x16x32_bf16 v[24:27], v[188:191], v[204:207], v[24:27]
	v_mfma_f32_16x16x32_bf16 v[16:19], v[180:183], v[212:215], v[16:19]
	v_mfma_f32_16x16x32_bf16 v[8:11], v[188:191], v[212:215], v[8:11]
	v_mfma_f32_16x16x32_bf16 v[4:7], v[180:183], v[220:223], v[4:7]
	v_mfma_f32_16x16x32_bf16 v[0:3], v[188:191], v[220:223], v[0:3]
	v_mfma_f32_16x16x32_bf16 v[48:51], v[184:187], v[200:203], v[48:51]
	v_mfma_f32_16x16x32_bf16 v[40:43], v[192:195], v[200:203], v[40:43]
	v_mfma_f32_16x16x32_bf16 v[32:35], v[184:187], v[208:211], v[32:35]
	v_mfma_f32_16x16x32_bf16 v[24:27], v[192:195], v[208:211], v[24:27]
	v_mfma_f32_16x16x32_bf16 v[16:19], v[184:187], v[216:219], v[16:19]
	v_mfma_f32_16x16x32_bf16 v[8:11], v[192:195], v[216:219], v[8:11]
	v_mfma_f32_16x16x32_bf16 v[4:7], v[184:187], v[224:227], v[4:7]
	v_mfma_f32_16x16x32_bf16 v[0:3], v[192:195], v[224:227], v[0:3]
	s_setprio 0
	s_barrier
	s_add_i32 s51, 0, 0x18000
	v_add_u32_e32 v159, s51, v153
	s_add_i32 s52, 0, 0x1c000
	ds_read_b128 v[146:149], v159
	ds_read_b128 v[160:163], v159 offset:1024
	ds_read_b128 v[164:167], v159 offset:2048
	ds_read_b128 v[168:171], v159 offset:3072
	v_add_u32_e32 v159, s52, v153
	ds_read_b128 v[180:183], v159
	ds_read_b128 v[184:187], v159 offset:1024
	ds_read_b128 v[188:191], v159 offset:2048
	ds_read_b128 v[192:195], v159 offset:3072
	s_add_u32 s26, s26, 0x80000
	s_addc_u32 s27, s27, 0
	s_mov_b32 m0, s34
	v_lshl_add_u64 v[234:235], s[26:27], 0, v[136:137]
	ds_read_b128 v[196:199], v158 offset:32768
	ds_read_b128 v[200:203], v158 offset:33792
	ds_read_b128 v[204:207], v158 offset:34816
	ds_read_b128 v[208:211], v158 offset:35840
	ds_read_b128 v[212:215], v158 offset:36864
	ds_read_b128 v[216:219], v158 offset:37888
	ds_read_b128 v[220:223], v158 offset:38912
	ds_read_b128 v[224:227], v158 offset:39936
	global_load_lds_dwordx4 v[234:235], off
	v_lshl_add_u64 v[234:235], s[26:27], 0, v[132:133]
	s_mov_b32 m0, s35
	s_nop 0
	global_load_lds_dwordx4 v[234:235], off
	s_waitcnt vmcnt(8)
	s_waitcnt lgkmcnt(0)
	s_barrier
	s_setprio 1
	s_waitcnt lgkmcnt(0)
	v_mfma_f32_16x16x32_bf16 v[124:127], v[146:149], v[196:199], v[124:127]
	v_mfma_f32_16x16x32_bf16 v[120:123], v[164:167], v[196:199], v[120:123]
	v_mfma_f32_16x16x32_bf16 v[116:119], v[146:149], v[204:207], v[116:119]
	v_mfma_f32_16x16x32_bf16 v[108:111], v[164:167], v[204:207], v[108:111]
	v_mfma_f32_16x16x32_bf16 v[100:103], v[146:149], v[212:215], v[100:103]
	v_mfma_f32_16x16x32_bf16 v[92:95], v[164:167], v[212:215], v[92:95]
	v_mfma_f32_16x16x32_bf16 v[84:87], v[146:149], v[220:223], v[84:87]
	v_mfma_f32_16x16x32_bf16 v[76:79], v[164:167], v[220:223], v[76:79]
	v_mfma_f32_16x16x32_bf16 v[124:127], v[160:163], v[200:203], v[124:127]
	v_mfma_f32_16x16x32_bf16 v[120:123], v[168:171], v[200:203], v[120:123]
	v_mfma_f32_16x16x32_bf16 v[116:119], v[160:163], v[208:211], v[116:119]
	v_mfma_f32_16x16x32_bf16 v[108:111], v[168:171], v[208:211], v[108:111]
	v_mfma_f32_16x16x32_bf16 v[100:103], v[160:163], v[216:219], v[100:103]
	v_mfma_f32_16x16x32_bf16 v[92:95], v[168:171], v[216:219], v[92:95]
	v_mfma_f32_16x16x32_bf16 v[84:87], v[160:163], v[224:227], v[84:87]
	v_mfma_f32_16x16x32_bf16 v[76:79], v[168:171], v[224:227], v[76:79]
	s_setprio 0
	s_setprio 1
	v_mfma_f32_16x16x32_bf16 v[112:115], v[180:183], v[196:199], v[112:115]
	v_mfma_f32_16x16x32_bf16 v[104:107], v[188:191], v[196:199], v[104:107]
	v_mfma_f32_16x16x32_bf16 v[96:99], v[180:183], v[204:207], v[96:99]
	v_mfma_f32_16x16x32_bf16 v[88:91], v[188:191], v[204:207], v[88:91]
	v_mfma_f32_16x16x32_bf16 v[80:83], v[180:183], v[212:215], v[80:83]
	v_mfma_f32_16x16x32_bf16 v[72:75], v[188:191], v[212:215], v[72:75]
	v_mfma_f32_16x16x32_bf16 v[68:71], v[180:183], v[220:223], v[68:71]
	v_mfma_f32_16x16x32_bf16 v[64:67], v[188:191], v[220:223], v[64:67]
	v_mfma_f32_16x16x32_bf16 v[112:115], v[184:187], v[200:203], v[112:115]
	v_mfma_f32_16x16x32_bf16 v[104:107], v[192:195], v[200:203], v[104:107]
	v_mfma_f32_16x16x32_bf16 v[96:99], v[184:187], v[208:211], v[96:99]
	v_mfma_f32_16x16x32_bf16 v[88:91], v[192:195], v[208:211], v[88:91]
	v_mfma_f32_16x16x32_bf16 v[80:83], v[184:187], v[216:219], v[80:83]
	v_mfma_f32_16x16x32_bf16 v[72:75], v[192:195], v[216:219], v[72:75]
	v_mfma_f32_16x16x32_bf16 v[68:71], v[184:187], v[224:227], v[68:71]
	v_mfma_f32_16x16x32_bf16 v[64:67], v[192:195], v[224:227], v[64:67]
	s_setprio 0
	s_barrier
; #define PG8_STAGE(bufoff, gbase, voff) do { _Pragma("unroll") for (int _i = 0; _i < 2; ++_i) \
;         __builtin_amdgcn_global_load_lds((const unsigned*)((const char*)(gbase) + (voff)[_i]), (PG8_LAS unsigned*)(lds + (bufoff) + ldsw + _i * 8192), 16, 0, 0); } while (0)
; #define PG8_LDA(dst, b, h) do { _Pragma("unroll") for (int m = 0; m < 4; ++m) _Pragma("unroll") for (int k = 0; k < 2; ++k) dst[m][k] = *(const PG8_LAS bf16x8*)(lds + PG8_SA(b, h) + aoff + m * 2048 + k * 1024); } while (0)
; #define PG8_MMA(ai, bj, At, Bt) do { __builtin_amdgcn_s_setprio(1); _Pragma("unroll") for (int m = 0; m < 4; ++m) _Pragma("unroll") for (int n = 0; n < 2; ++n) _Pragma("unroll") for (int k = 0; k < 2; ++k) \
;         acc[ai][bj][m][n] = __builtin_amdgcn_mfma_f32_16x16x32_bf16(Bt[n][k], At[m][k], acc[ai][bj][m][n], 0, 0, 0); __builtin_amdgcn_s_setprio(0); } while (0)
; #define PG8_WAIT_V(n) asm volatile("s_waitcnt vmcnt(" #n ")" ::: "memory")
; #define PG8_WAIT_L(n) asm volatile("s_waitcnt lgkmcnt(" #n ")" ::: "memory")
; #define PG8_BAR __builtin_amdgcn_s_barrier()
; #define PG8_SCHED __builtin_amdgcn_sched_barrier(0)
; template <class Epi, class Sched, bool ALIGN_EPI = false, bool SP2 = false>
; __device__ __forceinline__ void gemm_phase(PG8_LAS unsigned char* lds, const Gemm g, const Sched& S, const Epi& E) {
;     ...
;             PG8_LDA(At, 1, 1); PG8_STAGE(PG8_SB(1, 0), b3, voffB); PG8_STAGE(PG8_SB(1, 1), b3 + hstep, voffB); PG8_STAGE(PG8_SA(1, 0), a3, voffA);
;             PG8_WAIT_V(8); PG8_WAIT_L(0); PG8_BAR; PG8_MMA(1, 0, At, B0); PG8_MMA(1, 1, At, B1); PG8_BAR; PG8_SCHED;
;     ...
;         if constexpr (ALIGN_EPI) { if (wr == 0) PG8_BAR; }
	s_add_i32 s26, s51, s30
	v_lshl_add_u64 v[150:151], v[150:151], 0, s[2:3]
	s_mov_b32 m0, s26
	ds_read_b128 v[196:199], v158 offset:49152
	ds_read_b128 v[200:203], v158 offset:50176
	ds_read_b128 v[204:207], v158 offset:51200
	ds_read_b128 v[208:211], v158 offset:52224
	ds_read_b128 v[212:215], v158 offset:53248
	ds_read_b128 v[216:219], v158 offset:54272
	ds_read_b128 v[220:223], v158 offset:55296
	ds_read_b128 v[224:227], v158 offset:56320
	global_load_lds_dwordx4 v[150:151], off
	s_add_i32 m0, s26, 0x2000
	s_add_u32 s24, s24, 0x80080
	v_lshl_add_u64 v[150:151], v[228:229], 0, s[2:3]
	s_addc_u32 s25, s25, 0
	s_add_i32 s26, s52, s30
	global_load_lds_dwordx4 v[150:151], off
	v_lshl_add_u64 v[150:151], s[24:25], 0, v[134:135]
	s_mov_b32 m0, s26
	s_nop 0
	global_load_lds_dwordx4 v[150:151], off
	v_lshl_add_u64 v[150:151], s[24:25], 0, v[130:131]
	s_add_i32 m0, s26, 0x2000
	s_nop 0
	global_load_lds_dwordx4 v[150:151], off
	v_lshl_add_u64 v[150:151], v[230:231], 0, s[2:3]
	s_mov_b32 m0, s36
	s_nop 0
	global_load_lds_dwordx4 v[150:151], off
	v_lshl_add_u64 v[150:151], v[232:233], 0, s[2:3]
	s_mov_b32 m0, s37
	s_nop 0
	global_load_lds_dwordx4 v[150:151], off
	s_waitcnt vmcnt(8)
	s_waitcnt lgkmcnt(0)
	s_barrier
	s_setprio 1
	s_waitcnt lgkmcnt(0)
	v_mfma_f32_16x16x32_bf16 v[60:63], v[146:149], v[196:199], v[60:63]
	v_mfma_f32_16x16x32_bf16 v[56:59], v[164:167], v[196:199], v[56:59]
	v_mfma_f32_16x16x32_bf16 v[52:55], v[146:149], v[204:207], v[52:55]
	v_mfma_f32_16x16x32_bf16 v[44:47], v[164:167], v[204:207], v[44:47]
	v_mfma_f32_16x16x32_bf16 v[36:39], v[146:149], v[212:215], v[36:39]
	v_mfma_f32_16x16x32_bf16 v[28:31], v[164:167], v[212:215], v[28:31]
	v_mfma_f32_16x16x32_bf16 v[20:23], v[146:149], v[220:223], v[20:23]
	v_mfma_f32_16x16x32_bf16 v[12:15], v[164:167], v[220:223], v[12:15]
	v_mfma_f32_16x16x32_bf16 v[60:63], v[160:163], v[200:203], v[60:63]
	v_mfma_f32_16x16x32_bf16 v[56:59], v[168:171], v[200:203], v[56:59]
	v_mfma_f32_16x16x32_bf16 v[52:55], v[160:163], v[208:211], v[52:55]
	v_mfma_f32_16x16x32_bf16 v[44:47], v[168:171], v[208:211], v[44:47]
	v_mfma_f32_16x16x32_bf16 v[36:39], v[160:163], v[216:219], v[36:39]
	v_mfma_f32_16x16x32_bf16 v[28:31], v[168:171], v[216:219], v[28:31]
	v_mfma_f32_16x16x32_bf16 v[20:23], v[160:163], v[224:227], v[20:23]
	v_mfma_f32_16x16x32_bf16 v[12:15], v[168:171], v[224:227], v[12:15]
	s_setprio 0
	s_setprio 1
	v_mfma_f32_16x16x32_bf16 v[48:51], v[180:183], v[196:199], v[48:51]
	v_mfma_f32_16x16x32_bf16 v[40:43], v[188:191], v[196:199], v[40:43]
	v_mfma_f32_16x16x32_bf16 v[32:35], v[180:183], v[204:207], v[32:35]
	v_mfma_f32_16x16x32_bf16 v[24:27], v[188:191], v[204:207], v[24:27]
	v_mfma_f32_16x16x32_bf16 v[16:19], v[180:183], v[212:215], v[16:19]
	v_mfma_f32_16x16x32_bf16 v[8:11], v[188:191], v[212:215], v[8:11]
	v_mfma_f32_16x16x32_bf16 v[4:7], v[180:183], v[220:223], v[4:7]
	v_mfma_f32_16x16x32_bf16 v[0:3], v[188:191], v[220:223], v[0:3]
	v_mfma_f32_16x16x32_bf16 v[48:51], v[184:187], v[200:203], v[48:51]
	v_mfma_f32_16x16x32_bf16 v[40:43], v[192:195], v[200:203], v[40:43]
	v_mfma_f32_16x16x32_bf16 v[32:35], v[184:187], v[208:211], v[32:35]
	v_mfma_f32_16x16x32_bf16 v[24:27], v[192:195], v[208:211], v[24:27]
	v_mfma_f32_16x16x32_bf16 v[16:19], v[184:187], v[216:219], v[16:19]
	v_mfma_f32_16x16x32_bf16 v[8:11], v[192:195], v[216:219], v[8:11]
	v_mfma_f32_16x16x32_bf16 v[4:7], v[184:187], v[224:227], v[4:7]
	v_mfma_f32_16x16x32_bf16 v[0:3], v[192:195], v[224:227], v[0:3]
	s_setprio 0
	s_barrier
	s_add_i32 s50, s50, 2
	s_add_u32 s22, s22, 0x100
	s_addc_u32 s23, s23, 0
	s_add_u32 s48, s48, 0x100
	s_addc_u32 s49, s49, 0
	s_cmp_gt_u32 s50, 29
	s_cbranch_scc0 .LBB0_289
	s_nop 0
	v_readfirstlane_b32 s15, v172
	s_nop 3
	s_lshr_b32 s15, s15, 6
	s_cmp_lt_u32 s15, 4
	s_cbranch_scc0 .Lprio_k0
	s_setprio 1
.Lprio_k0:
	s_and_b64 vcc, exec, s[4:5]
	s_cbranch_vccz .LBB0_292
	s_barrier

; #define PG8_STAGE(bufoff, gbase, voff) do { _Pragma("unroll") for (int _i = 0; _i < 2; ++_i) \
;         __builtin_amdgcn_global_load_lds((const unsigned*)((const char*)(gbase) + (voff)[_i]), (PG8_LAS unsigned*)(lds + (bufoff) + ldsw + _i * 8192), 16, 0, 0); } while (0)
; #define PG8_LDA(dst, b, h) do { _Pragma("unroll") for (int m = 0; m < 4; ++m) _Pragma("unroll") for (int k = 0; k < 2; ++k) dst[m][k] = *(const PG8_LAS bf16x8*)(lds + PG8_SA(b, h) + aoff + m * 2048 + k * 1024); } while (0)
; #define PG8_LDB(dst, b, h) do { _Pragma("unroll") for (int n = 0; n < 2; ++n) _Pragma("unroll") for (int k = 0; k < 2; ++k) dst[n][k] = *(const PG8_LAS bf16x8*)(lds + PG8_SB(b, h) + boff + n * 2048 + k * 1024); } while (0)
; #define PG8_MMA(ai, bj, At, Bt) do { __builtin_amdgcn_s_setprio(1); _Pragma("unroll") for (int m = 0; m < 4; ++m) _Pragma("unroll") for (int n = 0; n < 2; ++n) _Pragma("unroll") for (int k = 0; k < 2; ++k) \
;         acc[ai][bj][m][n] = __builtin_amdgcn_mfma_f32_16x16x32_bf16(Bt[n][k], At[m][k], acc[ai][bj][m][n], 0, 0, 0); __builtin_amdgcn_s_setprio(0); } while (0)
; #define PG8_WAIT_V(n) asm volatile("s_waitcnt vmcnt(" #n ")" ::: "memory")
; #define PG8_WAIT_L(n) asm volatile("s_waitcnt lgkmcnt(" #n ")" ::: "memory")
; template <class Epi, class Sched, bool ALIGN_EPI = false, bool SP2 = false>
; __device__ __forceinline__ void gemm_phase(PG8_LAS unsigned char* lds, const Gemm g, const Sched& S, const Epi& E) {
;     ...
;             const bool last = (t == nt - 2);
;             const char* a1 = cA + (size_t)(t + 1) * kstep;
;             const char* a2 = last ? nA : cA + (size_t)(t + 2) * kstep; const char* b2 = last ? nB : cB + (size_t)(t + 2) * kstep;
;             const char* a3 = a2 + kstep; const char* b3 = b2 + kstep;
;             if (last && has_next) S.a_ready(nxt);
;             if constexpr (SP2) {
;             PG8_LDB(B0, 0, 0); PG8_LDB(B1, 0, 1); PG8_SCHED; PG8_LDA(At, 0, 0); PG8_STAGE(PG8_SA(1, 1), a1 + hstep, voffA);
;             PG8_WAIT_V(8); PG8_WAIT_L(0); PG8_BAR; PG8_MMA(0, 0, At, B0); PG8_MMA(0, 1, At, B1); PG8_BAR; PG8_SCHED;
;             PG8_LDA(At, 0, 1); PG8_STAGE(PG8_SB(0, 0), b2, voffB); PG8_STAGE(PG8_SB(0, 1), b2 + hstep, voffB); PG8_STAGE(PG8_SA(0, 0), a2, voffA);
;             PG8_WAIT_V(8); PG8_WAIT_L(0); PG8_BAR; PG8_MMA(1, 0, At, B0); PG8_MMA(1, 1, At, B1); PG8_BAR; PG8_SCHED;
.LBB0_585:
	ds_read_b128 v[142:145], v149
	ds_read_b128 v[152:155], v149 offset:1024
	ds_read_b128 v[156:159], v149 offset:2048
	ds_read_b128 v[160:163], v149 offset:3072
	ds_read_b128 v[164:167], v150
	ds_read_b128 v[168:171], v150 offset:1024
	ds_read_b128 v[180:183], v150 offset:2048
	ds_read_b128 v[184:187], v150 offset:3072
	s_add_u32 s26, s24, 0xfff80080
	s_addc_u32 s27, s25, -1
	s_cmp_eq_u32 s51, 28
	s_cselect_b32 s29, s17, s27
	s_cselect_b32 s28, s23, s26
	s_cselect_b32 s27, s13, s50
	s_cselect_b32 s26, s48, s49
	v_lshl_add_u64 v[220:221], s[24:25], 0, v[134:135]
	s_add_i32 m0, s34, 0xc000
	ds_read_b128 v[188:191], v151
	ds_read_b128 v[192:195], v151 offset:1024
	ds_read_b128 v[196:199], v151 offset:2048
	ds_read_b128 v[200:203], v151 offset:3072
	ds_read_b128 v[204:207], v151 offset:4096
	ds_read_b128 v[208:211], v151 offset:5120
	ds_read_b128 v[212:215], v151 offset:6144
	ds_read_b128 v[216:219], v151 offset:7168
	global_load_lds_dwordx4 v[220:221], off
	v_lshl_add_u64 v[220:221], s[24:25], 0, v[136:137]
	s_add_i32 m0, s34, 0xe000
	s_nop 0
	global_load_lds_dwordx4 v[220:221], off
	s_waitcnt vmcnt(8)
	s_waitcnt lgkmcnt(0)
	s_barrier
	s_setprio 1
	s_waitcnt lgkmcnt(0)
	v_mfma_f32_16x16x32_bf16 v[124:127], v[142:145], v[188:191], v[124:127]
	v_mfma_f32_16x16x32_bf16 v[120:123], v[156:159], v[188:191], v[120:123]
	v_mfma_f32_16x16x32_bf16 v[108:111], v[142:145], v[196:199], v[108:111]
	v_mfma_f32_16x16x32_bf16 v[104:107], v[156:159], v[196:199], v[104:107]
	v_mfma_f32_16x16x32_bf16 v[92:95], v[142:145], v[204:207], v[92:95]
	v_mfma_f32_16x16x32_bf16 v[88:91], v[156:159], v[204:207], v[88:91]
	v_mfma_f32_16x16x32_bf16 v[76:79], v[142:145], v[212:215], v[76:79]
	v_mfma_f32_16x16x32_bf16 v[72:75], v[156:159], v[212:215], v[72:75]
	v_mfma_f32_16x16x32_bf16 v[124:127], v[152:155], v[192:195], v[124:127]
	v_mfma_f32_16x16x32_bf16 v[120:123], v[160:163], v[192:195], v[120:123]
	v_mfma_f32_16x16x32_bf16 v[108:111], v[152:155], v[200:203], v[108:111]
	v_mfma_f32_16x16x32_bf16 v[104:107], v[160:163], v[200:203], v[104:107]
	v_mfma_f32_16x16x32_bf16 v[92:95], v[152:155], v[208:211], v[92:95]
	v_mfma_f32_16x16x32_bf16 v[88:91], v[160:163], v[208:211], v[88:91]
	v_mfma_f32_16x16x32_bf16 v[76:79], v[152:155], v[216:219], v[76:79]
	v_mfma_f32_16x16x32_bf16 v[72:75], v[160:163], v[216:219], v[72:75]
	s_setprio 0
	s_setprio 1
	v_mfma_f32_16x16x32_bf16 v[116:119], v[164:167], v[188:191], v[116:119]
	v_mfma_f32_16x16x32_bf16 v[112:115], v[180:183], v[188:191], v[112:115]
	v_mfma_f32_16x16x32_bf16 v[100:103], v[164:167], v[196:199], v[100:103]
	v_mfma_f32_16x16x32_bf16 v[96:99], v[180:183], v[196:199], v[96:99]
	v_mfma_f32_16x16x32_bf16 v[84:87], v[164:167], v[204:207], v[84:87]
	v_mfma_f32_16x16x32_bf16 v[80:83], v[180:183], v[204:207], v[80:83]
	v_mfma_f32_16x16x32_bf16 v[68:71], v[164:167], v[212:215], v[68:71]
	v_mfma_f32_16x16x32_bf16 v[64:67], v[180:183], v[212:215], v[64:67]
	v_mfma_f32_16x16x32_bf16 v[116:119], v[168:171], v[192:195], v[116:119]
	v_mfma_f32_16x16x32_bf16 v[112:115], v[184:187], v[192:195], v[112:115]
	v_mfma_f32_16x16x32_bf16 v[100:103], v[168:171], v[200:203], v[100:103]
	v_mfma_f32_16x16x32_bf16 v[96:99], v[184:187], v[200:203], v[96:99]
	v_mfma_f32_16x16x32_bf16 v[84:87], v[168:171], v[208:211], v[84:87]
	v_mfma_f32_16x16x32_bf16 v[80:83], v[184:187], v[208:211], v[80:83]
	v_mfma_f32_16x16x32_bf16 v[68:71], v[168:171], v[216:219], v[68:71]
	v_mfma_f32_16x16x32_bf16 v[64:67], v[184:187], v[216:219], v[64:67]
	s_setprio 0
	s_barrier
	s_add_i32 s52, s45, s33
	v_lshl_add_u64 v[220:221], s[26:27], 0, v[130:131]
	s_mov_b32 m0, s52
	ds_read_b128 v[188:191], v151 offset:16384
	ds_read_b128 v[192:195], v151 offset:17408
	ds_read_b128 v[196:199], v151 offset:18432
	ds_read_b128 v[200:203], v151 offset:19456
	ds_read_b128 v[204:207], v151 offset:20480
	ds_read_b128 v[208:211], v151 offset:21504
	ds_read_b128 v[212:215], v151 offset:22528
	ds_read_b128 v[216:219], v151 offset:23552
	global_load_lds_dwordx4 v[220:221], off
	s_add_i32 m0, s52, 0x2000
	s_add_u32 s52, s26, 0x80000
	v_lshl_add_u64 v[222:223], s[26:27], 0, v[132:133]
	s_addc_u32 s53, s27, 0
	s_add_i32 s54, s46, s33
	global_load_lds_dwordx4 v[222:223], off
	v_lshl_add_u64 v[224:225], s[52:53], 0, v[130:131]
	s_mov_b32 m0, s54
	v_lshl_add_u64 v[226:227], s[28:29], 0, v[132:133]
	global_load_lds_dwordx4 v[224:225], off
	v_lshl_add_u64 v[224:225], s[52:53], 0, v[132:133]
	s_add_i32 m0, s54, 0x2000
	s_nop 0
	global_load_lds_dwordx4 v[224:225], off
	v_lshl_add_u64 v[224:225], s[28:29], 0, v[130:131]
	s_mov_b32 m0, s34
	s_nop 0
	global_load_lds_dwordx4 v[224:225], off
	s_mov_b32 m0, s35
	s_nop 0
	global_load_lds_dwordx4 v[226:227], off
	s_waitcnt vmcnt(8)
	s_waitcnt lgkmcnt(0)
	s_barrier
; #define PG8_STAGE(bufoff, gbase, voff) do { _Pragma("unroll") for (int _i = 0; _i < 2; ++_i) \
;         __builtin_amdgcn_global_load_lds((const unsigned*)((const char*)(gbase) + (voff)[_i]), (PG8_LAS unsigned*)(lds + (bufoff) + ldsw + _i * 8192), 16, 0, 0); } while (0)
; #define PG8_LDA(dst, b, h) do { _Pragma("unroll") for (int m = 0; m < 4; ++m) _Pragma("unroll") for (int k = 0; k < 2; ++k) dst[m][k] = *(const PG8_LAS bf16x8*)(lds + PG8_SA(b, h) + aoff + m * 2048 + k * 1024); } while (0)
; #define PG8_LDB(dst, b, h) do { _Pragma("unroll") for (int n = 0; n < 2; ++n) _Pragma("unroll") for (int k = 0; k < 2; ++k) dst[n][k] = *(const PG8_LAS bf16x8*)(lds + PG8_SB(b, h) + boff + n * 2048 + k * 1024); } while (0)
; #define PG8_MMA(ai, bj, At, Bt) do { __builtin_amdgcn_s_setprio(1); _Pragma("unroll") for (int m = 0; m < 4; ++m) _Pragma("unroll") for (int n = 0; n < 2; ++n) _Pragma("unroll") for (int k = 0; k < 2; ++k) \
;         acc[ai][bj][m][n] = __builtin_amdgcn_mfma_f32_16x16x32_bf16(Bt[n][k], At[m][k], acc[ai][bj][m][n], 0, 0, 0); __builtin_amdgcn_s_setprio(0); } while (0)
; #define PG8_WAIT_V(n) asm volatile("s_waitcnt vmcnt(" #n ")" ::: "memory")
; #define PG8_WAIT_L(n) asm volatile("s_waitcnt lgkmcnt(" #n ")" ::: "memory")
; #define PG8_BAR __builtin_amdgcn_s_barrier()
; #define PG8_SCHED __builtin_amdgcn_sched_barrier(0)
; template <class Epi, class Sched, bool ALIGN_EPI = false, bool SP2 = false>
; __device__ __forceinline__ void gemm_phase(PG8_LAS unsigned char* lds, const Gemm g, const Sched& S, const Epi& E) {
;     ...
;             PG8_WAIT_V(8); PG8_WAIT_L(0); PG8_BAR; PG8_MMA(1, 0, At, B0); PG8_MMA(1, 1, At, B1); PG8_BAR; PG8_SCHED;
;             PG8_LDB(B0, 1, 0); PG8_LDB(B1, 1, 1); PG8_SCHED; PG8_LDA(At, 1, 0); PG8_STAGE(PG8_SA(0, 1), a2 + hstep, voffA);
;             PG8_WAIT_V(8); PG8_WAIT_L(0); PG8_BAR; PG8_MMA(0, 0, At, B0); PG8_MMA(0, 1, At, B1); PG8_BAR; PG8_SCHED;
	s_setprio 1
	s_waitcnt lgkmcnt(0)
	v_mfma_f32_16x16x32_bf16 v[60:63], v[142:145], v[188:191], v[60:63]
	v_mfma_f32_16x16x32_bf16 v[56:59], v[156:159], v[188:191], v[56:59]
	v_mfma_f32_16x16x32_bf16 v[44:47], v[142:145], v[196:199], v[44:47]
	v_mfma_f32_16x16x32_bf16 v[40:43], v[156:159], v[196:199], v[40:43]
	v_mfma_f32_16x16x32_bf16 v[28:31], v[142:145], v[204:207], v[28:31]
	v_mfma_f32_16x16x32_bf16 v[24:27], v[156:159], v[204:207], v[24:27]
	v_mfma_f32_16x16x32_bf16 v[12:15], v[142:145], v[212:215], v[12:15]
	v_mfma_f32_16x16x32_bf16 v[8:11], v[156:159], v[212:215], v[8:11]
	v_mfma_f32_16x16x32_bf16 v[60:63], v[152:155], v[192:195], v[60:63]
	v_mfma_f32_16x16x32_bf16 v[56:59], v[160:163], v[192:195], v[56:59]
	v_mfma_f32_16x16x32_bf16 v[44:47], v[152:155], v[200:203], v[44:47]
	v_mfma_f32_16x16x32_bf16 v[40:43], v[160:163], v[200:203], v[40:43]
	v_mfma_f32_16x16x32_bf16 v[28:31], v[152:155], v[208:211], v[28:31]
	v_mfma_f32_16x16x32_bf16 v[24:27], v[160:163], v[208:211], v[24:27]
	v_mfma_f32_16x16x32_bf16 v[12:15], v[152:155], v[216:219], v[12:15]
	v_mfma_f32_16x16x32_bf16 v[8:11], v[160:163], v[216:219], v[8:11]
	s_setprio 0
	s_setprio 1
	v_mfma_f32_16x16x32_bf16 v[52:55], v[164:167], v[188:191], v[52:55]
	v_mfma_f32_16x16x32_bf16 v[48:51], v[180:183], v[188:191], v[48:51]
	v_mfma_f32_16x16x32_bf16 v[36:39], v[164:167], v[196:199], v[36:39]
	v_mfma_f32_16x16x32_bf16 v[32:35], v[180:183], v[196:199], v[32:35]
	v_mfma_f32_16x16x32_bf16 v[20:23], v[164:167], v[204:207], v[20:23]
	v_mfma_f32_16x16x32_bf16 v[16:19], v[180:183], v[204:207], v[16:19]
	v_mfma_f32_16x16x32_bf16 v[4:7], v[164:167], v[212:215], v[4:7]
	v_mfma_f32_16x16x32_bf16 v[0:3], v[180:183], v[212:215], v[0:3]
	v_mfma_f32_16x16x32_bf16 v[52:55], v[168:171], v[192:195], v[52:55]
	v_mfma_f32_16x16x32_bf16 v[48:51], v[184:187], v[192:195], v[48:51]
	v_mfma_f32_16x16x32_bf16 v[36:39], v[168:171], v[200:203], v[36:39]
	v_mfma_f32_16x16x32_bf16 v[32:35], v[184:187], v[200:203], v[32:35]
	v_mfma_f32_16x16x32_bf16 v[20:23], v[168:171], v[208:211], v[20:23]
	v_mfma_f32_16x16x32_bf16 v[16:19], v[184:187], v[208:211], v[16:19]
	v_mfma_f32_16x16x32_bf16 v[4:7], v[168:171], v[216:219], v[4:7]
	v_mfma_f32_16x16x32_bf16 v[0:3], v[184:187], v[216:219], v[0:3]
	s_setprio 0
	s_barrier
	s_add_i32 s52, 0, 0x18000
	s_add_i32 s53, 0, 0x1c000
	v_add_u32_e32 v160, s52, v147
	v_add_u32_e32 v179, s53, v147
	ds_read_b128 v[142:145], v160
	ds_read_b128 v[152:155], v160 offset:1024
	ds_read_b128 v[156:159], v160 offset:2048
	ds_read_b128 v[160:163], v160 offset:3072
	ds_read_b128 v[164:167], v179
	ds_read_b128 v[168:171], v179 offset:1024
	ds_read_b128 v[180:183], v179 offset:2048
	ds_read_b128 v[184:187], v179 offset:3072
	s_add_u32 s28, s28, 0x80000
	s_addc_u32 s29, s29, 0
	s_mov_b32 m0, s36
	v_lshl_add_u64 v[228:229], s[28:29], 0, v[130:131]
	ds_read_b128 v[188:191], v151 offset:32768
	ds_read_b128 v[192:195], v151 offset:33792
	ds_read_b128 v[196:199], v151 offset:34816
	ds_read_b128 v[200:203], v151 offset:35840
	ds_read_b128 v[204:207], v151 offset:36864
	ds_read_b128 v[208:211], v151 offset:37888
	ds_read_b128 v[212:215], v151 offset:38912
	ds_read_b128 v[216:219], v151 offset:39936
	global_load_lds_dwordx4 v[228:229], off
	v_lshl_add_u64 v[228:229], s[28:29], 0, v[132:133]
	s_mov_b32 m0, s37
	s_nop 0
	global_load_lds_dwordx4 v[228:229], off
	s_waitcnt vmcnt(8)
	s_waitcnt lgkmcnt(0)
	s_barrier
	s_setprio 1
	s_waitcnt lgkmcnt(0)
	v_mfma_f32_16x16x32_bf16 v[124:127], v[142:145], v[188:191], v[124:127]
	v_mfma_f32_16x16x32_bf16 v[120:123], v[156:159], v[188:191], v[120:123]
	v_mfma_f32_16x16x32_bf16 v[108:111], v[142:145], v[196:199], v[108:111]
	v_mfma_f32_16x16x32_bf16 v[104:107], v[156:159], v[196:199], v[104:107]
	v_mfma_f32_16x16x32_bf16 v[92:95], v[142:145], v[204:207], v[92:95]
	v_mfma_f32_16x16x32_bf16 v[88:91], v[156:159], v[204:207], v[88:91]
	v_mfma_f32_16x16x32_bf16 v[76:79], v[142:145], v[212:215], v[76:79]
	v_mfma_f32_16x16x32_bf16 v[72:75], v[156:159], v[212:215], v[72:75]
	v_mfma_f32_16x16x32_bf16 v[124:127], v[152:155], v[192:195], v[124:127]
	v_mfma_f32_16x16x32_bf16 v[120:123], v[160:163], v[192:195], v[120:123]
	v_mfma_f32_16x16x32_bf16 v[108:111], v[152:155], v[200:203], v[108:111]
	v_mfma_f32_16x16x32_bf16 v[104:107], v[160:163], v[200:203], v[104:107]
	v_mfma_f32_16x16x32_bf16 v[92:95], v[152:155], v[208:211], v[92:95]
	v_mfma_f32_16x16x32_bf16 v[88:91], v[160:163], v[208:211], v[88:91]
	v_mfma_f32_16x16x32_bf16 v[76:79], v[152:155], v[216:219], v[76:79]
	v_mfma_f32_16x16x32_bf16 v[72:75], v[160:163], v[216:219], v[72:75]
	s_setprio 0
	s_setprio 1
	v_mfma_f32_16x16x32_bf16 v[116:119], v[164:167], v[188:191], v[116:119]
	v_mfma_f32_16x16x32_bf16 v[112:115], v[180:183], v[188:191], v[112:115]
	v_mfma_f32_16x16x32_bf16 v[100:103], v[164:167], v[196:199], v[100:103]
	v_mfma_f32_16x16x32_bf16 v[96:99], v[180:183], v[196:199], v[96:99]
	v_mfma_f32_16x16x32_bf16 v[84:87], v[164:167], v[204:207], v[84:87]
	v_mfma_f32_16x16x32_bf16 v[80:83], v[180:183], v[204:207], v[80:83]
	v_mfma_f32_16x16x32_bf16 v[68:71], v[164:167], v[212:215], v[68:71]
	v_mfma_f32_16x16x32_bf16 v[64:67], v[180:183], v[212:215], v[64:67]
	v_mfma_f32_16x16x32_bf16 v[116:119], v[168:171], v[192:195], v[116:119]
	v_mfma_f32_16x16x32_bf16 v[112:115], v[184:187], v[192:195], v[112:115]
	v_mfma_f32_16x16x32_bf16 v[100:103], v[168:171], v[200:203], v[100:103]
	v_mfma_f32_16x16x32_bf16 v[96:99], v[184:187], v[200:203], v[96:99]
	v_mfma_f32_16x16x32_bf16 v[84:87], v[168:171], v[208:211], v[84:87]
	v_mfma_f32_16x16x32_bf16 v[80:83], v[184:187], v[208:211], v[80:83]
	v_mfma_f32_16x16x32_bf16 v[68:71], v[168:171], v[216:219], v[68:71]
	v_mfma_f32_16x16x32_bf16 v[64:67], v[184:187], v[216:219], v[64:67]
	s_setprio 0
	s_barrier
; #define PG8_STAGE(bufoff, gbase, voff) do { _Pragma("unroll") for (int _i = 0; _i < 2; ++_i) \
;         __builtin_amdgcn_global_load_lds((const unsigned*)((const char*)(gbase) + (voff)[_i]), (PG8_LAS unsigned*)(lds + (bufoff) + ldsw + _i * 8192), 16, 0, 0); } while (0)
; #define PG8_LDA(dst, b, h) do { _Pragma("unroll") for (int m = 0; m < 4; ++m) _Pragma("unroll") for (int k = 0; k < 2; ++k) dst[m][k] = *(const PG8_LAS bf16x8*)(lds + PG8_SA(b, h) + aoff + m * 2048 + k * 1024); } while (0)
; #define PG8_MMA(ai, bj, At, Bt) do { __builtin_amdgcn_s_setprio(1); _Pragma("unroll") for (int m = 0; m < 4; ++m) _Pragma("unroll") for (int n = 0; n < 2; ++n) _Pragma("unroll") for (int k = 0; k < 2; ++k) \
;         acc[ai][bj][m][n] = __builtin_amdgcn_mfma_f32_16x16x32_bf16(Bt[n][k], At[m][k], acc[ai][bj][m][n], 0, 0, 0); __builtin_amdgcn_s_setprio(0); } while (0)
; #define PG8_WAIT_V(n) asm volatile("s_waitcnt vmcnt(" #n ")" ::: "memory")
; #define PG8_WAIT_L(n) asm volatile("s_waitcnt lgkmcnt(" #n ")" ::: "memory")
; #define PG8_BAR __builtin_amdgcn_s_barrier()
; #define PG8_SCHED __builtin_amdgcn_sched_barrier(0)
; template <class Epi, class Sched, bool ALIGN_EPI = false, bool SP2 = false>
; __device__ __forceinline__ void gemm_phase(PG8_LAS unsigned char* lds, const Gemm g, const Sched& S, const Epi& E) {
;     ...
;             PG8_LDA(At, 1, 1); PG8_STAGE(PG8_SB(1, 0), b3, voffB); PG8_STAGE(PG8_SB(1, 1), b3 + hstep, voffB); PG8_STAGE(PG8_SA(1, 0), a3, voffA);
;             PG8_WAIT_V(8); PG8_WAIT_L(0); PG8_BAR; PG8_MMA(1, 0, At, B0); PG8_MMA(1, 1, At, B1); PG8_BAR; PG8_SCHED;
;     ...
;         if constexpr (ALIGN_EPI) { if (wr == 0) PG8_BAR; }
	s_add_i32 s28, s52, s33
	v_lshl_add_u64 v[220:221], v[220:221], 0, s[4:5]
	s_mov_b32 m0, s28
	ds_read_b128 v[188:191], v151 offset:49152
	ds_read_b128 v[192:195], v151 offset:50176
	ds_read_b128 v[196:199], v151 offset:51200
	ds_read_b128 v[200:203], v151 offset:52224
	ds_read_b128 v[204:207], v151 offset:53248
	ds_read_b128 v[208:211], v151 offset:54272
	ds_read_b128 v[212:215], v151 offset:55296
	ds_read_b128 v[216:219], v151 offset:56320
	global_load_lds_dwordx4 v[220:221], off
	s_add_i32 m0, s28, 0x2000
	s_add_u32 s26, s26, 0x80080
	v_lshl_add_u64 v[220:221], v[222:223], 0, s[4:5]
	s_addc_u32 s27, s27, 0
	s_add_i32 s28, s53, s33
	global_load_lds_dwordx4 v[220:221], off
	v_lshl_add_u64 v[220:221], s[26:27], 0, v[130:131]
	s_mov_b32 m0, s28
	s_nop 0
	global_load_lds_dwordx4 v[220:221], off
	v_lshl_add_u64 v[220:221], s[26:27], 0, v[132:133]
	s_add_i32 m0, s28, 0x2000
	s_nop 0
	global_load_lds_dwordx4 v[220:221], off
	v_lshl_add_u64 v[220:221], v[224:225], 0, s[4:5]
	s_mov_b32 m0, s41
	s_nop 0
	global_load_lds_dwordx4 v[220:221], off
	v_lshl_add_u64 v[220:221], v[226:227], 0, s[4:5]
	s_mov_b32 m0, s44
	s_nop 0
	global_load_lds_dwordx4 v[220:221], off
	s_waitcnt vmcnt(8)
	s_waitcnt lgkmcnt(0)
	s_barrier
	s_setprio 1
	s_waitcnt lgkmcnt(0)
	v_mfma_f32_16x16x32_bf16 v[60:63], v[142:145], v[188:191], v[60:63]
	v_mfma_f32_16x16x32_bf16 v[56:59], v[156:159], v[188:191], v[56:59]
	v_mfma_f32_16x16x32_bf16 v[44:47], v[142:145], v[196:199], v[44:47]
	v_mfma_f32_16x16x32_bf16 v[40:43], v[156:159], v[196:199], v[40:43]
	v_mfma_f32_16x16x32_bf16 v[28:31], v[142:145], v[204:207], v[28:31]
	v_mfma_f32_16x16x32_bf16 v[24:27], v[156:159], v[204:207], v[24:27]
	v_mfma_f32_16x16x32_bf16 v[12:15], v[142:145], v[212:215], v[12:15]
	v_mfma_f32_16x16x32_bf16 v[8:11], v[156:159], v[212:215], v[8:11]
	v_mfma_f32_16x16x32_bf16 v[60:63], v[152:155], v[192:195], v[60:63]
	v_mfma_f32_16x16x32_bf16 v[56:59], v[160:163], v[192:195], v[56:59]
	v_mfma_f32_16x16x32_bf16 v[44:47], v[152:155], v[200:203], v[44:47]
	v_mfma_f32_16x16x32_bf16 v[40:43], v[160:163], v[200:203], v[40:43]
	v_mfma_f32_16x16x32_bf16 v[28:31], v[152:155], v[208:211], v[28:31]
	v_mfma_f32_16x16x32_bf16 v[24:27], v[160:163], v[208:211], v[24:27]
	v_mfma_f32_16x16x32_bf16 v[12:15], v[152:155], v[216:219], v[12:15]
	v_mfma_f32_16x16x32_bf16 v[8:11], v[160:163], v[216:219], v[8:11]
	s_setprio 0
	s_setprio 1
	v_mfma_f32_16x16x32_bf16 v[52:55], v[164:167], v[188:191], v[52:55]
	v_mfma_f32_16x16x32_bf16 v[48:51], v[180:183], v[188:191], v[48:51]
	v_mfma_f32_16x16x32_bf16 v[36:39], v[164:167], v[196:199], v[36:39]
	v_mfma_f32_16x16x32_bf16 v[32:35], v[180:183], v[196:199], v[32:35]
	v_mfma_f32_16x16x32_bf16 v[20:23], v[164:167], v[204:207], v[20:23]
	v_mfma_f32_16x16x32_bf16 v[16:19], v[180:183], v[204:207], v[16:19]
	v_mfma_f32_16x16x32_bf16 v[4:7], v[164:167], v[212:215], v[4:7]
	v_mfma_f32_16x16x32_bf16 v[0:3], v[180:183], v[212:215], v[0:3]
	v_mfma_f32_16x16x32_bf16 v[52:55], v[168:171], v[192:195], v[52:55]
	v_mfma_f32_16x16x32_bf16 v[48:51], v[184:187], v[192:195], v[48:51]
	v_mfma_f32_16x16x32_bf16 v[36:39], v[168:171], v[200:203], v[36:39]
	v_mfma_f32_16x16x32_bf16 v[32:35], v[184:187], v[200:203], v[32:35]
	v_mfma_f32_16x16x32_bf16 v[20:23], v[168:171], v[208:211], v[20:23]
	v_mfma_f32_16x16x32_bf16 v[16:19], v[184:187], v[208:211], v[16:19]
	v_mfma_f32_16x16x32_bf16 v[4:7], v[168:171], v[216:219], v[4:7]
	v_mfma_f32_16x16x32_bf16 v[0:3], v[184:187], v[216:219], v[0:3]
	s_setprio 0
	s_barrier
	s_add_i32 s51, s51, 2
	s_add_u32 s24, s24, 0x100
	s_addc_u32 s25, s25, 0
	s_add_u32 s49, s49, 0x100
	s_addc_u32 s50, s50, 0
	s_cmp_gt_u32 s51, 29
	s_cbranch_scc0 .LBB0_585
	s_nop 0
	v_readfirstlane_b32 s23, v172
	s_nop 3
	s_lshr_b32 s23, s23, 6
	s_cmp_lt_u32 s23, 4
	s_cbranch_scc0 .Lprio_k1
	s_setprio 1
.Lprio_k1:
	s_and_b64 vcc, exec, s[6:7]
	s_cbranch_vccz .LBB0_588
	s_barrier

; #define PG8_STAGE(bufoff, gbase, voff) do { _Pragma("unroll") for (int _i = 0; _i < 2; ++_i) \
;         __builtin_amdgcn_global_load_lds((const unsigned*)((const char*)(gbase) + (voff)[_i]), (PG8_LAS unsigned*)(lds + (bufoff) + ldsw + _i * 8192), 16, 0, 0); } while (0)
; #define PG8_LDA(dst, b, h) do { _Pragma("unroll") for (int m = 0; m < 4; ++m) _Pragma("unroll") for (int k = 0; k < 2; ++k) dst[m][k] = *(const PG8_LAS bf16x8*)(lds + PG8_SA(b, h) + aoff + m * 2048 + k * 1024); } while (0)
; #define PG8_LDB(dst, b, h) do { _Pragma("unroll") for (int n = 0; n < 2; ++n) _Pragma("unroll") for (int k = 0; k < 2; ++k) dst[n][k] = *(const PG8_LAS bf16x8*)(lds + PG8_SB(b, h) + boff + n * 2048 + k * 1024); } while (0)
; #define PG8_MMA(ai, bj, At, Bt) do { __builtin_amdgcn_s_setprio(1); _Pragma("unroll") for (int m = 0; m < 4; ++m) _Pragma("unroll") for (int n = 0; n < 2; ++n) _Pragma("unroll") for (int k = 0; k < 2; ++k) \
;         acc[ai][bj][m][n] = __builtin_amdgcn_mfma_f32_16x16x32_bf16(Bt[n][k], At[m][k], acc[ai][bj][m][n], 0, 0, 0); __builtin_amdgcn_s_setprio(0); } while (0)
; #define PG8_WAIT_V(n) asm volatile("s_waitcnt vmcnt(" #n ")" ::: "memory")
; #define PG8_WAIT_L(n) asm volatile("s_waitcnt lgkmcnt(" #n ")" ::: "memory")
; template <class Epi, class Sched, bool ALIGN_EPI = false, bool SP2 = false>
; __device__ __forceinline__ void gemm_phase(PG8_LAS unsigned char* lds, const Gemm g, const Sched& S, const Epi& E) {
;     ...
;             const bool last = (t == nt - 2);
;             const char* a1 = cA + (size_t)(t + 1) * kstep;
;             const char* a2 = last ? nA : cA + (size_t)(t + 2) * kstep; const char* b2 = last ? nB : cB + (size_t)(t + 2) * kstep;
;             const char* a3 = a2 + kstep; const char* b3 = b2 + kstep;
;             if (last && has_next) S.a_ready(nxt);
;             if constexpr (SP2) {
;             PG8_LDB(B0, 0, 0); PG8_LDB(B1, 0, 1); PG8_SCHED; PG8_LDA(At, 0, 0); PG8_STAGE(PG8_SA(1, 1), a1 + hstep, voffA);
;             PG8_WAIT_V(8); PG8_WAIT_L(0); PG8_BAR; PG8_MMA(0, 0, At, B0); PG8_MMA(0, 1, At, B1); PG8_BAR; PG8_SCHED;
;             PG8_LDA(At, 0, 1); PG8_STAGE(PG8_SB(0, 0), b2, voffB); PG8_STAGE(PG8_SB(0, 1), b2 + hstep, voffB); PG8_STAGE(PG8_SA(0, 0), a2, voffA);
;             PG8_WAIT_V(8); PG8_WAIT_L(0); PG8_BAR; PG8_MMA(1, 0, At, B0); PG8_MMA(1, 1, At, B1); PG8_BAR; PG8_SCHED;
.LBB0_837:
	ds_read_b128 v[146:149], v158
	ds_read_b128 v[150:153], v158 offset:1024
	ds_read_b128 v[162:165], v158 offset:2048
	ds_read_b128 v[166:169], v158 offset:3072
	ds_read_b128 v[180:183], v159
	ds_read_b128 v[184:187], v159 offset:1024
	ds_read_b128 v[188:191], v159 offset:2048
	ds_read_b128 v[192:195], v159 offset:3072
	s_add_u32 s22, s20, 0xfff80080
	s_addc_u32 s23, s21, -1
	s_cmp_eq_u32 s50, 28
	s_cselect_b32 s25, s11, s23
	s_cselect_b32 s24, s46, s22
	s_cselect_b32 s23, s7, s49
	s_cselect_b32 s22, s47, s48
	v_lshl_add_u64 v[170:171], s[20:21], 0, v[138:139]
	s_add_i32 m0, s30, 0xc000
	ds_read_b128 v[196:199], v160
	ds_read_b128 v[200:203], v160 offset:1024
	ds_read_b128 v[204:207], v160 offset:2048
	ds_read_b128 v[208:211], v160 offset:3072
	ds_read_b128 v[212:215], v160 offset:4096
	ds_read_b128 v[216:219], v160 offset:5120
	ds_read_b128 v[220:223], v160 offset:6144
	ds_read_b128 v[224:227], v160 offset:7168
	global_load_lds_dwordx4 v[170:171], off
	v_lshl_add_u64 v[170:171], s[20:21], 0, v[140:141]
	s_add_i32 m0, s30, 0xe000
	s_nop 0
	global_load_lds_dwordx4 v[170:171], off
	s_waitcnt vmcnt(8)
	s_waitcnt lgkmcnt(0)
	s_barrier
	s_setprio 1
	s_waitcnt lgkmcnt(0)
	v_mfma_f32_16x16x32_bf16 v[124:127], v[146:149], v[196:199], v[124:127]
	v_mfma_f32_16x16x32_bf16 v[116:119], v[162:165], v[196:199], v[116:119]
	v_mfma_f32_16x16x32_bf16 v[108:111], v[146:149], v[204:207], v[108:111]
	v_mfma_f32_16x16x32_bf16 v[100:103], v[162:165], v[204:207], v[100:103]
	v_mfma_f32_16x16x32_bf16 v[92:95], v[146:149], v[212:215], v[92:95]
	v_mfma_f32_16x16x32_bf16 v[84:87], v[162:165], v[212:215], v[84:87]
	v_mfma_f32_16x16x32_bf16 v[76:79], v[146:149], v[220:223], v[76:79]
	v_mfma_f32_16x16x32_bf16 v[68:71], v[162:165], v[220:223], v[68:71]
	v_mfma_f32_16x16x32_bf16 v[124:127], v[150:153], v[200:203], v[124:127]
	v_mfma_f32_16x16x32_bf16 v[116:119], v[166:169], v[200:203], v[116:119]
	v_mfma_f32_16x16x32_bf16 v[108:111], v[150:153], v[208:211], v[108:111]
	v_mfma_f32_16x16x32_bf16 v[100:103], v[166:169], v[208:211], v[100:103]
	v_mfma_f32_16x16x32_bf16 v[92:95], v[150:153], v[216:219], v[92:95]
	v_mfma_f32_16x16x32_bf16 v[84:87], v[166:169], v[216:219], v[84:87]
	v_mfma_f32_16x16x32_bf16 v[76:79], v[150:153], v[224:227], v[76:79]
	v_mfma_f32_16x16x32_bf16 v[68:71], v[166:169], v[224:227], v[68:71]
	s_setprio 0
	s_setprio 1
	v_mfma_f32_16x16x32_bf16 v[120:123], v[180:183], v[196:199], v[120:123]
	v_mfma_f32_16x16x32_bf16 v[112:115], v[188:191], v[196:199], v[112:115]
	v_mfma_f32_16x16x32_bf16 v[104:107], v[180:183], v[204:207], v[104:107]
	v_mfma_f32_16x16x32_bf16 v[96:99], v[188:191], v[204:207], v[96:99]
	v_mfma_f32_16x16x32_bf16 v[88:91], v[180:183], v[212:215], v[88:91]
	v_mfma_f32_16x16x32_bf16 v[80:83], v[188:191], v[212:215], v[80:83]
	v_mfma_f32_16x16x32_bf16 v[72:75], v[180:183], v[220:223], v[72:75]
	v_mfma_f32_16x16x32_bf16 v[64:67], v[188:191], v[220:223], v[64:67]
	v_mfma_f32_16x16x32_bf16 v[120:123], v[184:187], v[200:203], v[120:123]
	v_mfma_f32_16x16x32_bf16 v[112:115], v[192:195], v[200:203], v[112:115]
	v_mfma_f32_16x16x32_bf16 v[104:107], v[184:187], v[208:211], v[104:107]
	v_mfma_f32_16x16x32_bf16 v[96:99], v[192:195], v[208:211], v[96:99]
	v_mfma_f32_16x16x32_bf16 v[88:91], v[184:187], v[216:219], v[88:91]
	v_mfma_f32_16x16x32_bf16 v[80:83], v[192:195], v[216:219], v[80:83]
	v_mfma_f32_16x16x32_bf16 v[72:75], v[184:187], v[224:227], v[72:75]
	v_mfma_f32_16x16x32_bf16 v[64:67], v[192:195], v[224:227], v[64:67]
	s_setprio 0
	s_barrier
	s_add_i32 s51, s37, s26
	v_lshl_add_u64 v[170:171], s[22:23], 0, v[134:135]
	s_mov_b32 m0, s51
	ds_read_b128 v[196:199], v160 offset:16384
	ds_read_b128 v[200:203], v160 offset:17408
	ds_read_b128 v[204:207], v160 offset:18432
	ds_read_b128 v[208:211], v160 offset:19456
	ds_read_b128 v[212:215], v160 offset:20480
	ds_read_b128 v[216:219], v160 offset:21504
	ds_read_b128 v[220:223], v160 offset:22528
	ds_read_b128 v[224:227], v160 offset:23552
	global_load_lds_dwordx4 v[170:171], off
	s_add_i32 m0, s51, 0x2000
	s_add_u32 s52, s22, 0x80000
	v_lshl_add_u64 v[228:229], s[22:23], 0, v[130:131]
	s_addc_u32 s53, s23, 0
	s_add_i32 s51, s40, s26
	global_load_lds_dwordx4 v[228:229], off
	v_lshl_add_u64 v[230:231], s[52:53], 0, v[134:135]
	s_mov_b32 m0, s51
	v_lshl_add_u64 v[232:233], s[24:25], 0, v[132:133]
	global_load_lds_dwordx4 v[230:231], off
	v_lshl_add_u64 v[230:231], s[52:53], 0, v[130:131]
	s_add_i32 m0, s51, 0x2000
	s_nop 0
	global_load_lds_dwordx4 v[230:231], off
	v_lshl_add_u64 v[230:231], s[24:25], 0, v[136:137]
	s_mov_b32 m0, s30
	s_nop 0
	global_load_lds_dwordx4 v[230:231], off
	s_mov_b32 m0, s31
	s_nop 0
	global_load_lds_dwordx4 v[232:233], off
	s_waitcnt vmcnt(8)
	s_waitcnt lgkmcnt(0)
	s_barrier
; #define PG8_STAGE(bufoff, gbase, voff) do { _Pragma("unroll") for (int _i = 0; _i < 2; ++_i) \
;         __builtin_amdgcn_global_load_lds((const unsigned*)((const char*)(gbase) + (voff)[_i]), (PG8_LAS unsigned*)(lds + (bufoff) + ldsw + _i * 8192), 16, 0, 0); } while (0)
; #define PG8_LDA(dst, b, h) do { _Pragma("unroll") for (int m = 0; m < 4; ++m) _Pragma("unroll") for (int k = 0; k < 2; ++k) dst[m][k] = *(const PG8_LAS bf16x8*)(lds + PG8_SA(b, h) + aoff + m * 2048 + k * 1024); } while (0)
; #define PG8_LDB(dst, b, h) do { _Pragma("unroll") for (int n = 0; n < 2; ++n) _Pragma("unroll") for (int k = 0; k < 2; ++k) dst[n][k] = *(const PG8_LAS bf16x8*)(lds + PG8_SB(b, h) + boff + n * 2048 + k * 1024); } while (0)
; #define PG8_MMA(ai, bj, At, Bt) do { __builtin_amdgcn_s_setprio(1); _Pragma("unroll") for (int m = 0; m < 4; ++m) _Pragma("unroll") for (int n = 0; n < 2; ++n) _Pragma("unroll") for (int k = 0; k < 2; ++k) \
;         acc[ai][bj][m][n] = __builtin_amdgcn_mfma_f32_16x16x32_bf16(Bt[n][k], At[m][k], acc[ai][bj][m][n], 0, 0, 0); __builtin_amdgcn_s_setprio(0); } while (0)
; #define PG8_WAIT_V(n) asm volatile("s_waitcnt vmcnt(" #n ")" ::: "memory")
; #define PG8_WAIT_L(n) asm volatile("s_waitcnt lgkmcnt(" #n ")" ::: "memory")
; #define PG8_BAR __builtin_amdgcn_s_barrier()
; #define PG8_SCHED __builtin_amdgcn_sched_barrier(0)
; template <class Epi, class Sched, bool ALIGN_EPI = false, bool SP2 = false>
; __device__ __forceinline__ void gemm_phase(PG8_LAS unsigned char* lds, const Gemm g, const Sched& S, const Epi& E) {
;     ...
;             PG8_WAIT_V(8); PG8_WAIT_L(0); PG8_BAR; PG8_MMA(1, 0, At, B0); PG8_MMA(1, 1, At, B1); PG8_BAR; PG8_SCHED;
;             PG8_LDB(B0, 1, 0); PG8_LDB(B1, 1, 1); PG8_SCHED; PG8_LDA(At, 1, 0); PG8_STAGE(PG8_SA(0, 1), a2 + hstep, voffA);
;             PG8_WAIT_V(8); PG8_WAIT_L(0); PG8_BAR; PG8_MMA(0, 0, At, B0); PG8_MMA(0, 1, At, B1); PG8_BAR; PG8_SCHED;
	s_setprio 1
	s_waitcnt lgkmcnt(0)
	v_mfma_f32_16x16x32_bf16 v[60:63], v[146:149], v[196:199], v[60:63]
	v_mfma_f32_16x16x32_bf16 v[52:55], v[162:165], v[196:199], v[52:55]
	v_mfma_f32_16x16x32_bf16 v[44:47], v[146:149], v[204:207], v[44:47]
	v_mfma_f32_16x16x32_bf16 v[36:39], v[162:165], v[204:207], v[36:39]
	v_mfma_f32_16x16x32_bf16 v[28:31], v[146:149], v[212:215], v[28:31]
	v_mfma_f32_16x16x32_bf16 v[20:23], v[162:165], v[212:215], v[20:23]
	v_mfma_f32_16x16x32_bf16 v[12:15], v[146:149], v[220:223], v[12:15]
	v_mfma_f32_16x16x32_bf16 v[4:7], v[162:165], v[220:223], v[4:7]
	v_mfma_f32_16x16x32_bf16 v[60:63], v[150:153], v[200:203], v[60:63]
	v_mfma_f32_16x16x32_bf16 v[52:55], v[166:169], v[200:203], v[52:55]
	v_mfma_f32_16x16x32_bf16 v[44:47], v[150:153], v[208:211], v[44:47]
	v_mfma_f32_16x16x32_bf16 v[36:39], v[166:169], v[208:211], v[36:39]
	v_mfma_f32_16x16x32_bf16 v[28:31], v[150:153], v[216:219], v[28:31]
	v_mfma_f32_16x16x32_bf16 v[20:23], v[166:169], v[216:219], v[20:23]
	v_mfma_f32_16x16x32_bf16 v[12:15], v[150:153], v[224:227], v[12:15]
	v_mfma_f32_16x16x32_bf16 v[4:7], v[166:169], v[224:227], v[4:7]
	s_setprio 0
	s_setprio 1
	v_mfma_f32_16x16x32_bf16 v[56:59], v[180:183], v[196:199], v[56:59]
	v_mfma_f32_16x16x32_bf16 v[48:51], v[188:191], v[196:199], v[48:51]
	v_mfma_f32_16x16x32_bf16 v[40:43], v[180:183], v[204:207], v[40:43]
	v_mfma_f32_16x16x32_bf16 v[32:35], v[188:191], v[204:207], v[32:35]
	v_mfma_f32_16x16x32_bf16 v[24:27], v[180:183], v[212:215], v[24:27]
	v_mfma_f32_16x16x32_bf16 v[16:19], v[188:191], v[212:215], v[16:19]
	v_mfma_f32_16x16x32_bf16 v[8:11], v[180:183], v[220:223], v[8:11]
	v_mfma_f32_16x16x32_bf16 v[0:3], v[188:191], v[220:223], v[0:3]
	v_mfma_f32_16x16x32_bf16 v[56:59], v[184:187], v[200:203], v[56:59]
	v_mfma_f32_16x16x32_bf16 v[48:51], v[192:195], v[200:203], v[48:51]
	v_mfma_f32_16x16x32_bf16 v[40:43], v[184:187], v[208:211], v[40:43]
	v_mfma_f32_16x16x32_bf16 v[32:35], v[192:195], v[208:211], v[32:35]
	v_mfma_f32_16x16x32_bf16 v[24:27], v[184:187], v[216:219], v[24:27]
	v_mfma_f32_16x16x32_bf16 v[16:19], v[192:195], v[216:219], v[16:19]
	v_mfma_f32_16x16x32_bf16 v[8:11], v[184:187], v[224:227], v[8:11]
	v_mfma_f32_16x16x32_bf16 v[0:3], v[192:195], v[224:227], v[0:3]
	s_setprio 0
	s_barrier
	s_add_i32 s51, 0, 0x18000
	v_add_u32_e32 v161, s51, v155
	s_add_i32 s52, 0, 0x1c000
	ds_read_b128 v[146:149], v161
	ds_read_b128 v[150:153], v161 offset:1024
	ds_read_b128 v[162:165], v161 offset:2048
	ds_read_b128 v[166:169], v161 offset:3072
	v_add_u32_e32 v161, s52, v155
	ds_read_b128 v[180:183], v161
	ds_read_b128 v[184:187], v161 offset:1024
	ds_read_b128 v[188:191], v161 offset:2048
	ds_read_b128 v[192:195], v161 offset:3072
	s_add_u32 s24, s24, 0x80000
	s_addc_u32 s25, s25, 0
	s_mov_b32 m0, s33
	v_lshl_add_u64 v[234:235], s[24:25], 0, v[136:137]
	ds_read_b128 v[196:199], v160 offset:32768
	ds_read_b128 v[200:203], v160 offset:33792
	ds_read_b128 v[204:207], v160 offset:34816
	ds_read_b128 v[208:211], v160 offset:35840
	ds_read_b128 v[212:215], v160 offset:36864
	ds_read_b128 v[216:219], v160 offset:37888
	ds_read_b128 v[220:223], v160 offset:38912
	ds_read_b128 v[224:227], v160 offset:39936
	global_load_lds_dwordx4 v[234:235], off
	v_lshl_add_u64 v[234:235], s[24:25], 0, v[132:133]
	s_mov_b32 m0, s34
	s_nop 0
	global_load_lds_dwordx4 v[234:235], off
	s_waitcnt vmcnt(8)
	s_waitcnt lgkmcnt(0)
	s_barrier
	s_setprio 1
	s_waitcnt lgkmcnt(0)
	v_mfma_f32_16x16x32_bf16 v[124:127], v[146:149], v[196:199], v[124:127]
	v_mfma_f32_16x16x32_bf16 v[116:119], v[162:165], v[196:199], v[116:119]
	v_mfma_f32_16x16x32_bf16 v[108:111], v[146:149], v[204:207], v[108:111]
	v_mfma_f32_16x16x32_bf16 v[100:103], v[162:165], v[204:207], v[100:103]
	v_mfma_f32_16x16x32_bf16 v[92:95], v[146:149], v[212:215], v[92:95]
	v_mfma_f32_16x16x32_bf16 v[84:87], v[162:165], v[212:215], v[84:87]
	v_mfma_f32_16x16x32_bf16 v[76:79], v[146:149], v[220:223], v[76:79]
	v_mfma_f32_16x16x32_bf16 v[68:71], v[162:165], v[220:223], v[68:71]
	v_mfma_f32_16x16x32_bf16 v[124:127], v[150:153], v[200:203], v[124:127]
	v_mfma_f32_16x16x32_bf16 v[116:119], v[166:169], v[200:203], v[116:119]
	v_mfma_f32_16x16x32_bf16 v[108:111], v[150:153], v[208:211], v[108:111]
	v_mfma_f32_16x16x32_bf16 v[100:103], v[166:169], v[208:211], v[100:103]
	v_mfma_f32_16x16x32_bf16 v[92:95], v[150:153], v[216:219], v[92:95]
	v_mfma_f32_16x16x32_bf16 v[84:87], v[166:169], v[216:219], v[84:87]
	v_mfma_f32_16x16x32_bf16 v[76:79], v[150:153], v[224:227], v[76:79]
	v_mfma_f32_16x16x32_bf16 v[68:71], v[166:169], v[224:227], v[68:71]
	s_setprio 0
	s_setprio 1
	v_mfma_f32_16x16x32_bf16 v[120:123], v[180:183], v[196:199], v[120:123]
	v_mfma_f32_16x16x32_bf16 v[112:115], v[188:191], v[196:199], v[112:115]
	v_mfma_f32_16x16x32_bf16 v[104:107], v[180:183], v[204:207], v[104:107]
	v_mfma_f32_16x16x32_bf16 v[96:99], v[188:191], v[204:207], v[96:99]
	v_mfma_f32_16x16x32_bf16 v[88:91], v[180:183], v[212:215], v[88:91]
	v_mfma_f32_16x16x32_bf16 v[80:83], v[188:191], v[212:215], v[80:83]
	v_mfma_f32_16x16x32_bf16 v[72:75], v[180:183], v[220:223], v[72:75]
	v_mfma_f32_16x16x32_bf16 v[64:67], v[188:191], v[220:223], v[64:67]
	v_mfma_f32_16x16x32_bf16 v[120:123], v[184:187], v[200:203], v[120:123]
	v_mfma_f32_16x16x32_bf16 v[112:115], v[192:195], v[200:203], v[112:115]
	v_mfma_f32_16x16x32_bf16 v[104:107], v[184:187], v[208:211], v[104:107]
	v_mfma_f32_16x16x32_bf16 v[96:99], v[192:195], v[208:211], v[96:99]
	v_mfma_f32_16x16x32_bf16 v[88:91], v[184:187], v[216:219], v[88:91]
	v_mfma_f32_16x16x32_bf16 v[80:83], v[192:195], v[216:219], v[80:83]
	v_mfma_f32_16x16x32_bf16 v[72:75], v[184:187], v[224:227], v[72:75]
	v_mfma_f32_16x16x32_bf16 v[64:67], v[192:195], v[224:227], v[64:67]
	s_setprio 0
	s_barrier
; #define PG8_STAGE(bufoff, gbase, voff) do { _Pragma("unroll") for (int _i = 0; _i < 2; ++_i) \
;         __builtin_amdgcn_global_load_lds((const unsigned*)((const char*)(gbase) + (voff)[_i]), (PG8_LAS unsigned*)(lds + (bufoff) + ldsw + _i * 8192), 16, 0, 0); } while (0)
; #define PG8_LDA(dst, b, h) do { _Pragma("unroll") for (int m = 0; m < 4; ++m) _Pragma("unroll") for (int k = 0; k < 2; ++k) dst[m][k] = *(const PG8_LAS bf16x8*)(lds + PG8_SA(b, h) + aoff + m * 2048 + k * 1024); } while (0)
; #define PG8_MMA(ai, bj, At, Bt) do { __builtin_amdgcn_s_setprio(1); _Pragma("unroll") for (int m = 0; m < 4; ++m) _Pragma("unroll") for (int n = 0; n < 2; ++n) _Pragma("unroll") for (int k = 0; k < 2; ++k) \
;         acc[ai][bj][m][n] = __builtin_amdgcn_mfma_f32_16x16x32_bf16(Bt[n][k], At[m][k], acc[ai][bj][m][n], 0, 0, 0); __builtin_amdgcn_s_setprio(0); } while (0)
; #define PG8_WAIT_V(n) asm volatile("s_waitcnt vmcnt(" #n ")" ::: "memory")
; #define PG8_WAIT_L(n) asm volatile("s_waitcnt lgkmcnt(" #n ")" ::: "memory")
; #define PG8_BAR __builtin_amdgcn_s_barrier()
; #define PG8_SCHED __builtin_amdgcn_sched_barrier(0)
; template <class Epi, class Sched, bool ALIGN_EPI = false, bool SP2 = false>
; __device__ __forceinline__ void gemm_phase(PG8_LAS unsigned char* lds, const Gemm g, const Sched& S, const Epi& E) {
;     ...
;             PG8_LDA(At, 1, 1); PG8_STAGE(PG8_SB(1, 0), b3, voffB); PG8_STAGE(PG8_SB(1, 1), b3 + hstep, voffB); PG8_STAGE(PG8_SA(1, 0), a3, voffA);
;             PG8_WAIT_V(8); PG8_WAIT_L(0); PG8_BAR; PG8_MMA(1, 0, At, B0); PG8_MMA(1, 1, At, B1); PG8_BAR; PG8_SCHED;
;     ...
;         if constexpr (ALIGN_EPI) { if (wr == 0) PG8_BAR; }
	s_add_i32 s24, s51, s26
	v_lshl_add_u64 v[170:171], v[170:171], 0, s[2:3]
	s_mov_b32 m0, s24
	ds_read_b128 v[196:199], v160 offset:49152
	ds_read_b128 v[200:203], v160 offset:50176
	ds_read_b128 v[204:207], v160 offset:51200
	ds_read_b128 v[208:211], v160 offset:52224
	ds_read_b128 v[212:215], v160 offset:53248
	ds_read_b128 v[216:219], v160 offset:54272
	ds_read_b128 v[220:223], v160 offset:55296
	ds_read_b128 v[224:227], v160 offset:56320
	global_load_lds_dwordx4 v[170:171], off
	s_add_i32 m0, s24, 0x2000
	s_add_u32 s22, s22, 0x80080
	v_lshl_add_u64 v[170:171], v[228:229], 0, s[2:3]
	s_addc_u32 s23, s23, 0
	s_add_i32 s24, s52, s26
	global_load_lds_dwordx4 v[170:171], off
	v_lshl_add_u64 v[170:171], s[22:23], 0, v[134:135]
	s_mov_b32 m0, s24
	s_nop 0
	global_load_lds_dwordx4 v[170:171], off
	v_lshl_add_u64 v[170:171], s[22:23], 0, v[130:131]
	s_add_i32 m0, s24, 0x2000
	s_nop 0
	global_load_lds_dwordx4 v[170:171], off
	v_lshl_add_u64 v[170:171], v[230:231], 0, s[2:3]
	s_mov_b32 m0, s35
	s_nop 0
	global_load_lds_dwordx4 v[170:171], off
	v_lshl_add_u64 v[170:171], v[232:233], 0, s[2:3]
	s_mov_b32 m0, s36
	s_nop 0
	global_load_lds_dwordx4 v[170:171], off
	s_waitcnt vmcnt(8)
	s_waitcnt lgkmcnt(0)
	s_barrier
	s_setprio 1
	s_waitcnt lgkmcnt(0)
	v_mfma_f32_16x16x32_bf16 v[60:63], v[146:149], v[196:199], v[60:63]
	v_mfma_f32_16x16x32_bf16 v[52:55], v[162:165], v[196:199], v[52:55]
	v_mfma_f32_16x16x32_bf16 v[44:47], v[146:149], v[204:207], v[44:47]
	v_mfma_f32_16x16x32_bf16 v[36:39], v[162:165], v[204:207], v[36:39]
	v_mfma_f32_16x16x32_bf16 v[28:31], v[146:149], v[212:215], v[28:31]
	v_mfma_f32_16x16x32_bf16 v[20:23], v[162:165], v[212:215], v[20:23]
	v_mfma_f32_16x16x32_bf16 v[12:15], v[146:149], v[220:223], v[12:15]
	v_mfma_f32_16x16x32_bf16 v[4:7], v[162:165], v[220:223], v[4:7]
	v_mfma_f32_16x16x32_bf16 v[60:63], v[150:153], v[200:203], v[60:63]
	v_mfma_f32_16x16x32_bf16 v[52:55], v[166:169], v[200:203], v[52:55]
	v_mfma_f32_16x16x32_bf16 v[44:47], v[150:153], v[208:211], v[44:47]
	v_mfma_f32_16x16x32_bf16 v[36:39], v[166:169], v[208:211], v[36:39]
	v_mfma_f32_16x16x32_bf16 v[28:31], v[150:153], v[216:219], v[28:31]
	v_mfma_f32_16x16x32_bf16 v[20:23], v[166:169], v[216:219], v[20:23]
	v_mfma_f32_16x16x32_bf16 v[12:15], v[150:153], v[224:227], v[12:15]
	v_mfma_f32_16x16x32_bf16 v[4:7], v[166:169], v[224:227], v[4:7]
	s_setprio 0
	s_setprio 1
	v_mfma_f32_16x16x32_bf16 v[56:59], v[180:183], v[196:199], v[56:59]
	v_mfma_f32_16x16x32_bf16 v[48:51], v[188:191], v[196:199], v[48:51]
	v_mfma_f32_16x16x32_bf16 v[40:43], v[180:183], v[204:207], v[40:43]
	v_mfma_f32_16x16x32_bf16 v[32:35], v[188:191], v[204:207], v[32:35]
	v_mfma_f32_16x16x32_bf16 v[24:27], v[180:183], v[212:215], v[24:27]
	v_mfma_f32_16x16x32_bf16 v[16:19], v[188:191], v[212:215], v[16:19]
	v_mfma_f32_16x16x32_bf16 v[8:11], v[180:183], v[220:223], v[8:11]
	v_mfma_f32_16x16x32_bf16 v[0:3], v[188:191], v[220:223], v[0:3]
	v_mfma_f32_16x16x32_bf16 v[56:59], v[184:187], v[200:203], v[56:59]
	v_mfma_f32_16x16x32_bf16 v[48:51], v[192:195], v[200:203], v[48:51]
	v_mfma_f32_16x16x32_bf16 v[40:43], v[184:187], v[208:211], v[40:43]
	v_mfma_f32_16x16x32_bf16 v[32:35], v[192:195], v[208:211], v[32:35]
	v_mfma_f32_16x16x32_bf16 v[24:27], v[184:187], v[216:219], v[24:27]
	v_mfma_f32_16x16x32_bf16 v[16:19], v[192:195], v[216:219], v[16:19]
	v_mfma_f32_16x16x32_bf16 v[8:11], v[184:187], v[224:227], v[8:11]
	v_mfma_f32_16x16x32_bf16 v[0:3], v[192:195], v[224:227], v[0:3]
	s_setprio 0
	s_barrier
	s_add_i32 s50, s50, 2
	s_add_u32 s20, s20, 0x100
	s_addc_u32 s21, s21, 0
	s_add_u32 s48, s48, 0x100
	s_addc_u32 s49, s49, 0
	s_cmp_gt_u32 s50, 29
	s_cbranch_scc0 .LBB0_837
	s_nop 0
	v_readfirstlane_b32 s11, v172
	s_nop 3
	s_lshr_b32 s11, s11, 6
	s_cmp_lt_u32 s11, 4
	s_cbranch_scc0 .Lprio_k2
	s_setprio 1

; #define PG8_STAGE(bufoff, gbase, voff) do { _Pragma("unroll") for (int _i = 0; _i < 2; ++_i) \
;         __builtin_amdgcn_global_load_lds((const unsigned*)((const char*)(gbase) + (voff)[_i]), (PG8_LAS unsigned*)(lds + (bufoff) + ldsw + _i * 8192), 16, 0, 0); } while (0)
; #define PG8_LDA(dst, b, h) do { _Pragma("unroll") for (int m = 0; m < 4; ++m) _Pragma("unroll") for (int k = 0; k < 2; ++k) dst[m][k] = *(const PG8_LAS bf16x8*)(lds + PG8_SA(b, h) + aoff + m * 2048 + k * 1024); } while (0)
; #define PG8_LDB(dst, b, h) do { _Pragma("unroll") for (int n = 0; n < 2; ++n) _Pragma("unroll") for (int k = 0; k < 2; ++k) dst[n][k] = *(const PG8_LAS bf16x8*)(lds + PG8_SB(b, h) + boff + n * 2048 + k * 1024); } while (0)
; #define PG8_MMA(ai, bj, At, Bt) do { __builtin_amdgcn_s_setprio(1); _Pragma("unroll") for (int m = 0; m < 4; ++m) _Pragma("unroll") for (int n = 0; n < 2; ++n) _Pragma("unroll") for (int k = 0; k < 2; ++k) \
;         acc[ai][bj][m][n] = __builtin_amdgcn_mfma_f32_16x16x32_bf16(Bt[n][k], At[m][k], acc[ai][bj][m][n], 0, 0, 0); __builtin_amdgcn_s_setprio(0); } while (0)
; #define PG8_WAIT_V(n) asm volatile("s_waitcnt vmcnt(" #n ")" ::: "memory")
; #define PG8_WAIT_L(n) asm volatile("s_waitcnt lgkmcnt(" #n ")" ::: "memory")
; template <class Epi, class Sched, bool ALIGN_EPI = false, bool SP2 = false>
; __device__ __forceinline__ void gemm_phase(PG8_LAS unsigned char* lds, const Gemm g, const Sched& S, const Epi& E) {
;     ...
;             const bool last = (t == nt - 2);
;             const char* a1 = cA + (size_t)(t + 1) * kstep;
;             const char* a2 = last ? nA : cA + (size_t)(t + 2) * kstep; const char* b2 = last ? nB : cB + (size_t)(t + 2) * kstep;
;             const char* a3 = a2 + kstep; const char* b3 = b2 + kstep;
;             if (last && has_next) S.a_ready(nxt);
;             if constexpr (SP2) {
;             PG8_LDB(B0, 0, 0); PG8_LDB(B1, 0, 1); PG8_SCHED; PG8_LDA(At, 0, 0); PG8_STAGE(PG8_SA(1, 1), a1 + hstep, voffA);
;             PG8_WAIT_V(8); PG8_WAIT_L(0); PG8_BAR; PG8_MMA(0, 0, At, B0); PG8_MMA(0, 1, At, B1); PG8_BAR; PG8_SCHED;
;             PG8_LDA(At, 0, 1); PG8_STAGE(PG8_SB(0, 0), b2, voffB); PG8_STAGE(PG8_SB(0, 1), b2 + hstep, voffB); PG8_STAGE(PG8_SA(0, 0), a2, voffA);
;             PG8_WAIT_V(8); PG8_WAIT_L(0); PG8_BAR; PG8_MMA(1, 0, At, B0); PG8_MMA(1, 1, At, B1); PG8_BAR; PG8_SCHED;
.LBB0_1080:
	ds_read_b128 v[142:145], v151
	ds_read_b128 v[154:157], v151 offset:1024
	ds_read_b128 v[158:161], v151 offset:2048
	ds_read_b128 v[162:165], v151 offset:3072
	ds_read_b128 v[166:169], v152
	ds_read_b128 v[180:183], v152 offset:1024
	ds_read_b128 v[184:187], v152 offset:2048
	ds_read_b128 v[188:191], v152 offset:3072
	s_add_u32 s20, s18, 0x100
	s_addc_u32 s21, s19, 0
	s_cmpk_eq_i32 s49, 0x54
	s_cselect_b32 s25, s13, s21
	s_cselect_b32 s24, s12, s20
	s_cselect_b32 s23, s17, s48
	s_cselect_b32 s22, s16, s47
	v_lshl_add_u64 v[146:147], s[18:19], 0, v[134:135]
	s_add_i32 m0, s29, 0xc000
	ds_read_b128 v[192:195], v153
	ds_read_b128 v[196:199], v153 offset:1024
	ds_read_b128 v[200:203], v153 offset:2048
	ds_read_b128 v[204:207], v153 offset:3072
	ds_read_b128 v[208:211], v153 offset:4096
	ds_read_b128 v[212:215], v153 offset:5120
	ds_read_b128 v[216:219], v153 offset:6144
	ds_read_b128 v[220:223], v153 offset:7168
	global_load_lds_dwordx4 v[146:147], off
	v_lshl_add_u64 v[146:147], s[18:19], 0, v[136:137]
	s_add_i32 m0, s29, 0xe000
	s_nop 0
	global_load_lds_dwordx4 v[146:147], off
	s_waitcnt vmcnt(8)
	s_waitcnt lgkmcnt(0)
	s_barrier
	s_setprio 1
	s_waitcnt lgkmcnt(0)
	v_mfma_f32_16x16x32_bf16 v[124:127], v[142:145], v[192:195], v[124:127]
	v_mfma_f32_16x16x32_bf16 v[120:123], v[158:161], v[192:195], v[120:123]
	v_mfma_f32_16x16x32_bf16 v[108:111], v[142:145], v[200:203], v[108:111]
	v_mfma_f32_16x16x32_bf16 v[104:107], v[158:161], v[200:203], v[104:107]
	v_mfma_f32_16x16x32_bf16 v[92:95], v[142:145], v[208:211], v[92:95]
	v_mfma_f32_16x16x32_bf16 v[88:91], v[158:161], v[208:211], v[88:91]
	v_mfma_f32_16x16x32_bf16 v[76:79], v[142:145], v[216:219], v[76:79]
	v_mfma_f32_16x16x32_bf16 v[72:75], v[158:161], v[216:219], v[72:75]
	v_mfma_f32_16x16x32_bf16 v[124:127], v[154:157], v[196:199], v[124:127]
	v_mfma_f32_16x16x32_bf16 v[120:123], v[162:165], v[196:199], v[120:123]
	v_mfma_f32_16x16x32_bf16 v[108:111], v[154:157], v[204:207], v[108:111]
	v_mfma_f32_16x16x32_bf16 v[104:107], v[162:165], v[204:207], v[104:107]
	v_mfma_f32_16x16x32_bf16 v[92:95], v[154:157], v[212:215], v[92:95]
	v_mfma_f32_16x16x32_bf16 v[88:91], v[162:165], v[212:215], v[88:91]
	v_mfma_f32_16x16x32_bf16 v[76:79], v[154:157], v[220:223], v[76:79]
	v_mfma_f32_16x16x32_bf16 v[72:75], v[162:165], v[220:223], v[72:75]
	s_setprio 0
	s_setprio 1
	v_mfma_f32_16x16x32_bf16 v[116:119], v[166:169], v[192:195], v[116:119]
	v_mfma_f32_16x16x32_bf16 v[112:115], v[184:187], v[192:195], v[112:115]
	v_mfma_f32_16x16x32_bf16 v[100:103], v[166:169], v[200:203], v[100:103]
	v_mfma_f32_16x16x32_bf16 v[96:99], v[184:187], v[200:203], v[96:99]
	v_mfma_f32_16x16x32_bf16 v[84:87], v[166:169], v[208:211], v[84:87]
	v_mfma_f32_16x16x32_bf16 v[80:83], v[184:187], v[208:211], v[80:83]
	v_mfma_f32_16x16x32_bf16 v[68:71], v[166:169], v[216:219], v[68:71]
	v_mfma_f32_16x16x32_bf16 v[64:67], v[184:187], v[216:219], v[64:67]
	v_mfma_f32_16x16x32_bf16 v[116:119], v[180:183], v[196:199], v[116:119]
	v_mfma_f32_16x16x32_bf16 v[112:115], v[188:191], v[196:199], v[112:115]
	v_mfma_f32_16x16x32_bf16 v[100:103], v[180:183], v[204:207], v[100:103]
	v_mfma_f32_16x16x32_bf16 v[96:99], v[188:191], v[204:207], v[96:99]
	v_mfma_f32_16x16x32_bf16 v[84:87], v[180:183], v[212:215], v[84:87]
	v_mfma_f32_16x16x32_bf16 v[80:83], v[188:191], v[212:215], v[80:83]
	v_mfma_f32_16x16x32_bf16 v[68:71], v[180:183], v[220:223], v[68:71]
	v_mfma_f32_16x16x32_bf16 v[64:67], v[188:191], v[220:223], v[64:67]
	s_setprio 0
	s_barrier
	s_add_i32 s18, s37, s28
	v_lshl_add_u64 v[146:147], s[22:23], 0, v[130:131]
	s_mov_b32 m0, s18
	ds_read_b128 v[192:195], v153 offset:16384
	ds_read_b128 v[196:199], v153 offset:17408
	ds_read_b128 v[200:203], v153 offset:18432
	ds_read_b128 v[204:207], v153 offset:19456
	ds_read_b128 v[208:211], v153 offset:20480
	ds_read_b128 v[212:215], v153 offset:21504
	ds_read_b128 v[216:219], v153 offset:22528
	ds_read_b128 v[220:223], v153 offset:23552
	global_load_lds_dwordx4 v[146:147], off
	s_add_i32 m0, s18, 0x2000
	s_add_u32 s18, s22, 0x160000
	v_lshl_add_u64 v[170:171], s[22:23], 0, v[132:133]
	s_addc_u32 s19, s23, 0
	s_add_i32 s50, s40, s28
	global_load_lds_dwordx4 v[170:171], off
	v_lshl_add_u64 v[224:225], s[18:19], 0, v[130:131]
	s_mov_b32 m0, s50
	v_lshl_add_u64 v[226:227], s[24:25], 0, v[132:133]
	global_load_lds_dwordx4 v[224:225], off
	v_lshl_add_u64 v[224:225], s[18:19], 0, v[132:133]
	s_add_i32 m0, s50, 0x2000
	s_nop 0
	global_load_lds_dwordx4 v[224:225], off
	v_lshl_add_u64 v[224:225], s[24:25], 0, v[130:131]
	s_mov_b32 m0, s29
	s_nop 0
	global_load_lds_dwordx4 v[224:225], off
	s_mov_b32 m0, s30
	s_nop 0
	global_load_lds_dwordx4 v[226:227], off
	s_waitcnt vmcnt(8)
	s_waitcnt lgkmcnt(0)
	s_barrier
; #define PG8_STAGE(bufoff, gbase, voff) do { _Pragma("unroll") for (int _i = 0; _i < 2; ++_i) \
;         __builtin_amdgcn_global_load_lds((const unsigned*)((const char*)(gbase) + (voff)[_i]), (PG8_LAS unsigned*)(lds + (bufoff) + ldsw + _i * 8192), 16, 0, 0); } while (0)
; #define PG8_LDA(dst, b, h) do { _Pragma("unroll") for (int m = 0; m < 4; ++m) _Pragma("unroll") for (int k = 0; k < 2; ++k) dst[m][k] = *(const PG8_LAS bf16x8*)(lds + PG8_SA(b, h) + aoff + m * 2048 + k * 1024); } while (0)
; #define PG8_LDB(dst, b, h) do { _Pragma("unroll") for (int n = 0; n < 2; ++n) _Pragma("unroll") for (int k = 0; k < 2; ++k) dst[n][k] = *(const PG8_LAS bf16x8*)(lds + PG8_SB(b, h) + boff + n * 2048 + k * 1024); } while (0)
; #define PG8_MMA(ai, bj, At, Bt) do { __builtin_amdgcn_s_setprio(1); _Pragma("unroll") for (int m = 0; m < 4; ++m) _Pragma("unroll") for (int n = 0; n < 2; ++n) _Pragma("unroll") for (int k = 0; k < 2; ++k) \
;         acc[ai][bj][m][n] = __builtin_amdgcn_mfma_f32_16x16x32_bf16(Bt[n][k], At[m][k], acc[ai][bj][m][n], 0, 0, 0); __builtin_amdgcn_s_setprio(0); } while (0)
; #define PG8_WAIT_V(n) asm volatile("s_waitcnt vmcnt(" #n ")" ::: "memory")
; #define PG8_WAIT_L(n) asm volatile("s_waitcnt lgkmcnt(" #n ")" ::: "memory")
; #define PG8_BAR __builtin_amdgcn_s_barrier()
; #define PG8_SCHED __builtin_amdgcn_sched_barrier(0)
; template <class Epi, class Sched, bool ALIGN_EPI = false, bool SP2 = false>
; __device__ __forceinline__ void gemm_phase(PG8_LAS unsigned char* lds, const Gemm g, const Sched& S, const Epi& E) {
;     ...
;             PG8_WAIT_V(8); PG8_WAIT_L(0); PG8_BAR; PG8_MMA(1, 0, At, B0); PG8_MMA(1, 1, At, B1); PG8_BAR; PG8_SCHED;
;             PG8_LDB(B0, 1, 0); PG8_LDB(B1, 1, 1); PG8_SCHED; PG8_LDA(At, 1, 0); PG8_STAGE(PG8_SA(0, 1), a2 + hstep, voffA);
;             PG8_WAIT_V(8); PG8_WAIT_L(0); PG8_BAR; PG8_MMA(0, 0, At, B0); PG8_MMA(0, 1, At, B1); PG8_BAR; PG8_SCHED;
	s_setprio 1
	s_waitcnt lgkmcnt(0)
	v_mfma_f32_16x16x32_bf16 v[60:63], v[142:145], v[192:195], v[60:63]
	v_mfma_f32_16x16x32_bf16 v[56:59], v[158:161], v[192:195], v[56:59]
	v_mfma_f32_16x16x32_bf16 v[44:47], v[142:145], v[200:203], v[44:47]
	v_mfma_f32_16x16x32_bf16 v[40:43], v[158:161], v[200:203], v[40:43]
	v_mfma_f32_16x16x32_bf16 v[28:31], v[142:145], v[208:211], v[28:31]
	v_mfma_f32_16x16x32_bf16 v[24:27], v[158:161], v[208:211], v[24:27]
	v_mfma_f32_16x16x32_bf16 v[12:15], v[142:145], v[216:219], v[12:15]
	v_mfma_f32_16x16x32_bf16 v[8:11], v[158:161], v[216:219], v[8:11]
	v_mfma_f32_16x16x32_bf16 v[60:63], v[154:157], v[196:199], v[60:63]
	v_mfma_f32_16x16x32_bf16 v[56:59], v[162:165], v[196:199], v[56:59]
	v_mfma_f32_16x16x32_bf16 v[44:47], v[154:157], v[204:207], v[44:47]
	v_mfma_f32_16x16x32_bf16 v[40:43], v[162:165], v[204:207], v[40:43]
	v_mfma_f32_16x16x32_bf16 v[28:31], v[154:157], v[212:215], v[28:31]
	v_mfma_f32_16x16x32_bf16 v[24:27], v[162:165], v[212:215], v[24:27]
	v_mfma_f32_16x16x32_bf16 v[12:15], v[154:157], v[220:223], v[12:15]
	v_mfma_f32_16x16x32_bf16 v[8:11], v[162:165], v[220:223], v[8:11]
	s_setprio 0
	s_setprio 1
	v_mfma_f32_16x16x32_bf16 v[52:55], v[166:169], v[192:195], v[52:55]
	v_mfma_f32_16x16x32_bf16 v[48:51], v[184:187], v[192:195], v[48:51]
	v_mfma_f32_16x16x32_bf16 v[36:39], v[166:169], v[200:203], v[36:39]
	v_mfma_f32_16x16x32_bf16 v[32:35], v[184:187], v[200:203], v[32:35]
	v_mfma_f32_16x16x32_bf16 v[20:23], v[166:169], v[208:211], v[20:23]
	v_mfma_f32_16x16x32_bf16 v[16:19], v[184:187], v[208:211], v[16:19]
	v_mfma_f32_16x16x32_bf16 v[4:7], v[166:169], v[216:219], v[4:7]
	v_mfma_f32_16x16x32_bf16 v[0:3], v[184:187], v[216:219], v[0:3]
	v_mfma_f32_16x16x32_bf16 v[52:55], v[180:183], v[196:199], v[52:55]
	v_mfma_f32_16x16x32_bf16 v[48:51], v[188:191], v[196:199], v[48:51]
	v_mfma_f32_16x16x32_bf16 v[36:39], v[180:183], v[204:207], v[36:39]
	v_mfma_f32_16x16x32_bf16 v[32:35], v[188:191], v[204:207], v[32:35]
	v_mfma_f32_16x16x32_bf16 v[20:23], v[180:183], v[212:215], v[20:23]
	v_mfma_f32_16x16x32_bf16 v[16:19], v[188:191], v[212:215], v[16:19]
	v_mfma_f32_16x16x32_bf16 v[4:7], v[180:183], v[220:223], v[4:7]
	v_mfma_f32_16x16x32_bf16 v[0:3], v[188:191], v[220:223], v[0:3]
	s_setprio 0
	s_barrier
	s_add_i32 s50, 0, 0x18000
	s_add_i32 s51, 0, 0x1c000
	v_add_u32_e32 v162, s50, v149
	v_add_u32_e32 v179, s51, v149
	ds_read_b128 v[142:145], v162
	ds_read_b128 v[154:157], v162 offset:1024
	ds_read_b128 v[158:161], v162 offset:2048
	ds_read_b128 v[162:165], v162 offset:3072
	ds_read_b128 v[166:169], v179
	ds_read_b128 v[180:183], v179 offset:1024
	ds_read_b128 v[184:187], v179 offset:2048
	ds_read_b128 v[188:191], v179 offset:3072
	s_add_u32 s18, s24, 0x160000
	s_addc_u32 s19, s25, 0
	s_mov_b32 m0, s31
	v_lshl_add_u64 v[228:229], s[18:19], 0, v[130:131]
	ds_read_b128 v[192:195], v153 offset:32768
	ds_read_b128 v[196:199], v153 offset:33792
	ds_read_b128 v[200:203], v153 offset:34816
	ds_read_b128 v[204:207], v153 offset:35840
	ds_read_b128 v[208:211], v153 offset:36864
	ds_read_b128 v[212:215], v153 offset:37888
	ds_read_b128 v[216:219], v153 offset:38912
	ds_read_b128 v[220:223], v153 offset:39936
	global_load_lds_dwordx4 v[228:229], off
	v_lshl_add_u64 v[228:229], s[18:19], 0, v[132:133]
	s_mov_b32 m0, s33
	s_nop 0
	global_load_lds_dwordx4 v[228:229], off
	s_waitcnt vmcnt(8)
	s_waitcnt lgkmcnt(0)
	s_barrier
	s_setprio 1
	s_waitcnt lgkmcnt(0)
	v_mfma_f32_16x16x32_bf16 v[124:127], v[142:145], v[192:195], v[124:127]
	v_mfma_f32_16x16x32_bf16 v[120:123], v[158:161], v[192:195], v[120:123]
	v_mfma_f32_16x16x32_bf16 v[108:111], v[142:145], v[200:203], v[108:111]
	v_mfma_f32_16x16x32_bf16 v[104:107], v[158:161], v[200:203], v[104:107]
	v_mfma_f32_16x16x32_bf16 v[92:95], v[142:145], v[208:211], v[92:95]
	v_mfma_f32_16x16x32_bf16 v[88:91], v[158:161], v[208:211], v[88:91]
	v_mfma_f32_16x16x32_bf16 v[76:79], v[142:145], v[216:219], v[76:79]
	v_mfma_f32_16x16x32_bf16 v[72:75], v[158:161], v[216:219], v[72:75]
	v_mfma_f32_16x16x32_bf16 v[124:127], v[154:157], v[196:199], v[124:127]
	v_mfma_f32_16x16x32_bf16 v[120:123], v[162:165], v[196:199], v[120:123]
	v_mfma_f32_16x16x32_bf16 v[108:111], v[154:157], v[204:207], v[108:111]
	v_mfma_f32_16x16x32_bf16 v[104:107], v[162:165], v[204:207], v[104:107]
	v_mfma_f32_16x16x32_bf16 v[92:95], v[154:157], v[212:215], v[92:95]
	v_mfma_f32_16x16x32_bf16 v[88:91], v[162:165], v[212:215], v[88:91]
	v_mfma_f32_16x16x32_bf16 v[76:79], v[154:157], v[220:223], v[76:79]
	v_mfma_f32_16x16x32_bf16 v[72:75], v[162:165], v[220:223], v[72:75]
	s_setprio 0
	s_setprio 1
	v_mfma_f32_16x16x32_bf16 v[116:119], v[166:169], v[192:195], v[116:119]
	v_mfma_f32_16x16x32_bf16 v[112:115], v[184:187], v[192:195], v[112:115]
	v_mfma_f32_16x16x32_bf16 v[100:103], v[166:169], v[200:203], v[100:103]
	v_mfma_f32_16x16x32_bf16 v[96:99], v[184:187], v[200:203], v[96:99]
	v_mfma_f32_16x16x32_bf16 v[84:87], v[166:169], v[208:211], v[84:87]
	v_mfma_f32_16x16x32_bf16 v[80:83], v[184:187], v[208:211], v[80:83]
	v_mfma_f32_16x16x32_bf16 v[68:71], v[166:169], v[216:219], v[68:71]
	v_mfma_f32_16x16x32_bf16 v[64:67], v[184:187], v[216:219], v[64:67]
	v_mfma_f32_16x16x32_bf16 v[116:119], v[180:183], v[196:199], v[116:119]
	v_mfma_f32_16x16x32_bf16 v[112:115], v[188:191], v[196:199], v[112:115]
	v_mfma_f32_16x16x32_bf16 v[100:103], v[180:183], v[204:207], v[100:103]
	v_mfma_f32_16x16x32_bf16 v[96:99], v[188:191], v[204:207], v[96:99]
	v_mfma_f32_16x16x32_bf16 v[84:87], v[180:183], v[212:215], v[84:87]
	v_mfma_f32_16x16x32_bf16 v[80:83], v[188:191], v[212:215], v[80:83]
	v_mfma_f32_16x16x32_bf16 v[68:71], v[180:183], v[220:223], v[68:71]
	v_mfma_f32_16x16x32_bf16 v[64:67], v[188:191], v[220:223], v[64:67]
	s_setprio 0
	s_barrier
; #define PG8_STAGE(bufoff, gbase, voff) do { _Pragma("unroll") for (int _i = 0; _i < 2; ++_i) \
;         __builtin_amdgcn_global_load_lds((const unsigned*)((const char*)(gbase) + (voff)[_i]), (PG8_LAS unsigned*)(lds + (bufoff) + ldsw + _i * 8192), 16, 0, 0); } while (0)
; #define PG8_LDA(dst, b, h) do { _Pragma("unroll") for (int m = 0; m < 4; ++m) _Pragma("unroll") for (int k = 0; k < 2; ++k) dst[m][k] = *(const PG8_LAS bf16x8*)(lds + PG8_SA(b, h) + aoff + m * 2048 + k * 1024); } while (0)
; #define PG8_MMA(ai, bj, At, Bt) do { __builtin_amdgcn_s_setprio(1); _Pragma("unroll") for (int m = 0; m < 4; ++m) _Pragma("unroll") for (int n = 0; n < 2; ++n) _Pragma("unroll") for (int k = 0; k < 2; ++k) \
;         acc[ai][bj][m][n] = __builtin_amdgcn_mfma_f32_16x16x32_bf16(Bt[n][k], At[m][k], acc[ai][bj][m][n], 0, 0, 0); __builtin_amdgcn_s_setprio(0); } while (0)
; #define PG8_WAIT_V(n) asm volatile("s_waitcnt vmcnt(" #n ")" ::: "memory")
; #define PG8_WAIT_L(n) asm volatile("s_waitcnt lgkmcnt(" #n ")" ::: "memory")
; #define PG8_BAR __builtin_amdgcn_s_barrier()
; #define PG8_SCHED __builtin_amdgcn_sched_barrier(0)
; template <class Epi, class Sched, bool ALIGN_EPI = false, bool SP2 = false>
; __device__ __forceinline__ void gemm_phase(PG8_LAS unsigned char* lds, const Gemm g, const Sched& S, const Epi& E) {
;     ...
;             PG8_LDA(At, 1, 1); PG8_STAGE(PG8_SB(1, 0), b3, voffB); PG8_STAGE(PG8_SB(1, 1), b3 + hstep, voffB); PG8_STAGE(PG8_SA(1, 0), a3, voffA);
;             PG8_WAIT_V(8); PG8_WAIT_L(0); PG8_BAR; PG8_MMA(1, 0, At, B0); PG8_MMA(1, 1, At, B1); PG8_BAR; PG8_SCHED;
;     ...
;         if constexpr (ALIGN_EPI) { if (wr == 0) PG8_BAR; }
	s_add_i32 s18, s50, s28
	v_lshl_add_u64 v[146:147], v[146:147], 0, s[4:5]
	s_mov_b32 m0, s18
	ds_read_b128 v[192:195], v153 offset:49152
	ds_read_b128 v[196:199], v153 offset:50176
	ds_read_b128 v[200:203], v153 offset:51200
	ds_read_b128 v[204:207], v153 offset:52224
	ds_read_b128 v[208:211], v153 offset:53248
	ds_read_b128 v[212:215], v153 offset:54272
	ds_read_b128 v[216:219], v153 offset:55296
	ds_read_b128 v[220:223], v153 offset:56320
	global_load_lds_dwordx4 v[146:147], off
	s_add_i32 m0, s18, 0x2000
	s_add_u32 s18, s22, 0x160080
	v_lshl_add_u64 v[146:147], v[170:171], 0, s[4:5]
	s_addc_u32 s19, s23, 0
	s_add_i32 s22, s51, s28
	global_load_lds_dwordx4 v[146:147], off
	v_lshl_add_u64 v[146:147], s[18:19], 0, v[130:131]
	s_mov_b32 m0, s22
	s_nop 0
	global_load_lds_dwordx4 v[146:147], off
	v_lshl_add_u64 v[146:147], s[18:19], 0, v[132:133]
	s_add_i32 m0, s22, 0x2000
	s_nop 0
	global_load_lds_dwordx4 v[146:147], off
	v_lshl_add_u64 v[146:147], v[224:225], 0, s[4:5]
	s_mov_b32 m0, s35
	s_nop 0
	global_load_lds_dwordx4 v[146:147], off
	v_lshl_add_u64 v[146:147], v[226:227], 0, s[4:5]
	s_mov_b32 m0, s36
	s_nop 0
	global_load_lds_dwordx4 v[146:147], off
	s_waitcnt vmcnt(8)
	s_waitcnt lgkmcnt(0)
	s_barrier
	s_setprio 1
	s_waitcnt lgkmcnt(0)
	v_mfma_f32_16x16x32_bf16 v[60:63], v[142:145], v[192:195], v[60:63]
	v_mfma_f32_16x16x32_bf16 v[56:59], v[158:161], v[192:195], v[56:59]
	v_mfma_f32_16x16x32_bf16 v[44:47], v[142:145], v[200:203], v[44:47]
	v_mfma_f32_16x16x32_bf16 v[40:43], v[158:161], v[200:203], v[40:43]
	v_mfma_f32_16x16x32_bf16 v[28:31], v[142:145], v[208:211], v[28:31]
	v_mfma_f32_16x16x32_bf16 v[24:27], v[158:161], v[208:211], v[24:27]
	v_mfma_f32_16x16x32_bf16 v[12:15], v[142:145], v[216:219], v[12:15]
	v_mfma_f32_16x16x32_bf16 v[8:11], v[158:161], v[216:219], v[8:11]
	v_mfma_f32_16x16x32_bf16 v[60:63], v[154:157], v[196:199], v[60:63]
	v_mfma_f32_16x16x32_bf16 v[56:59], v[162:165], v[196:199], v[56:59]
	v_mfma_f32_16x16x32_bf16 v[44:47], v[154:157], v[204:207], v[44:47]
	v_mfma_f32_16x16x32_bf16 v[40:43], v[162:165], v[204:207], v[40:43]
	v_mfma_f32_16x16x32_bf16 v[28:31], v[154:157], v[212:215], v[28:31]
	v_mfma_f32_16x16x32_bf16 v[24:27], v[162:165], v[212:215], v[24:27]
	v_mfma_f32_16x16x32_bf16 v[12:15], v[154:157], v[220:223], v[12:15]
	v_mfma_f32_16x16x32_bf16 v[8:11], v[162:165], v[220:223], v[8:11]
	s_setprio 0
	s_setprio 1
	v_mfma_f32_16x16x32_bf16 v[52:55], v[166:169], v[192:195], v[52:55]
	v_mfma_f32_16x16x32_bf16 v[48:51], v[184:187], v[192:195], v[48:51]
	v_mfma_f32_16x16x32_bf16 v[36:39], v[166:169], v[200:203], v[36:39]
	v_mfma_f32_16x16x32_bf16 v[32:35], v[184:187], v[200:203], v[32:35]
	v_mfma_f32_16x16x32_bf16 v[20:23], v[166:169], v[208:211], v[20:23]
	v_mfma_f32_16x16x32_bf16 v[16:19], v[184:187], v[208:211], v[16:19]
	v_mfma_f32_16x16x32_bf16 v[4:7], v[166:169], v[216:219], v[4:7]
	v_mfma_f32_16x16x32_bf16 v[0:3], v[184:187], v[216:219], v[0:3]
	v_mfma_f32_16x16x32_bf16 v[52:55], v[180:183], v[196:199], v[52:55]
	v_mfma_f32_16x16x32_bf16 v[48:51], v[188:191], v[196:199], v[48:51]
	v_mfma_f32_16x16x32_bf16 v[36:39], v[180:183], v[204:207], v[36:39]
	v_mfma_f32_16x16x32_bf16 v[32:35], v[188:191], v[204:207], v[32:35]
	v_mfma_f32_16x16x32_bf16 v[20:23], v[180:183], v[212:215], v[20:23]
	v_mfma_f32_16x16x32_bf16 v[16:19], v[188:191], v[212:215], v[16:19]
	v_mfma_f32_16x16x32_bf16 v[4:7], v[180:183], v[220:223], v[4:7]
	v_mfma_f32_16x16x32_bf16 v[0:3], v[188:191], v[220:223], v[0:3]
	s_setprio 0
	s_barrier
	s_add_i32 s49, s49, 2
	s_add_u32 s47, s47, 0x100
	s_addc_u32 s48, s48, 0
	s_cmpk_gt_u32 s49, 0x55
	s_mov_b64 s[18:19], s[20:21]
	s_cbranch_scc0 .LBB0_1080
	s_nop 0
	v_readfirstlane_b32 s18, v172
	s_nop 3
	s_lshr_b32 s18, s18, 6
	s_cmp_lt_u32 s18, 4
	s_cbranch_scc0 .Lprio_k3
	s_setprio 1

; #define PG8_STAGE(bufoff, gbase, voff) do { _Pragma("unroll") for (int _i = 0; _i < 2; ++_i) \
;         __builtin_amdgcn_global_load_lds((const unsigned*)((const char*)(gbase) + (voff)[_i]), (PG8_LAS unsigned*)(lds + (bufoff) + ldsw + _i * 8192), 16, 0, 0); } while (0)
; #define PG8_LDA(dst, b, h) do { _Pragma("unroll") for (int m = 0; m < 4; ++m) _Pragma("unroll") for (int k = 0; k < 2; ++k) dst[m][k] = *(const PG8_LAS bf16x8*)(lds + PG8_SA(b, h) + aoff + m * 2048 + k * 1024); } while (0)
; #define PG8_LDB(dst, b, h) do { _Pragma("unroll") for (int n = 0; n < 2; ++n) _Pragma("unroll") for (int k = 0; k < 2; ++k) dst[n][k] = *(const PG8_LAS bf16x8*)(lds + PG8_SB(b, h) + boff + n * 2048 + k * 1024); } while (0)
; #define PG8_MMA(ai, bj, At, Bt) do { __builtin_amdgcn_s_setprio(1); _Pragma("unroll") for (int m = 0; m < 4; ++m) _Pragma("unroll") for (int n = 0; n < 2; ++n) _Pragma("unroll") for (int k = 0; k < 2; ++k) \
;         acc[ai][bj][m][n] = __builtin_amdgcn_mfma_f32_16x16x32_bf16(Bt[n][k], At[m][k], acc[ai][bj][m][n], 0, 0, 0); __builtin_amdgcn_s_setprio(0); } while (0)
; #define PG8_WAIT_V(n) asm volatile("s_waitcnt vmcnt(" #n ")" ::: "memory")
; #define PG8_WAIT_L(n) asm volatile("s_waitcnt lgkmcnt(" #n ")" ::: "memory")
; template <class Epi, class Sched, bool ALIGN_EPI = false, bool SP2 = false>
; __device__ __forceinline__ void gemm_phase(PG8_LAS unsigned char* lds, const Gemm g, const Sched& S, const Epi& E) {
;     ...
;             const bool last = (t == nt - 2);
;             const char* a1 = cA + (size_t)(t + 1) * kstep;
;             const char* a2 = last ? nA : cA + (size_t)(t + 2) * kstep; const char* b2 = last ? nB : cB + (size_t)(t + 2) * kstep;
;             const char* a3 = a2 + kstep; const char* b3 = b2 + kstep;
;             if (last && has_next) S.a_ready(nxt);
;             if constexpr (SP2) {
;             PG8_LDB(B0, 0, 0); PG8_LDB(B1, 0, 1); PG8_SCHED; PG8_LDA(At, 0, 0); PG8_STAGE(PG8_SA(1, 1), a1 + hstep, voffA);
;             PG8_WAIT_V(8); PG8_WAIT_L(0); PG8_BAR; PG8_MMA(0, 0, At, B0); PG8_MMA(0, 1, At, B1); PG8_BAR; PG8_SCHED;
;             PG8_LDA(At, 0, 1); PG8_STAGE(PG8_SB(0, 0), b2, voffB); PG8_STAGE(PG8_SB(0, 1), b2 + hstep, voffB); PG8_STAGE(PG8_SA(0, 0), a2, voffA);
;             PG8_WAIT_V(8); PG8_WAIT_L(0); PG8_BAR; PG8_MMA(1, 0, At, B0); PG8_MMA(1, 1, At, B1); PG8_BAR; PG8_SCHED;
.LBB0_1181:
	ds_read_b128 v[146:149], v154
	ds_read_b128 v[158:161], v154 offset:1024
	ds_read_b128 v[162:165], v154 offset:2048
	ds_read_b128 v[166:169], v154 offset:3072
	ds_read_b128 v[180:183], v155
	ds_read_b128 v[184:187], v155 offset:1024
	ds_read_b128 v[188:191], v155 offset:2048
	ds_read_b128 v[192:195], v155 offset:3072
	s_add_u32 s22, s20, 0xfff80080
	s_addc_u32 s23, s21, -1
	s_cmp_eq_u32 s48, 28
	s_cselect_b32 s25, s11, s23
	s_cselect_b32 s24, s44, s22
	s_cselect_b32 s23, s7, s47
	s_cselect_b32 s22, s45, s46
	v_lshl_add_u64 v[170:171], s[20:21], 0, v[138:139]
	s_add_i32 m0, s17, 0xc000
	ds_read_b128 v[196:199], v156
	ds_read_b128 v[200:203], v156 offset:1024
	ds_read_b128 v[204:207], v156 offset:2048
	ds_read_b128 v[208:211], v156 offset:3072
	ds_read_b128 v[212:215], v156 offset:4096
	ds_read_b128 v[216:219], v156 offset:5120
	ds_read_b128 v[220:223], v156 offset:6144
	ds_read_b128 v[224:227], v156 offset:7168
	global_load_lds_dwordx4 v[170:171], off
	v_lshl_add_u64 v[170:171], s[20:21], 0, v[140:141]
	s_add_i32 m0, s17, 0xe000
	s_nop 0
	global_load_lds_dwordx4 v[170:171], off
	s_waitcnt vmcnt(8)
	s_waitcnt lgkmcnt(0)
	s_barrier
	s_setprio 1
	s_waitcnt lgkmcnt(0)
	v_mfma_f32_16x16x32_bf16 v[124:127], v[146:149], v[196:199], v[124:127]
	v_mfma_f32_16x16x32_bf16 v[120:123], v[162:165], v[196:199], v[120:123]
	v_mfma_f32_16x16x32_bf16 v[112:115], v[146:149], v[204:207], v[112:115]
	v_mfma_f32_16x16x32_bf16 v[104:107], v[162:165], v[204:207], v[104:107]
	v_mfma_f32_16x16x32_bf16 v[96:99], v[146:149], v[212:215], v[96:99]
	v_mfma_f32_16x16x32_bf16 v[88:91], v[162:165], v[212:215], v[88:91]
	v_mfma_f32_16x16x32_bf16 v[80:83], v[146:149], v[220:223], v[80:83]
	v_mfma_f32_16x16x32_bf16 v[72:75], v[162:165], v[220:223], v[72:75]
	v_mfma_f32_16x16x32_bf16 v[124:127], v[158:161], v[200:203], v[124:127]
	v_mfma_f32_16x16x32_bf16 v[120:123], v[166:169], v[200:203], v[120:123]
	v_mfma_f32_16x16x32_bf16 v[112:115], v[158:161], v[208:211], v[112:115]
	v_mfma_f32_16x16x32_bf16 v[104:107], v[166:169], v[208:211], v[104:107]
	v_mfma_f32_16x16x32_bf16 v[96:99], v[158:161], v[216:219], v[96:99]
	v_mfma_f32_16x16x32_bf16 v[88:91], v[166:169], v[216:219], v[88:91]
	v_mfma_f32_16x16x32_bf16 v[80:83], v[158:161], v[224:227], v[80:83]
	v_mfma_f32_16x16x32_bf16 v[72:75], v[166:169], v[224:227], v[72:75]
	s_setprio 0
	s_setprio 1
	v_mfma_f32_16x16x32_bf16 v[116:119], v[180:183], v[196:199], v[116:119]
	v_mfma_f32_16x16x32_bf16 v[108:111], v[188:191], v[196:199], v[108:111]
	v_mfma_f32_16x16x32_bf16 v[100:103], v[180:183], v[204:207], v[100:103]
	v_mfma_f32_16x16x32_bf16 v[92:95], v[188:191], v[204:207], v[92:95]
	v_mfma_f32_16x16x32_bf16 v[84:87], v[180:183], v[212:215], v[84:87]
	v_mfma_f32_16x16x32_bf16 v[76:79], v[188:191], v[212:215], v[76:79]
	v_mfma_f32_16x16x32_bf16 v[68:71], v[180:183], v[220:223], v[68:71]
	v_mfma_f32_16x16x32_bf16 v[64:67], v[188:191], v[220:223], v[64:67]
	v_mfma_f32_16x16x32_bf16 v[116:119], v[184:187], v[200:203], v[116:119]
	v_mfma_f32_16x16x32_bf16 v[108:111], v[192:195], v[200:203], v[108:111]
	v_mfma_f32_16x16x32_bf16 v[100:103], v[184:187], v[208:211], v[100:103]
	v_mfma_f32_16x16x32_bf16 v[92:95], v[192:195], v[208:211], v[92:95]
	v_mfma_f32_16x16x32_bf16 v[84:87], v[184:187], v[216:219], v[84:87]
	v_mfma_f32_16x16x32_bf16 v[76:79], v[192:195], v[216:219], v[76:79]
	v_mfma_f32_16x16x32_bf16 v[68:71], v[184:187], v[224:227], v[68:71]
	v_mfma_f32_16x16x32_bf16 v[64:67], v[192:195], v[224:227], v[64:67]
	s_setprio 0
	s_barrier
	s_add_i32 s49, s35, s28
	v_lshl_add_u64 v[170:171], s[22:23], 0, v[132:133]
	s_mov_b32 m0, s49
	ds_read_b128 v[196:199], v156 offset:16384
	ds_read_b128 v[200:203], v156 offset:17408
	ds_read_b128 v[204:207], v156 offset:18432
	ds_read_b128 v[208:211], v156 offset:19456
	ds_read_b128 v[212:215], v156 offset:20480
	ds_read_b128 v[216:219], v156 offset:21504
	ds_read_b128 v[220:223], v156 offset:22528
	ds_read_b128 v[224:227], v156 offset:23552
	global_load_lds_dwordx4 v[170:171], off
	s_add_i32 m0, s49, 0x2000
	s_add_u32 s50, s22, 0x80000
	v_lshl_add_u64 v[228:229], s[22:23], 0, v[136:137]
	s_addc_u32 s51, s23, 0
	s_add_i32 s49, s36, s28
	global_load_lds_dwordx4 v[228:229], off
	v_lshl_add_u64 v[230:231], s[50:51], 0, v[132:133]
	s_mov_b32 m0, s49
	v_lshl_add_u64 v[232:233], s[24:25], 0, v[134:135]
	global_load_lds_dwordx4 v[230:231], off
	v_lshl_add_u64 v[230:231], s[50:51], 0, v[136:137]
	s_add_i32 m0, s49, 0x2000
	s_nop 0
	global_load_lds_dwordx4 v[230:231], off
	v_lshl_add_u64 v[230:231], s[24:25], 0, v[130:131]
	s_mov_b32 m0, s17
	s_nop 0
	global_load_lds_dwordx4 v[230:231], off
	s_mov_b32 m0, s29
	s_nop 0
	global_load_lds_dwordx4 v[232:233], off
	s_waitcnt vmcnt(8)
	s_waitcnt lgkmcnt(0)
	s_barrier
; #define PG8_STAGE(bufoff, gbase, voff) do { _Pragma("unroll") for (int _i = 0; _i < 2; ++_i) \
;         __builtin_amdgcn_global_load_lds((const unsigned*)((const char*)(gbase) + (voff)[_i]), (PG8_LAS unsigned*)(lds + (bufoff) + ldsw + _i * 8192), 16, 0, 0); } while (0)
; #define PG8_LDA(dst, b, h) do { _Pragma("unroll") for (int m = 0; m < 4; ++m) _Pragma("unroll") for (int k = 0; k < 2; ++k) dst[m][k] = *(const PG8_LAS bf16x8*)(lds + PG8_SA(b, h) + aoff + m * 2048 + k * 1024); } while (0)
; #define PG8_LDB(dst, b, h) do { _Pragma("unroll") for (int n = 0; n < 2; ++n) _Pragma("unroll") for (int k = 0; k < 2; ++k) dst[n][k] = *(const PG8_LAS bf16x8*)(lds + PG8_SB(b, h) + boff + n * 2048 + k * 1024); } while (0)
; #define PG8_MMA(ai, bj, At, Bt) do { __builtin_amdgcn_s_setprio(1); _Pragma("unroll") for (int m = 0; m < 4; ++m) _Pragma("unroll") for (int n = 0; n < 2; ++n) _Pragma("unroll") for (int k = 0; k < 2; ++k) \
;         acc[ai][bj][m][n] = __builtin_amdgcn_mfma_f32_16x16x32_bf16(Bt[n][k], At[m][k], acc[ai][bj][m][n], 0, 0, 0); __builtin_amdgcn_s_setprio(0); } while (0)
; #define PG8_WAIT_V(n) asm volatile("s_waitcnt vmcnt(" #n ")" ::: "memory")
; #define PG8_WAIT_L(n) asm volatile("s_waitcnt lgkmcnt(" #n ")" ::: "memory")
; #define PG8_BAR __builtin_amdgcn_s_barrier()
; #define PG8_SCHED __builtin_amdgcn_sched_barrier(0)
; template <class Epi, class Sched, bool ALIGN_EPI = false, bool SP2 = false>
; __device__ __forceinline__ void gemm_phase(PG8_LAS unsigned char* lds, const Gemm g, const Sched& S, const Epi& E) {
;     ...
;             PG8_WAIT_V(8); PG8_WAIT_L(0); PG8_BAR; PG8_MMA(1, 0, At, B0); PG8_MMA(1, 1, At, B1); PG8_BAR; PG8_SCHED;
;             PG8_LDB(B0, 1, 0); PG8_LDB(B1, 1, 1); PG8_SCHED; PG8_LDA(At, 1, 0); PG8_STAGE(PG8_SA(0, 1), a2 + hstep, voffA);
;             PG8_WAIT_V(8); PG8_WAIT_L(0); PG8_BAR; PG8_MMA(0, 0, At, B0); PG8_MMA(0, 1, At, B1); PG8_BAR; PG8_SCHED;
	s_setprio 1
	s_waitcnt lgkmcnt(0)
	v_mfma_f32_16x16x32_bf16 v[60:63], v[146:149], v[196:199], v[60:63]
	v_mfma_f32_16x16x32_bf16 v[56:59], v[162:165], v[196:199], v[56:59]
	v_mfma_f32_16x16x32_bf16 v[52:55], v[146:149], v[204:207], v[52:55]
	v_mfma_f32_16x16x32_bf16 v[44:47], v[162:165], v[204:207], v[44:47]
	v_mfma_f32_16x16x32_bf16 v[36:39], v[146:149], v[212:215], v[36:39]
	v_mfma_f32_16x16x32_bf16 v[28:31], v[162:165], v[212:215], v[28:31]
	v_mfma_f32_16x16x32_bf16 v[20:23], v[146:149], v[220:223], v[20:23]
	v_mfma_f32_16x16x32_bf16 v[12:15], v[162:165], v[220:223], v[12:15]
	v_mfma_f32_16x16x32_bf16 v[60:63], v[158:161], v[200:203], v[60:63]
	v_mfma_f32_16x16x32_bf16 v[56:59], v[166:169], v[200:203], v[56:59]
	v_mfma_f32_16x16x32_bf16 v[52:55], v[158:161], v[208:211], v[52:55]
	v_mfma_f32_16x16x32_bf16 v[44:47], v[166:169], v[208:211], v[44:47]
	v_mfma_f32_16x16x32_bf16 v[36:39], v[158:161], v[216:219], v[36:39]
	v_mfma_f32_16x16x32_bf16 v[28:31], v[166:169], v[216:219], v[28:31]
	v_mfma_f32_16x16x32_bf16 v[20:23], v[158:161], v[224:227], v[20:23]
	v_mfma_f32_16x16x32_bf16 v[12:15], v[166:169], v[224:227], v[12:15]
	s_setprio 0
	s_setprio 1
	v_mfma_f32_16x16x32_bf16 v[48:51], v[180:183], v[196:199], v[48:51]
	v_mfma_f32_16x16x32_bf16 v[40:43], v[188:191], v[196:199], v[40:43]
	v_mfma_f32_16x16x32_bf16 v[32:35], v[180:183], v[204:207], v[32:35]
	v_mfma_f32_16x16x32_bf16 v[24:27], v[188:191], v[204:207], v[24:27]
	v_mfma_f32_16x16x32_bf16 v[16:19], v[180:183], v[212:215], v[16:19]
	v_mfma_f32_16x16x32_bf16 v[8:11], v[188:191], v[212:215], v[8:11]
	v_mfma_f32_16x16x32_bf16 v[4:7], v[180:183], v[220:223], v[4:7]
	v_mfma_f32_16x16x32_bf16 v[0:3], v[188:191], v[220:223], v[0:3]
	v_mfma_f32_16x16x32_bf16 v[48:51], v[184:187], v[200:203], v[48:51]
	v_mfma_f32_16x16x32_bf16 v[40:43], v[192:195], v[200:203], v[40:43]
	v_mfma_f32_16x16x32_bf16 v[32:35], v[184:187], v[208:211], v[32:35]
	v_mfma_f32_16x16x32_bf16 v[24:27], v[192:195], v[208:211], v[24:27]
	v_mfma_f32_16x16x32_bf16 v[16:19], v[184:187], v[216:219], v[16:19]
	v_mfma_f32_16x16x32_bf16 v[8:11], v[192:195], v[216:219], v[8:11]
	v_mfma_f32_16x16x32_bf16 v[4:7], v[184:187], v[224:227], v[4:7]
	v_mfma_f32_16x16x32_bf16 v[0:3], v[192:195], v[224:227], v[0:3]
	s_setprio 0
	s_barrier
	s_add_i32 s49, 0, 0x18000
	v_add_u32_e32 v157, s49, v151
	s_add_i32 s50, 0, 0x1c000
	ds_read_b128 v[146:149], v157
	ds_read_b128 v[158:161], v157 offset:1024
	ds_read_b128 v[162:165], v157 offset:2048
	ds_read_b128 v[166:169], v157 offset:3072
	v_add_u32_e32 v157, s50, v151
	ds_read_b128 v[180:183], v157
	ds_read_b128 v[184:187], v157 offset:1024
	ds_read_b128 v[188:191], v157 offset:2048
	ds_read_b128 v[192:195], v157 offset:3072
	s_add_u32 s24, s24, 0x80000
	s_addc_u32 s25, s25, 0
	s_mov_b32 m0, s30
	v_lshl_add_u64 v[234:235], s[24:25], 0, v[130:131]
	ds_read_b128 v[196:199], v156 offset:32768
	ds_read_b128 v[200:203], v156 offset:33792
	ds_read_b128 v[204:207], v156 offset:34816
	ds_read_b128 v[208:211], v156 offset:35840
	ds_read_b128 v[212:215], v156 offset:36864
	ds_read_b128 v[216:219], v156 offset:37888
	ds_read_b128 v[220:223], v156 offset:38912
	ds_read_b128 v[224:227], v156 offset:39936
	global_load_lds_dwordx4 v[234:235], off
	v_lshl_add_u64 v[234:235], s[24:25], 0, v[134:135]
	s_mov_b32 m0, s31
	s_nop 0
	global_load_lds_dwordx4 v[234:235], off
	s_waitcnt vmcnt(8)
	s_waitcnt lgkmcnt(0)
	s_barrier
	s_setprio 1
	s_waitcnt lgkmcnt(0)
	v_mfma_f32_16x16x32_bf16 v[124:127], v[146:149], v[196:199], v[124:127]
	v_mfma_f32_16x16x32_bf16 v[120:123], v[162:165], v[196:199], v[120:123]
	v_mfma_f32_16x16x32_bf16 v[112:115], v[146:149], v[204:207], v[112:115]
	v_mfma_f32_16x16x32_bf16 v[104:107], v[162:165], v[204:207], v[104:107]
	v_mfma_f32_16x16x32_bf16 v[96:99], v[146:149], v[212:215], v[96:99]
	v_mfma_f32_16x16x32_bf16 v[88:91], v[162:165], v[212:215], v[88:91]
	v_mfma_f32_16x16x32_bf16 v[80:83], v[146:149], v[220:223], v[80:83]
	v_mfma_f32_16x16x32_bf16 v[72:75], v[162:165], v[220:223], v[72:75]
	v_mfma_f32_16x16x32_bf16 v[124:127], v[158:161], v[200:203], v[124:127]
	v_mfma_f32_16x16x32_bf16 v[120:123], v[166:169], v[200:203], v[120:123]
	v_mfma_f32_16x16x32_bf16 v[112:115], v[158:161], v[208:211], v[112:115]
	v_mfma_f32_16x16x32_bf16 v[104:107], v[166:169], v[208:211], v[104:107]
	v_mfma_f32_16x16x32_bf16 v[96:99], v[158:161], v[216:219], v[96:99]
	v_mfma_f32_16x16x32_bf16 v[88:91], v[166:169], v[216:219], v[88:91]
	v_mfma_f32_16x16x32_bf16 v[80:83], v[158:161], v[224:227], v[80:83]
	v_mfma_f32_16x16x32_bf16 v[72:75], v[166:169], v[224:227], v[72:75]
	s_setprio 0
	s_setprio 1
	v_mfma_f32_16x16x32_bf16 v[116:119], v[180:183], v[196:199], v[116:119]
	v_mfma_f32_16x16x32_bf16 v[108:111], v[188:191], v[196:199], v[108:111]
	v_mfma_f32_16x16x32_bf16 v[100:103], v[180:183], v[204:207], v[100:103]
	v_mfma_f32_16x16x32_bf16 v[92:95], v[188:191], v[204:207], v[92:95]
	v_mfma_f32_16x16x32_bf16 v[84:87], v[180:183], v[212:215], v[84:87]
	v_mfma_f32_16x16x32_bf16 v[76:79], v[188:191], v[212:215], v[76:79]
	v_mfma_f32_16x16x32_bf16 v[68:71], v[180:183], v[220:223], v[68:71]
	v_mfma_f32_16x16x32_bf16 v[64:67], v[188:191], v[220:223], v[64:67]
	v_mfma_f32_16x16x32_bf16 v[116:119], v[184:187], v[200:203], v[116:119]
	v_mfma_f32_16x16x32_bf16 v[108:111], v[192:195], v[200:203], v[108:111]
	v_mfma_f32_16x16x32_bf16 v[100:103], v[184:187], v[208:211], v[100:103]
	v_mfma_f32_16x16x32_bf16 v[92:95], v[192:195], v[208:211], v[92:95]
	v_mfma_f32_16x16x32_bf16 v[84:87], v[184:187], v[216:219], v[84:87]
	v_mfma_f32_16x16x32_bf16 v[76:79], v[192:195], v[216:219], v[76:79]
	v_mfma_f32_16x16x32_bf16 v[68:71], v[184:187], v[224:227], v[68:71]
	v_mfma_f32_16x16x32_bf16 v[64:67], v[192:195], v[224:227], v[64:67]
	s_setprio 0
	s_barrier
; #define PG8_STAGE(bufoff, gbase, voff) do { _Pragma("unroll") for (int _i = 0; _i < 2; ++_i) \
;         __builtin_amdgcn_global_load_lds((const unsigned*)((const char*)(gbase) + (voff)[_i]), (PG8_LAS unsigned*)(lds + (bufoff) + ldsw + _i * 8192), 16, 0, 0); } while (0)
; #define PG8_LDA(dst, b, h) do { _Pragma("unroll") for (int m = 0; m < 4; ++m) _Pragma("unroll") for (int k = 0; k < 2; ++k) dst[m][k] = *(const PG8_LAS bf16x8*)(lds + PG8_SA(b, h) + aoff + m * 2048 + k * 1024); } while (0)
; #define PG8_MMA(ai, bj, At, Bt) do { __builtin_amdgcn_s_setprio(1); _Pragma("unroll") for (int m = 0; m < 4; ++m) _Pragma("unroll") for (int n = 0; n < 2; ++n) _Pragma("unroll") for (int k = 0; k < 2; ++k) \
;         acc[ai][bj][m][n] = __builtin_amdgcn_mfma_f32_16x16x32_bf16(Bt[n][k], At[m][k], acc[ai][bj][m][n], 0, 0, 0); __builtin_amdgcn_s_setprio(0); } while (0)
; #define PG8_WAIT_V(n) asm volatile("s_waitcnt vmcnt(" #n ")" ::: "memory")
; #define PG8_WAIT_L(n) asm volatile("s_waitcnt lgkmcnt(" #n ")" ::: "memory")
; #define PG8_BAR __builtin_amdgcn_s_barrier()
; #define PG8_SCHED __builtin_amdgcn_sched_barrier(0)
; template <class Epi, class Sched, bool ALIGN_EPI = false, bool SP2 = false>
; __device__ __forceinline__ void gemm_phase(PG8_LAS unsigned char* lds, const Gemm g, const Sched& S, const Epi& E) {
;     ...
;             PG8_LDA(At, 1, 1); PG8_STAGE(PG8_SB(1, 0), b3, voffB); PG8_STAGE(PG8_SB(1, 1), b3 + hstep, voffB); PG8_STAGE(PG8_SA(1, 0), a3, voffA);
;             PG8_WAIT_V(8); PG8_WAIT_L(0); PG8_BAR; PG8_MMA(1, 0, At, B0); PG8_MMA(1, 1, At, B1); PG8_BAR; PG8_SCHED;
;     ...
;         if constexpr (ALIGN_EPI) { if (wr == 0) PG8_BAR; }
	s_add_i32 s24, s49, s28
	v_lshl_add_u64 v[170:171], v[170:171], 0, s[2:3]
	s_mov_b32 m0, s24
	ds_read_b128 v[196:199], v156 offset:49152
	ds_read_b128 v[200:203], v156 offset:50176
	ds_read_b128 v[204:207], v156 offset:51200
	ds_read_b128 v[208:211], v156 offset:52224
	ds_read_b128 v[212:215], v156 offset:53248
	ds_read_b128 v[216:219], v156 offset:54272
	ds_read_b128 v[220:223], v156 offset:55296
	ds_read_b128 v[224:227], v156 offset:56320
	global_load_lds_dwordx4 v[170:171], off
	s_add_i32 m0, s24, 0x2000
	s_add_u32 s22, s22, 0x80080
	v_lshl_add_u64 v[170:171], v[228:229], 0, s[2:3]
	s_addc_u32 s23, s23, 0
	s_add_i32 s24, s50, s28
	global_load_lds_dwordx4 v[170:171], off
	v_lshl_add_u64 v[170:171], s[22:23], 0, v[132:133]
	s_mov_b32 m0, s24
	s_nop 0
	global_load_lds_dwordx4 v[170:171], off
	v_lshl_add_u64 v[170:171], s[22:23], 0, v[136:137]
	s_add_i32 m0, s24, 0x2000
	s_nop 0
	global_load_lds_dwordx4 v[170:171], off
	v_lshl_add_u64 v[170:171], v[230:231], 0, s[2:3]
	s_mov_b32 m0, s33
	s_nop 0
	global_load_lds_dwordx4 v[170:171], off
	v_lshl_add_u64 v[170:171], v[232:233], 0, s[2:3]
	s_mov_b32 m0, s34
	s_nop 0
	global_load_lds_dwordx4 v[170:171], off
	s_waitcnt vmcnt(8)
	s_waitcnt lgkmcnt(0)
	s_barrier
	s_setprio 1
	s_waitcnt lgkmcnt(0)
	v_mfma_f32_16x16x32_bf16 v[60:63], v[146:149], v[196:199], v[60:63]
	v_mfma_f32_16x16x32_bf16 v[56:59], v[162:165], v[196:199], v[56:59]
	v_mfma_f32_16x16x32_bf16 v[52:55], v[146:149], v[204:207], v[52:55]
	v_mfma_f32_16x16x32_bf16 v[44:47], v[162:165], v[204:207], v[44:47]
	v_mfma_f32_16x16x32_bf16 v[36:39], v[146:149], v[212:215], v[36:39]
	v_mfma_f32_16x16x32_bf16 v[28:31], v[162:165], v[212:215], v[28:31]
	v_mfma_f32_16x16x32_bf16 v[20:23], v[146:149], v[220:223], v[20:23]
	v_mfma_f32_16x16x32_bf16 v[12:15], v[162:165], v[220:223], v[12:15]
	v_mfma_f32_16x16x32_bf16 v[60:63], v[158:161], v[200:203], v[60:63]
	v_mfma_f32_16x16x32_bf16 v[56:59], v[166:169], v[200:203], v[56:59]
	v_mfma_f32_16x16x32_bf16 v[52:55], v[158:161], v[208:211], v[52:55]
	v_mfma_f32_16x16x32_bf16 v[44:47], v[166:169], v[208:211], v[44:47]
	v_mfma_f32_16x16x32_bf16 v[36:39], v[158:161], v[216:219], v[36:39]
	v_mfma_f32_16x16x32_bf16 v[28:31], v[166:169], v[216:219], v[28:31]
	v_mfma_f32_16x16x32_bf16 v[20:23], v[158:161], v[224:227], v[20:23]
	v_mfma_f32_16x16x32_bf16 v[12:15], v[166:169], v[224:227], v[12:15]
	s_setprio 0
	s_setprio 1
	v_mfma_f32_16x16x32_bf16 v[48:51], v[180:183], v[196:199], v[48:51]
	v_mfma_f32_16x16x32_bf16 v[40:43], v[188:191], v[196:199], v[40:43]
	v_mfma_f32_16x16x32_bf16 v[32:35], v[180:183], v[204:207], v[32:35]
	v_mfma_f32_16x16x32_bf16 v[24:27], v[188:191], v[204:207], v[24:27]
	v_mfma_f32_16x16x32_bf16 v[16:19], v[180:183], v[212:215], v[16:19]
	v_mfma_f32_16x16x32_bf16 v[8:11], v[188:191], v[212:215], v[8:11]
	v_mfma_f32_16x16x32_bf16 v[4:7], v[180:183], v[220:223], v[4:7]
	v_mfma_f32_16x16x32_bf16 v[0:3], v[188:191], v[220:223], v[0:3]
	v_mfma_f32_16x16x32_bf16 v[48:51], v[184:187], v[200:203], v[48:51]
	v_mfma_f32_16x16x32_bf16 v[40:43], v[192:195], v[200:203], v[40:43]
	v_mfma_f32_16x16x32_bf16 v[32:35], v[184:187], v[208:211], v[32:35]
	v_mfma_f32_16x16x32_bf16 v[24:27], v[192:195], v[208:211], v[24:27]
	v_mfma_f32_16x16x32_bf16 v[16:19], v[184:187], v[216:219], v[16:19]
	v_mfma_f32_16x16x32_bf16 v[8:11], v[192:195], v[216:219], v[8:11]
	v_mfma_f32_16x16x32_bf16 v[4:7], v[184:187], v[224:227], v[4:7]
	v_mfma_f32_16x16x32_bf16 v[0:3], v[192:195], v[224:227], v[0:3]
	s_setprio 0
	s_barrier
	s_add_i32 s48, s48, 2
	s_add_u32 s20, s20, 0x100
	s_addc_u32 s21, s21, 0
	s_add_u32 s46, s46, 0x100
	s_addc_u32 s47, s47, 0
	s_cmp_gt_u32 s48, 29
	s_cbranch_scc0 .LBB0_1181
	s_nop 0
	v_readfirstlane_b32 s7, v172
	s_nop 3
	s_lshr_b32 s7, s7, 6
	s_cmp_lt_u32 s7, 4
	s_cbranch_scc0 .Lprio_k4
	s_setprio 1

; #define PG8_STAGE(bufoff, gbase, voff) do { _Pragma("unroll") for (int _i = 0; _i < 2; ++_i) \
;         __builtin_amdgcn_global_load_lds((const unsigned*)((const char*)(gbase) + (voff)[_i]), (PG8_LAS unsigned*)(lds + (bufoff) + ldsw + _i * 8192), 16, 0, 0); } while (0)
; #define PG8_LDA(dst, b, h) do { _Pragma("unroll") for (int m = 0; m < 4; ++m) _Pragma("unroll") for (int k = 0; k < 2; ++k) dst[m][k] = *(const PG8_LAS bf16x8*)(lds + PG8_SA(b, h) + aoff + m * 2048 + k * 1024); } while (0)
; #define PG8_LDB(dst, b, h) do { _Pragma("unroll") for (int n = 0; n < 2; ++n) _Pragma("unroll") for (int k = 0; k < 2; ++k) dst[n][k] = *(const PG8_LAS bf16x8*)(lds + PG8_SB(b, h) + boff + n * 2048 + k * 1024); } while (0)
; #define PG8_MMA(ai, bj, At, Bt) do { __builtin_amdgcn_s_setprio(1); _Pragma("unroll") for (int m = 0; m < 4; ++m) _Pragma("unroll") for (int n = 0; n < 2; ++n) _Pragma("unroll") for (int k = 0; k < 2; ++k) \
;         acc[ai][bj][m][n] = __builtin_amdgcn_mfma_f32_16x16x32_bf16(Bt[n][k], At[m][k], acc[ai][bj][m][n], 0, 0, 0); __builtin_amdgcn_s_setprio(0); } while (0)
; #define PG8_WAIT_V(n) asm volatile("s_waitcnt vmcnt(" #n ")" ::: "memory")
; #define PG8_WAIT_L(n) asm volatile("s_waitcnt lgkmcnt(" #n ")" ::: "memory")
; template <class Epi, class Sched, bool ALIGN_EPI = false, bool SP2 = false>
; __device__ __forceinline__ void gemm_phase(PG8_LAS unsigned char* lds, const Gemm g, const Sched& S, const Epi& E) {
;     ...
;             const bool last = (t == nt - 2);
;             const char* a1 = cA + (size_t)(t + 1) * kstep;
;             const char* a2 = last ? nA : cA + (size_t)(t + 2) * kstep; const char* b2 = last ? nB : cB + (size_t)(t + 2) * kstep;
;             const char* a3 = a2 + kstep; const char* b3 = b2 + kstep;
;             if (last && has_next) S.a_ready(nxt);
;             if constexpr (SP2) {
;             PG8_LDB(B0, 0, 0); PG8_LDB(B1, 0, 1); PG8_SCHED; PG8_LDA(At, 0, 0); PG8_STAGE(PG8_SA(1, 1), a1 + hstep, voffA);
;             PG8_WAIT_V(8); PG8_WAIT_L(0); PG8_BAR; PG8_MMA(0, 0, At, B0); PG8_MMA(0, 1, At, B1); PG8_BAR; PG8_SCHED;
;             PG8_LDA(At, 0, 1); PG8_STAGE(PG8_SB(0, 0), b2, voffB); PG8_STAGE(PG8_SB(0, 1), b2 + hstep, voffB); PG8_STAGE(PG8_SA(0, 0), a2, voffA);
;             PG8_WAIT_V(8); PG8_WAIT_L(0); PG8_BAR; PG8_MMA(1, 0, At, B0); PG8_MMA(1, 1, At, B1); PG8_BAR; PG8_SCHED;
.LBB0_1457:
	ds_read_b128 v[142:145], v151
	ds_read_b128 v[154:157], v151 offset:1024
	ds_read_b128 v[158:161], v151 offset:2048
	ds_read_b128 v[162:165], v151 offset:3072
	ds_read_b128 v[166:169], v152
	ds_read_b128 v[178:181], v152 offset:1024
	ds_read_b128 v[182:185], v152 offset:2048
	ds_read_b128 v[186:189], v152 offset:3072
	s_add_u32 s24, s22, 0x100
	s_addc_u32 s25, s23, 0
	s_cmp_eq_u32 s47, 28
	s_cselect_b32 s29, s15, s25
	s_cselect_b32 s28, s21, s24
	s_cselect_b32 s27, s13, s46
	s_cselect_b32 s26, s44, s45
	v_lshl_add_u64 v[146:147], s[22:23], 0, v[134:135]
	s_add_i32 m0, s34, 0xc000
	ds_read_b128 v[190:193], v153
	ds_read_b128 v[194:197], v153 offset:1024
	ds_read_b128 v[198:201], v153 offset:2048
	ds_read_b128 v[202:205], v153 offset:3072
	ds_read_b128 v[206:209], v153 offset:4096
	ds_read_b128 v[210:213], v153 offset:5120
	ds_read_b128 v[214:217], v153 offset:6144
	ds_read_b128 v[218:221], v153 offset:7168
	global_load_lds_dwordx4 v[146:147], off
	v_lshl_add_u64 v[146:147], s[22:23], 0, v[136:137]
	s_add_i32 m0, s34, 0xe000
	s_nop 0
	global_load_lds_dwordx4 v[146:147], off
	s_waitcnt vmcnt(8)
	s_waitcnt lgkmcnt(0)
	s_barrier
	s_setprio 1
	s_waitcnt lgkmcnt(0)
	v_mfma_f32_16x16x32_bf16 v[124:127], v[142:145], v[190:193], v[124:127]
	v_mfma_f32_16x16x32_bf16 v[120:123], v[158:161], v[190:193], v[120:123]
	v_mfma_f32_16x16x32_bf16 v[108:111], v[142:145], v[198:201], v[108:111]
	v_mfma_f32_16x16x32_bf16 v[104:107], v[158:161], v[198:201], v[104:107]
	v_mfma_f32_16x16x32_bf16 v[92:95], v[142:145], v[206:209], v[92:95]
	v_mfma_f32_16x16x32_bf16 v[88:91], v[158:161], v[206:209], v[88:91]
	v_mfma_f32_16x16x32_bf16 v[76:79], v[142:145], v[214:217], v[76:79]
	v_mfma_f32_16x16x32_bf16 v[72:75], v[158:161], v[214:217], v[72:75]
	v_mfma_f32_16x16x32_bf16 v[124:127], v[154:157], v[194:197], v[124:127]
	v_mfma_f32_16x16x32_bf16 v[120:123], v[162:165], v[194:197], v[120:123]
	v_mfma_f32_16x16x32_bf16 v[108:111], v[154:157], v[202:205], v[108:111]
	v_mfma_f32_16x16x32_bf16 v[104:107], v[162:165], v[202:205], v[104:107]
	v_mfma_f32_16x16x32_bf16 v[92:95], v[154:157], v[210:213], v[92:95]
	v_mfma_f32_16x16x32_bf16 v[88:91], v[162:165], v[210:213], v[88:91]
	v_mfma_f32_16x16x32_bf16 v[76:79], v[154:157], v[218:221], v[76:79]
	v_mfma_f32_16x16x32_bf16 v[72:75], v[162:165], v[218:221], v[72:75]
	s_setprio 0
	s_setprio 1
	v_mfma_f32_16x16x32_bf16 v[116:119], v[166:169], v[190:193], v[116:119]
	v_mfma_f32_16x16x32_bf16 v[112:115], v[182:185], v[190:193], v[112:115]
	v_mfma_f32_16x16x32_bf16 v[100:103], v[166:169], v[198:201], v[100:103]
	v_mfma_f32_16x16x32_bf16 v[96:99], v[182:185], v[198:201], v[96:99]
	v_mfma_f32_16x16x32_bf16 v[84:87], v[166:169], v[206:209], v[84:87]
	v_mfma_f32_16x16x32_bf16 v[80:83], v[182:185], v[206:209], v[80:83]
	v_mfma_f32_16x16x32_bf16 v[68:71], v[166:169], v[214:217], v[68:71]
	v_mfma_f32_16x16x32_bf16 v[64:67], v[182:185], v[214:217], v[64:67]
	v_mfma_f32_16x16x32_bf16 v[116:119], v[178:181], v[194:197], v[116:119]
	v_mfma_f32_16x16x32_bf16 v[112:115], v[186:189], v[194:197], v[112:115]
	v_mfma_f32_16x16x32_bf16 v[100:103], v[178:181], v[202:205], v[100:103]
	v_mfma_f32_16x16x32_bf16 v[96:99], v[186:189], v[202:205], v[96:99]
	v_mfma_f32_16x16x32_bf16 v[84:87], v[178:181], v[210:213], v[84:87]
	v_mfma_f32_16x16x32_bf16 v[80:83], v[186:189], v[210:213], v[80:83]
	v_mfma_f32_16x16x32_bf16 v[68:71], v[178:181], v[218:221], v[68:71]
	v_mfma_f32_16x16x32_bf16 v[64:67], v[186:189], v[218:221], v[64:67]
	s_setprio 0
	s_barrier
	s_add_i32 s22, s41, s33
	v_lshl_add_u64 v[146:147], s[26:27], 0, v[130:131]
	s_mov_b32 m0, s22
	ds_read_b128 v[190:193], v153 offset:16384
	ds_read_b128 v[194:197], v153 offset:17408
	ds_read_b128 v[198:201], v153 offset:18432
	ds_read_b128 v[202:205], v153 offset:19456
	ds_read_b128 v[206:209], v153 offset:20480
	ds_read_b128 v[210:213], v153 offset:21504
	ds_read_b128 v[214:217], v153 offset:22528
	ds_read_b128 v[218:221], v153 offset:23552
	global_load_lds_dwordx4 v[146:147], off
	s_add_i32 m0, s22, 0x2000
	s_add_u32 s22, s26, 0x80000
	v_lshl_add_u64 v[170:171], s[26:27], 0, v[132:133]
	s_addc_u32 s23, s27, 0
	s_add_i32 s48, s42, s33
	global_load_lds_dwordx4 v[170:171], off
	v_lshl_add_u64 v[222:223], s[22:23], 0, v[130:131]
	s_mov_b32 m0, s48
	v_lshl_add_u64 v[224:225], s[28:29], 0, v[132:133]
	global_load_lds_dwordx4 v[222:223], off
	v_lshl_add_u64 v[222:223], s[22:23], 0, v[132:133]
	s_add_i32 m0, s48, 0x2000
	s_nop 0
	global_load_lds_dwordx4 v[222:223], off
	v_lshl_add_u64 v[222:223], s[28:29], 0, v[130:131]
	s_mov_b32 m0, s34
	s_nop 0
	global_load_lds_dwordx4 v[222:223], off
	s_mov_b32 m0, s35
	s_nop 0
	global_load_lds_dwordx4 v[224:225], off
	s_waitcnt vmcnt(8)
	s_waitcnt lgkmcnt(0)
	s_barrier
; #define PG8_STAGE(bufoff, gbase, voff) do { _Pragma("unroll") for (int _i = 0; _i < 2; ++_i) \
;         __builtin_amdgcn_global_load_lds((const unsigned*)((const char*)(gbase) + (voff)[_i]), (PG8_LAS unsigned*)(lds + (bufoff) + ldsw + _i * 8192), 16, 0, 0); } while (0)
; #define PG8_LDA(dst, b, h) do { _Pragma("unroll") for (int m = 0; m < 4; ++m) _Pragma("unroll") for (int k = 0; k < 2; ++k) dst[m][k] = *(const PG8_LAS bf16x8*)(lds + PG8_SA(b, h) + aoff + m * 2048 + k * 1024); } while (0)
; #define PG8_LDB(dst, b, h) do { _Pragma("unroll") for (int n = 0; n < 2; ++n) _Pragma("unroll") for (int k = 0; k < 2; ++k) dst[n][k] = *(const PG8_LAS bf16x8*)(lds + PG8_SB(b, h) + boff + n * 2048 + k * 1024); } while (0)
; #define PG8_MMA(ai, bj, At, Bt) do { __builtin_amdgcn_s_setprio(1); _Pragma("unroll") for (int m = 0; m < 4; ++m) _Pragma("unroll") for (int n = 0; n < 2; ++n) _Pragma("unroll") for (int k = 0; k < 2; ++k) \
;         acc[ai][bj][m][n] = __builtin_amdgcn_mfma_f32_16x16x32_bf16(Bt[n][k], At[m][k], acc[ai][bj][m][n], 0, 0, 0); __builtin_amdgcn_s_setprio(0); } while (0)
; #define PG8_WAIT_V(n) asm volatile("s_waitcnt vmcnt(" #n ")" ::: "memory")
; #define PG8_WAIT_L(n) asm volatile("s_waitcnt lgkmcnt(" #n ")" ::: "memory")
; #define PG8_BAR __builtin_amdgcn_s_barrier()
; #define PG8_SCHED __builtin_amdgcn_sched_barrier(0)
; template <class Epi, class Sched, bool ALIGN_EPI = false, bool SP2 = false>
; __device__ __forceinline__ void gemm_phase(PG8_LAS unsigned char* lds, const Gemm g, const Sched& S, const Epi& E) {
;     ...
;             PG8_WAIT_V(8); PG8_WAIT_L(0); PG8_BAR; PG8_MMA(1, 0, At, B0); PG8_MMA(1, 1, At, B1); PG8_BAR; PG8_SCHED;
;             PG8_LDB(B0, 1, 0); PG8_LDB(B1, 1, 1); PG8_SCHED; PG8_LDA(At, 1, 0); PG8_STAGE(PG8_SA(0, 1), a2 + hstep, voffA);
;             PG8_WAIT_V(8); PG8_WAIT_L(0); PG8_BAR; PG8_MMA(0, 0, At, B0); PG8_MMA(0, 1, At, B1); PG8_BAR; PG8_SCHED;
	s_setprio 1
	s_waitcnt lgkmcnt(0)
	v_mfma_f32_16x16x32_bf16 v[60:63], v[142:145], v[190:193], v[60:63]
	v_mfma_f32_16x16x32_bf16 v[56:59], v[158:161], v[190:193], v[56:59]
	v_mfma_f32_16x16x32_bf16 v[44:47], v[142:145], v[198:201], v[44:47]
	v_mfma_f32_16x16x32_bf16 v[40:43], v[158:161], v[198:201], v[40:43]
	v_mfma_f32_16x16x32_bf16 v[28:31], v[142:145], v[206:209], v[28:31]
	v_mfma_f32_16x16x32_bf16 v[24:27], v[158:161], v[206:209], v[24:27]
	v_mfma_f32_16x16x32_bf16 v[12:15], v[142:145], v[214:217], v[12:15]
	v_mfma_f32_16x16x32_bf16 v[8:11], v[158:161], v[214:217], v[8:11]
	v_mfma_f32_16x16x32_bf16 v[60:63], v[154:157], v[194:197], v[60:63]
	v_mfma_f32_16x16x32_bf16 v[56:59], v[162:165], v[194:197], v[56:59]
	v_mfma_f32_16x16x32_bf16 v[44:47], v[154:157], v[202:205], v[44:47]
	v_mfma_f32_16x16x32_bf16 v[40:43], v[162:165], v[202:205], v[40:43]
	v_mfma_f32_16x16x32_bf16 v[28:31], v[154:157], v[210:213], v[28:31]
	v_mfma_f32_16x16x32_bf16 v[24:27], v[162:165], v[210:213], v[24:27]
	v_mfma_f32_16x16x32_bf16 v[12:15], v[154:157], v[218:221], v[12:15]
	v_mfma_f32_16x16x32_bf16 v[8:11], v[162:165], v[218:221], v[8:11]
	s_setprio 0
	s_setprio 1
	v_mfma_f32_16x16x32_bf16 v[52:55], v[166:169], v[190:193], v[52:55]
	v_mfma_f32_16x16x32_bf16 v[48:51], v[182:185], v[190:193], v[48:51]
	v_mfma_f32_16x16x32_bf16 v[36:39], v[166:169], v[198:201], v[36:39]
	v_mfma_f32_16x16x32_bf16 v[32:35], v[182:185], v[198:201], v[32:35]
	v_mfma_f32_16x16x32_bf16 v[20:23], v[166:169], v[206:209], v[20:23]
	v_mfma_f32_16x16x32_bf16 v[16:19], v[182:185], v[206:209], v[16:19]
	v_mfma_f32_16x16x32_bf16 v[4:7], v[166:169], v[214:217], v[4:7]
	v_mfma_f32_16x16x32_bf16 v[0:3], v[182:185], v[214:217], v[0:3]
	v_mfma_f32_16x16x32_bf16 v[52:55], v[178:181], v[194:197], v[52:55]
	v_mfma_f32_16x16x32_bf16 v[48:51], v[186:189], v[194:197], v[48:51]
	v_mfma_f32_16x16x32_bf16 v[36:39], v[178:181], v[202:205], v[36:39]
	v_mfma_f32_16x16x32_bf16 v[32:35], v[186:189], v[202:205], v[32:35]
	v_mfma_f32_16x16x32_bf16 v[20:23], v[178:181], v[210:213], v[20:23]
	v_mfma_f32_16x16x32_bf16 v[16:19], v[186:189], v[210:213], v[16:19]
	v_mfma_f32_16x16x32_bf16 v[4:7], v[178:181], v[218:221], v[4:7]
	v_mfma_f32_16x16x32_bf16 v[0:3], v[186:189], v[218:221], v[0:3]
	s_setprio 0
	s_barrier
	s_add_i32 s48, 0, 0x18000
	s_add_i32 s49, 0, 0x1c000
	v_add_u32_e32 v162, s48, v149
	v_add_u32_e32 v186, s49, v149
	ds_read_b128 v[142:145], v162
	ds_read_b128 v[154:157], v162 offset:1024
	ds_read_b128 v[158:161], v162 offset:2048
	ds_read_b128 v[162:165], v162 offset:3072
	ds_read_b128 v[166:169], v186
	ds_read_b128 v[178:181], v186 offset:1024
	ds_read_b128 v[182:185], v186 offset:2048
	ds_read_b128 v[186:189], v186 offset:3072
	s_add_u32 s22, s28, 0x80000
	s_addc_u32 s23, s29, 0
	s_mov_b32 m0, s36
	v_lshl_add_u64 v[226:227], s[22:23], 0, v[130:131]
	ds_read_b128 v[190:193], v153 offset:32768
	ds_read_b128 v[194:197], v153 offset:33792
	ds_read_b128 v[198:201], v153 offset:34816
	ds_read_b128 v[202:205], v153 offset:35840
	ds_read_b128 v[206:209], v153 offset:36864
	ds_read_b128 v[210:213], v153 offset:37888
	ds_read_b128 v[214:217], v153 offset:38912
	ds_read_b128 v[218:221], v153 offset:39936
	global_load_lds_dwordx4 v[226:227], off
	v_lshl_add_u64 v[226:227], s[22:23], 0, v[132:133]
	s_mov_b32 m0, s37
	s_nop 0
	global_load_lds_dwordx4 v[226:227], off
	s_waitcnt vmcnt(8)
	s_waitcnt lgkmcnt(0)
	s_barrier
	s_setprio 1
	s_waitcnt lgkmcnt(0)
	v_mfma_f32_16x16x32_bf16 v[124:127], v[142:145], v[190:193], v[124:127]
	v_mfma_f32_16x16x32_bf16 v[120:123], v[158:161], v[190:193], v[120:123]
	v_mfma_f32_16x16x32_bf16 v[108:111], v[142:145], v[198:201], v[108:111]
	v_mfma_f32_16x16x32_bf16 v[104:107], v[158:161], v[198:201], v[104:107]
	v_mfma_f32_16x16x32_bf16 v[92:95], v[142:145], v[206:209], v[92:95]
	v_mfma_f32_16x16x32_bf16 v[88:91], v[158:161], v[206:209], v[88:91]
	v_mfma_f32_16x16x32_bf16 v[76:79], v[142:145], v[214:217], v[76:79]
	v_mfma_f32_16x16x32_bf16 v[72:75], v[158:161], v[214:217], v[72:75]
	v_mfma_f32_16x16x32_bf16 v[124:127], v[154:157], v[194:197], v[124:127]
	v_mfma_f32_16x16x32_bf16 v[120:123], v[162:165], v[194:197], v[120:123]
	v_mfma_f32_16x16x32_bf16 v[108:111], v[154:157], v[202:205], v[108:111]
	v_mfma_f32_16x16x32_bf16 v[104:107], v[162:165], v[202:205], v[104:107]
	v_mfma_f32_16x16x32_bf16 v[92:95], v[154:157], v[210:213], v[92:95]
	v_mfma_f32_16x16x32_bf16 v[88:91], v[162:165], v[210:213], v[88:91]
	v_mfma_f32_16x16x32_bf16 v[76:79], v[154:157], v[218:221], v[76:79]
	v_mfma_f32_16x16x32_bf16 v[72:75], v[162:165], v[218:221], v[72:75]
	s_setprio 0
	s_setprio 1
	v_mfma_f32_16x16x32_bf16 v[116:119], v[166:169], v[190:193], v[116:119]
	v_mfma_f32_16x16x32_bf16 v[112:115], v[182:185], v[190:193], v[112:115]
	v_mfma_f32_16x16x32_bf16 v[100:103], v[166:169], v[198:201], v[100:103]
	v_mfma_f32_16x16x32_bf16 v[96:99], v[182:185], v[198:201], v[96:99]
	v_mfma_f32_16x16x32_bf16 v[84:87], v[166:169], v[206:209], v[84:87]
	v_mfma_f32_16x16x32_bf16 v[80:83], v[182:185], v[206:209], v[80:83]
	v_mfma_f32_16x16x32_bf16 v[68:71], v[166:169], v[214:217], v[68:71]
	v_mfma_f32_16x16x32_bf16 v[64:67], v[182:185], v[214:217], v[64:67]
	v_mfma_f32_16x16x32_bf16 v[116:119], v[178:181], v[194:197], v[116:119]
	v_mfma_f32_16x16x32_bf16 v[112:115], v[186:189], v[194:197], v[112:115]
	v_mfma_f32_16x16x32_bf16 v[100:103], v[178:181], v[202:205], v[100:103]
	v_mfma_f32_16x16x32_bf16 v[96:99], v[186:189], v[202:205], v[96:99]
	v_mfma_f32_16x16x32_bf16 v[84:87], v[178:181], v[210:213], v[84:87]
	v_mfma_f32_16x16x32_bf16 v[80:83], v[186:189], v[210:213], v[80:83]
	v_mfma_f32_16x16x32_bf16 v[68:71], v[178:181], v[218:221], v[68:71]
	v_mfma_f32_16x16x32_bf16 v[64:67], v[186:189], v[218:221], v[64:67]
	s_setprio 0
	s_barrier
; #define PG8_STAGE(bufoff, gbase, voff) do { _Pragma("unroll") for (int _i = 0; _i < 2; ++_i) \
;         __builtin_amdgcn_global_load_lds((const unsigned*)((const char*)(gbase) + (voff)[_i]), (PG8_LAS unsigned*)(lds + (bufoff) + ldsw + _i * 8192), 16, 0, 0); } while (0)
; #define PG8_LDA(dst, b, h) do { _Pragma("unroll") for (int m = 0; m < 4; ++m) _Pragma("unroll") for (int k = 0; k < 2; ++k) dst[m][k] = *(const PG8_LAS bf16x8*)(lds + PG8_SA(b, h) + aoff + m * 2048 + k * 1024); } while (0)
; #define PG8_MMA(ai, bj, At, Bt) do { __builtin_amdgcn_s_setprio(1); _Pragma("unroll") for (int m = 0; m < 4; ++m) _Pragma("unroll") for (int n = 0; n < 2; ++n) _Pragma("unroll") for (int k = 0; k < 2; ++k) \
;         acc[ai][bj][m][n] = __builtin_amdgcn_mfma_f32_16x16x32_bf16(Bt[n][k], At[m][k], acc[ai][bj][m][n], 0, 0, 0); __builtin_amdgcn_s_setprio(0); } while (0)
; #define PG8_WAIT_V(n) asm volatile("s_waitcnt vmcnt(" #n ")" ::: "memory")
; #define PG8_WAIT_L(n) asm volatile("s_waitcnt lgkmcnt(" #n ")" ::: "memory")
; #define PG8_BAR __builtin_amdgcn_s_barrier()
; #define PG8_SCHED __builtin_amdgcn_sched_barrier(0)
; template <class Epi, class Sched, bool ALIGN_EPI = false, bool SP2 = false>
; __device__ __forceinline__ void gemm_phase(PG8_LAS unsigned char* lds, const Gemm g, const Sched& S, const Epi& E) {
;     ...
;             PG8_LDA(At, 1, 1); PG8_STAGE(PG8_SB(1, 0), b3, voffB); PG8_STAGE(PG8_SB(1, 1), b3 + hstep, voffB); PG8_STAGE(PG8_SA(1, 0), a3, voffA);
;             PG8_WAIT_V(8); PG8_WAIT_L(0); PG8_BAR; PG8_MMA(1, 0, At, B0); PG8_MMA(1, 1, At, B1); PG8_BAR; PG8_SCHED;
;     ...
;         if constexpr (ALIGN_EPI) { if (wr == 0) PG8_BAR; }
	s_add_i32 s22, s48, s33
	v_lshl_add_u64 v[146:147], v[146:147], 0, s[4:5]
	s_mov_b32 m0, s22
	ds_read_b128 v[190:193], v153 offset:49152
	ds_read_b128 v[194:197], v153 offset:50176
	ds_read_b128 v[198:201], v153 offset:51200
	ds_read_b128 v[202:205], v153 offset:52224
	ds_read_b128 v[206:209], v153 offset:53248
	ds_read_b128 v[210:213], v153 offset:54272
	ds_read_b128 v[214:217], v153 offset:55296
	ds_read_b128 v[218:221], v153 offset:56320
	global_load_lds_dwordx4 v[146:147], off
	s_add_i32 m0, s22, 0x2000
	s_add_u32 s22, s26, 0x80080
	v_lshl_add_u64 v[146:147], v[170:171], 0, s[4:5]
	s_addc_u32 s23, s27, 0
	s_add_i32 s26, s49, s33
	global_load_lds_dwordx4 v[146:147], off
	v_lshl_add_u64 v[146:147], s[22:23], 0, v[130:131]
	s_mov_b32 m0, s26
	s_nop 0
	global_load_lds_dwordx4 v[146:147], off
	v_lshl_add_u64 v[146:147], s[22:23], 0, v[132:133]
	s_add_i32 m0, s26, 0x2000
	s_nop 0
	global_load_lds_dwordx4 v[146:147], off
	v_lshl_add_u64 v[146:147], v[222:223], 0, s[4:5]
	s_mov_b32 m0, s39
	s_nop 0
	global_load_lds_dwordx4 v[146:147], off
	v_lshl_add_u64 v[146:147], v[224:225], 0, s[4:5]
	s_mov_b32 m0, s40
	s_nop 0
	global_load_lds_dwordx4 v[146:147], off
	s_waitcnt vmcnt(8)
	s_waitcnt lgkmcnt(0)
	s_barrier
	s_setprio 1
	s_waitcnt lgkmcnt(0)
	v_mfma_f32_16x16x32_bf16 v[60:63], v[142:145], v[190:193], v[60:63]
	v_mfma_f32_16x16x32_bf16 v[56:59], v[158:161], v[190:193], v[56:59]
	v_mfma_f32_16x16x32_bf16 v[44:47], v[142:145], v[198:201], v[44:47]
	v_mfma_f32_16x16x32_bf16 v[40:43], v[158:161], v[198:201], v[40:43]
	v_mfma_f32_16x16x32_bf16 v[28:31], v[142:145], v[206:209], v[28:31]
	v_mfma_f32_16x16x32_bf16 v[24:27], v[158:161], v[206:209], v[24:27]
	v_mfma_f32_16x16x32_bf16 v[12:15], v[142:145], v[214:217], v[12:15]
	v_mfma_f32_16x16x32_bf16 v[8:11], v[158:161], v[214:217], v[8:11]
	v_mfma_f32_16x16x32_bf16 v[60:63], v[154:157], v[194:197], v[60:63]
	v_mfma_f32_16x16x32_bf16 v[56:59], v[162:165], v[194:197], v[56:59]
	v_mfma_f32_16x16x32_bf16 v[44:47], v[154:157], v[202:205], v[44:47]
	v_mfma_f32_16x16x32_bf16 v[40:43], v[162:165], v[202:205], v[40:43]
	v_mfma_f32_16x16x32_bf16 v[28:31], v[154:157], v[210:213], v[28:31]
	v_mfma_f32_16x16x32_bf16 v[24:27], v[162:165], v[210:213], v[24:27]
	v_mfma_f32_16x16x32_bf16 v[12:15], v[154:157], v[218:221], v[12:15]
	v_mfma_f32_16x16x32_bf16 v[8:11], v[162:165], v[218:221], v[8:11]
	s_setprio 0
	s_setprio 1
	v_mfma_f32_16x16x32_bf16 v[52:55], v[166:169], v[190:193], v[52:55]
	v_mfma_f32_16x16x32_bf16 v[48:51], v[182:185], v[190:193], v[48:51]
	v_mfma_f32_16x16x32_bf16 v[36:39], v[166:169], v[198:201], v[36:39]
	v_mfma_f32_16x16x32_bf16 v[32:35], v[182:185], v[198:201], v[32:35]
	v_mfma_f32_16x16x32_bf16 v[20:23], v[166:169], v[206:209], v[20:23]
	v_mfma_f32_16x16x32_bf16 v[16:19], v[182:185], v[206:209], v[16:19]
	v_mfma_f32_16x16x32_bf16 v[4:7], v[166:169], v[214:217], v[4:7]
	v_mfma_f32_16x16x32_bf16 v[0:3], v[182:185], v[214:217], v[0:3]
	v_mfma_f32_16x16x32_bf16 v[52:55], v[178:181], v[194:197], v[52:55]
	v_mfma_f32_16x16x32_bf16 v[48:51], v[186:189], v[194:197], v[48:51]
	v_mfma_f32_16x16x32_bf16 v[36:39], v[178:181], v[202:205], v[36:39]
	v_mfma_f32_16x16x32_bf16 v[32:35], v[186:189], v[202:205], v[32:35]
	v_mfma_f32_16x16x32_bf16 v[20:23], v[178:181], v[210:213], v[20:23]
	v_mfma_f32_16x16x32_bf16 v[16:19], v[186:189], v[210:213], v[16:19]
	v_mfma_f32_16x16x32_bf16 v[4:7], v[178:181], v[218:221], v[4:7]
	v_mfma_f32_16x16x32_bf16 v[0:3], v[186:189], v[218:221], v[0:3]
	s_setprio 0
	s_barrier
	s_add_i32 s47, s47, 2
	s_add_u32 s45, s45, 0x100
	s_addc_u32 s46, s46, 0
	s_cmp_gt_u32 s47, 29
	s_mov_b64 s[22:23], s[24:25]
	s_cbranch_scc0 .LBB0_1457
	s_nop 0
	v_readfirstlane_b32 s21, v172
	s_nop 3
	s_lshr_b32 s21, s21, 6
	s_cmp_lt_u32 s21, 4
	s_cbranch_scc0 .Lprio_k5
	s_setprio 1

; #define PG8_STAGE(bufoff, gbase, voff) do { _Pragma("unroll") for (int _i = 0; _i < 2; ++_i) \
;         __builtin_amdgcn_global_load_lds((const unsigned*)((const char*)(gbase) + (voff)[_i]), (PG8_LAS unsigned*)(lds + (bufoff) + ldsw + _i * 8192), 16, 0, 0); } while (0)
; #define PG8_LDA(dst, b, h) do { _Pragma("unroll") for (int m = 0; m < 4; ++m) _Pragma("unroll") for (int k = 0; k < 2; ++k) dst[m][k] = *(const PG8_LAS bf16x8*)(lds + PG8_SA(b, h) + aoff + m * 2048 + k * 1024); } while (0)
; #define PG8_LDB(dst, b, h) do { _Pragma("unroll") for (int n = 0; n < 2; ++n) _Pragma("unroll") for (int k = 0; k < 2; ++k) dst[n][k] = *(const PG8_LAS bf16x8*)(lds + PG8_SB(b, h) + boff + n * 2048 + k * 1024); } while (0)
; #define PG8_MMA(ai, bj, At, Bt) do { __builtin_amdgcn_s_setprio(1); _Pragma("unroll") for (int m = 0; m < 4; ++m) _Pragma("unroll") for (int n = 0; n < 2; ++n) _Pragma("unroll") for (int k = 0; k < 2; ++k) \
;         acc[ai][bj][m][n] = __builtin_amdgcn_mfma_f32_16x16x32_bf16(Bt[n][k], At[m][k], acc[ai][bj][m][n], 0, 0, 0); __builtin_amdgcn_s_setprio(0); } while (0)
; #define PG8_WAIT_V(n) asm volatile("s_waitcnt vmcnt(" #n ")" ::: "memory")
; #define PG8_WAIT_L(n) asm volatile("s_waitcnt lgkmcnt(" #n ")" ::: "memory")
; template <class Epi, class Sched, bool ALIGN_EPI = false, bool SP2 = false>
; __device__ __forceinline__ void gemm_phase(PG8_LAS unsigned char* lds, const Gemm g, const Sched& S, const Epi& E) {
;     ...
;             const bool last = (t == nt - 2);
;             const char* a1 = cA + (size_t)(t + 1) * kstep;
;             const char* a2 = last ? nA : cA + (size_t)(t + 2) * kstep; const char* b2 = last ? nB : cB + (size_t)(t + 2) * kstep;
;             const char* a3 = a2 + kstep; const char* b3 = b2 + kstep;
;             if (last && has_next) S.a_ready(nxt);
;             if constexpr (SP2) {
;             PG8_LDB(B0, 0, 0); PG8_LDB(B1, 0, 1); PG8_SCHED; PG8_LDA(At, 0, 0); PG8_STAGE(PG8_SA(1, 1), a1 + hstep, voffA);
;             PG8_WAIT_V(8); PG8_WAIT_L(0); PG8_BAR; PG8_MMA(0, 0, At, B0); PG8_MMA(0, 1, At, B1); PG8_BAR; PG8_SCHED;
;             PG8_LDA(At, 0, 1); PG8_STAGE(PG8_SB(0, 0), b2, voffB); PG8_STAGE(PG8_SB(0, 1), b2 + hstep, voffB); PG8_STAGE(PG8_SA(0, 0), a2, voffA);
;             PG8_WAIT_V(8); PG8_WAIT_L(0); PG8_BAR; PG8_MMA(1, 0, At, B0); PG8_MMA(1, 1, At, B1); PG8_BAR; PG8_SCHED;
.LBB0_1712:
	ds_read_b128 v[144:147], v156
	ds_read_b128 v[148:151], v156 offset:1024
	ds_read_b128 v[160:163], v156 offset:2048
	ds_read_b128 v[164:167], v156 offset:3072
	ds_read_b128 v[168:171], v157
	ds_read_b128 v[174:177], v157 offset:1024
	ds_read_b128 v[178:181], v157 offset:2048
	ds_read_b128 v[182:185], v157 offset:3072
	s_add_u32 s20, s18, 0xfff80080
	s_addc_u32 s21, s19, -1
	s_cmp_eq_u32 s44, 28
	s_cselect_b32 s23, s11, s21
	s_cselect_b32 s22, s40, s20
	s_cselect_b32 s21, s9, s43
	s_cselect_b32 s20, s41, s42
	v_lshl_add_u64 v[218:219], s[18:19], 0, v[136:137]
	s_add_i32 m0, s17, 0xc000
	ds_read_b128 v[186:189], v158
	ds_read_b128 v[190:193], v158 offset:1024
	ds_read_b128 v[194:197], v158 offset:2048
	ds_read_b128 v[198:201], v158 offset:3072
	ds_read_b128 v[202:205], v158 offset:4096
	ds_read_b128 v[206:209], v158 offset:5120
	ds_read_b128 v[210:213], v158 offset:6144
	ds_read_b128 v[214:217], v158 offset:7168
	global_load_lds_dwordx4 v[218:219], off
	v_lshl_add_u64 v[218:219], s[18:19], 0, v[138:139]
	s_add_i32 m0, s17, 0xe000
	s_nop 0
	global_load_lds_dwordx4 v[218:219], off
	s_waitcnt vmcnt(8)
	s_waitcnt lgkmcnt(0)
	s_barrier
	s_setprio 1
	s_waitcnt lgkmcnt(0)
	v_mfma_f32_16x16x32_bf16 v[124:127], v[144:147], v[186:189], v[124:127]
	v_mfma_f32_16x16x32_bf16 v[120:123], v[160:163], v[186:189], v[120:123]
	v_mfma_f32_16x16x32_bf16 v[108:111], v[144:147], v[194:197], v[108:111]
	v_mfma_f32_16x16x32_bf16 v[104:107], v[160:163], v[194:197], v[104:107]
	v_mfma_f32_16x16x32_bf16 v[92:95], v[144:147], v[202:205], v[92:95]
	v_mfma_f32_16x16x32_bf16 v[88:91], v[160:163], v[202:205], v[88:91]
	v_mfma_f32_16x16x32_bf16 v[76:79], v[144:147], v[210:213], v[76:79]
	v_mfma_f32_16x16x32_bf16 v[72:75], v[160:163], v[210:213], v[72:75]
	v_mfma_f32_16x16x32_bf16 v[124:127], v[148:151], v[190:193], v[124:127]
	v_mfma_f32_16x16x32_bf16 v[120:123], v[164:167], v[190:193], v[120:123]
	v_mfma_f32_16x16x32_bf16 v[108:111], v[148:151], v[198:201], v[108:111]
	v_mfma_f32_16x16x32_bf16 v[104:107], v[164:167], v[198:201], v[104:107]
	v_mfma_f32_16x16x32_bf16 v[92:95], v[148:151], v[206:209], v[92:95]
	v_mfma_f32_16x16x32_bf16 v[88:91], v[164:167], v[206:209], v[88:91]
	v_mfma_f32_16x16x32_bf16 v[76:79], v[148:151], v[214:217], v[76:79]
	v_mfma_f32_16x16x32_bf16 v[72:75], v[164:167], v[214:217], v[72:75]
	s_setprio 0
	s_setprio 1
	v_mfma_f32_16x16x32_bf16 v[116:119], v[168:171], v[186:189], v[116:119]
	v_mfma_f32_16x16x32_bf16 v[112:115], v[178:181], v[186:189], v[112:115]
	v_mfma_f32_16x16x32_bf16 v[100:103], v[168:171], v[194:197], v[100:103]
	v_mfma_f32_16x16x32_bf16 v[96:99], v[178:181], v[194:197], v[96:99]
	v_mfma_f32_16x16x32_bf16 v[84:87], v[168:171], v[202:205], v[84:87]
	v_mfma_f32_16x16x32_bf16 v[80:83], v[178:181], v[202:205], v[80:83]
	v_mfma_f32_16x16x32_bf16 v[68:71], v[168:171], v[210:213], v[68:71]
	v_mfma_f32_16x16x32_bf16 v[64:67], v[178:181], v[210:213], v[64:67]
	v_mfma_f32_16x16x32_bf16 v[116:119], v[174:177], v[190:193], v[116:119]
	v_mfma_f32_16x16x32_bf16 v[112:115], v[182:185], v[190:193], v[112:115]
	v_mfma_f32_16x16x32_bf16 v[100:103], v[174:177], v[198:201], v[100:103]
	v_mfma_f32_16x16x32_bf16 v[96:99], v[182:185], v[198:201], v[96:99]
	v_mfma_f32_16x16x32_bf16 v[84:87], v[174:177], v[206:209], v[84:87]
	v_mfma_f32_16x16x32_bf16 v[80:83], v[182:185], v[206:209], v[80:83]
	v_mfma_f32_16x16x32_bf16 v[68:71], v[174:177], v[214:217], v[68:71]
	v_mfma_f32_16x16x32_bf16 v[64:67], v[182:185], v[214:217], v[64:67]
	s_setprio 0
	s_barrier
	s_add_i32 s45, s34, s26
	v_lshl_add_u64 v[218:219], s[20:21], 0, v[132:133]
	s_mov_b32 m0, s45
	ds_read_b128 v[186:189], v158 offset:16384
	ds_read_b128 v[190:193], v158 offset:17408
	ds_read_b128 v[194:197], v158 offset:18432
	ds_read_b128 v[198:201], v158 offset:19456
	ds_read_b128 v[202:205], v158 offset:20480
	ds_read_b128 v[206:209], v158 offset:21504
	ds_read_b128 v[210:213], v158 offset:22528
	ds_read_b128 v[214:217], v158 offset:23552
	global_load_lds_dwordx4 v[218:219], off
	s_add_i32 m0, s45, 0x2000
	s_add_u32 s46, s20, 0x80000
	v_lshl_add_u64 v[220:221], s[20:21], 0, v[128:129]
	s_addc_u32 s47, s21, 0
	s_add_i32 s45, s35, s26
	global_load_lds_dwordx4 v[220:221], off
	v_lshl_add_u64 v[222:223], s[46:47], 0, v[132:133]
	s_mov_b32 m0, s45
	v_lshl_add_u64 v[224:225], s[22:23], 0, v[130:131]
	global_load_lds_dwordx4 v[222:223], off
	v_lshl_add_u64 v[222:223], s[46:47], 0, v[128:129]
	s_add_i32 m0, s45, 0x2000
	s_nop 0
	global_load_lds_dwordx4 v[222:223], off
	v_lshl_add_u64 v[222:223], s[22:23], 0, v[134:135]
	s_mov_b32 m0, s17
	s_nop 0
	global_load_lds_dwordx4 v[222:223], off
	s_mov_b32 m0, s28
	s_nop 0
	global_load_lds_dwordx4 v[224:225], off
	s_waitcnt vmcnt(8)
	s_waitcnt lgkmcnt(0)
	s_barrier
; #define PG8_STAGE(bufoff, gbase, voff) do { _Pragma("unroll") for (int _i = 0; _i < 2; ++_i) \
;         __builtin_amdgcn_global_load_lds((const unsigned*)((const char*)(gbase) + (voff)[_i]), (PG8_LAS unsigned*)(lds + (bufoff) + ldsw + _i * 8192), 16, 0, 0); } while (0)
; #define PG8_LDA(dst, b, h) do { _Pragma("unroll") for (int m = 0; m < 4; ++m) _Pragma("unroll") for (int k = 0; k < 2; ++k) dst[m][k] = *(const PG8_LAS bf16x8*)(lds + PG8_SA(b, h) + aoff + m * 2048 + k * 1024); } while (0)
; #define PG8_LDB(dst, b, h) do { _Pragma("unroll") for (int n = 0; n < 2; ++n) _Pragma("unroll") for (int k = 0; k < 2; ++k) dst[n][k] = *(const PG8_LAS bf16x8*)(lds + PG8_SB(b, h) + boff + n * 2048 + k * 1024); } while (0)
; #define PG8_MMA(ai, bj, At, Bt) do { __builtin_amdgcn_s_setprio(1); _Pragma("unroll") for (int m = 0; m < 4; ++m) _Pragma("unroll") for (int n = 0; n < 2; ++n) _Pragma("unroll") for (int k = 0; k < 2; ++k) \
;         acc[ai][bj][m][n] = __builtin_amdgcn_mfma_f32_16x16x32_bf16(Bt[n][k], At[m][k], acc[ai][bj][m][n], 0, 0, 0); __builtin_amdgcn_s_setprio(0); } while (0)
; #define PG8_WAIT_V(n) asm volatile("s_waitcnt vmcnt(" #n ")" ::: "memory")
; #define PG8_WAIT_L(n) asm volatile("s_waitcnt lgkmcnt(" #n ")" ::: "memory")
; #define PG8_BAR __builtin_amdgcn_s_barrier()
; #define PG8_SCHED __builtin_amdgcn_sched_barrier(0)
; template <class Epi, class Sched, bool ALIGN_EPI = false, bool SP2 = false>
; __device__ __forceinline__ void gemm_phase(PG8_LAS unsigned char* lds, const Gemm g, const Sched& S, const Epi& E) {
;     ...
;             PG8_WAIT_V(8); PG8_WAIT_L(0); PG8_BAR; PG8_MMA(1, 0, At, B0); PG8_MMA(1, 1, At, B1); PG8_BAR; PG8_SCHED;
;             PG8_LDB(B0, 1, 0); PG8_LDB(B1, 1, 1); PG8_SCHED; PG8_LDA(At, 1, 0); PG8_STAGE(PG8_SA(0, 1), a2 + hstep, voffA);
;             PG8_WAIT_V(8); PG8_WAIT_L(0); PG8_BAR; PG8_MMA(0, 0, At, B0); PG8_MMA(0, 1, At, B1); PG8_BAR; PG8_SCHED;
	s_setprio 1
	s_waitcnt lgkmcnt(0)
	v_mfma_f32_16x16x32_bf16 v[60:63], v[144:147], v[186:189], v[60:63]
	v_mfma_f32_16x16x32_bf16 v[56:59], v[160:163], v[186:189], v[56:59]
	v_mfma_f32_16x16x32_bf16 v[44:47], v[144:147], v[194:197], v[44:47]
	v_mfma_f32_16x16x32_bf16 v[40:43], v[160:163], v[194:197], v[40:43]
	v_mfma_f32_16x16x32_bf16 v[28:31], v[144:147], v[202:205], v[28:31]
	v_mfma_f32_16x16x32_bf16 v[24:27], v[160:163], v[202:205], v[24:27]
	v_mfma_f32_16x16x32_bf16 v[12:15], v[144:147], v[210:213], v[12:15]
	v_mfma_f32_16x16x32_bf16 v[8:11], v[160:163], v[210:213], v[8:11]
	v_mfma_f32_16x16x32_bf16 v[60:63], v[148:151], v[190:193], v[60:63]
	v_mfma_f32_16x16x32_bf16 v[56:59], v[164:167], v[190:193], v[56:59]
	v_mfma_f32_16x16x32_bf16 v[44:47], v[148:151], v[198:201], v[44:47]
	v_mfma_f32_16x16x32_bf16 v[40:43], v[164:167], v[198:201], v[40:43]
	v_mfma_f32_16x16x32_bf16 v[28:31], v[148:151], v[206:209], v[28:31]
	v_mfma_f32_16x16x32_bf16 v[24:27], v[164:167], v[206:209], v[24:27]
	v_mfma_f32_16x16x32_bf16 v[12:15], v[148:151], v[214:217], v[12:15]
	v_mfma_f32_16x16x32_bf16 v[8:11], v[164:167], v[214:217], v[8:11]
	s_setprio 0
	s_setprio 1
	v_mfma_f32_16x16x32_bf16 v[52:55], v[168:171], v[186:189], v[52:55]
	v_mfma_f32_16x16x32_bf16 v[48:51], v[178:181], v[186:189], v[48:51]
	v_mfma_f32_16x16x32_bf16 v[36:39], v[168:171], v[194:197], v[36:39]
	v_mfma_f32_16x16x32_bf16 v[32:35], v[178:181], v[194:197], v[32:35]
	v_mfma_f32_16x16x32_bf16 v[20:23], v[168:171], v[202:205], v[20:23]
	v_mfma_f32_16x16x32_bf16 v[16:19], v[178:181], v[202:205], v[16:19]
	v_mfma_f32_16x16x32_bf16 v[4:7], v[168:171], v[210:213], v[4:7]
	v_mfma_f32_16x16x32_bf16 v[0:3], v[178:181], v[210:213], v[0:3]
	v_mfma_f32_16x16x32_bf16 v[52:55], v[174:177], v[190:193], v[52:55]
	v_mfma_f32_16x16x32_bf16 v[48:51], v[182:185], v[190:193], v[48:51]
	v_mfma_f32_16x16x32_bf16 v[36:39], v[174:177], v[198:201], v[36:39]
	v_mfma_f32_16x16x32_bf16 v[32:35], v[182:185], v[198:201], v[32:35]
	v_mfma_f32_16x16x32_bf16 v[20:23], v[174:177], v[206:209], v[20:23]
	v_mfma_f32_16x16x32_bf16 v[16:19], v[182:185], v[206:209], v[16:19]
	v_mfma_f32_16x16x32_bf16 v[4:7], v[174:177], v[214:217], v[4:7]
	v_mfma_f32_16x16x32_bf16 v[0:3], v[182:185], v[214:217], v[0:3]
	s_setprio 0
	s_barrier
	s_add_i32 s45, 0, 0x18000
	v_add_u32_e32 v159, s45, v153
	s_add_i32 s46, 0, 0x1c000
	ds_read_b128 v[144:147], v159
	ds_read_b128 v[148:151], v159 offset:1024
	ds_read_b128 v[160:163], v159 offset:2048
	ds_read_b128 v[164:167], v159 offset:3072
	v_add_u32_e32 v159, s46, v153
	ds_read_b128 v[168:171], v159
	ds_read_b128 v[174:177], v159 offset:1024
	ds_read_b128 v[178:181], v159 offset:2048
	ds_read_b128 v[182:185], v159 offset:3072
	s_add_u32 s22, s22, 0x80000
	s_addc_u32 s23, s23, 0
	s_mov_b32 m0, s29
	v_lshl_add_u64 v[226:227], s[22:23], 0, v[134:135]
	ds_read_b128 v[186:189], v158 offset:32768
	ds_read_b128 v[190:193], v158 offset:33792
	ds_read_b128 v[194:197], v158 offset:34816
	ds_read_b128 v[198:201], v158 offset:35840
	ds_read_b128 v[202:205], v158 offset:36864
	ds_read_b128 v[206:209], v158 offset:37888
	ds_read_b128 v[210:213], v158 offset:38912
	ds_read_b128 v[214:217], v158 offset:39936
	global_load_lds_dwordx4 v[226:227], off
	v_lshl_add_u64 v[226:227], s[22:23], 0, v[130:131]
	s_mov_b32 m0, s30
	s_nop 0
	global_load_lds_dwordx4 v[226:227], off
	s_waitcnt vmcnt(8)
	s_waitcnt lgkmcnt(0)
	s_barrier
	s_setprio 1
	s_waitcnt lgkmcnt(0)
	v_mfma_f32_16x16x32_bf16 v[124:127], v[144:147], v[186:189], v[124:127]
	v_mfma_f32_16x16x32_bf16 v[120:123], v[160:163], v[186:189], v[120:123]
	v_mfma_f32_16x16x32_bf16 v[108:111], v[144:147], v[194:197], v[108:111]
	v_mfma_f32_16x16x32_bf16 v[104:107], v[160:163], v[194:197], v[104:107]
	v_mfma_f32_16x16x32_bf16 v[92:95], v[144:147], v[202:205], v[92:95]
	v_mfma_f32_16x16x32_bf16 v[88:91], v[160:163], v[202:205], v[88:91]
	v_mfma_f32_16x16x32_bf16 v[76:79], v[144:147], v[210:213], v[76:79]
	v_mfma_f32_16x16x32_bf16 v[72:75], v[160:163], v[210:213], v[72:75]
	v_mfma_f32_16x16x32_bf16 v[124:127], v[148:151], v[190:193], v[124:127]
	v_mfma_f32_16x16x32_bf16 v[120:123], v[164:167], v[190:193], v[120:123]
	v_mfma_f32_16x16x32_bf16 v[108:111], v[148:151], v[198:201], v[108:111]
	v_mfma_f32_16x16x32_bf16 v[104:107], v[164:167], v[198:201], v[104:107]
	v_mfma_f32_16x16x32_bf16 v[92:95], v[148:151], v[206:209], v[92:95]
	v_mfma_f32_16x16x32_bf16 v[88:91], v[164:167], v[206:209], v[88:91]
	v_mfma_f32_16x16x32_bf16 v[76:79], v[148:151], v[214:217], v[76:79]
	v_mfma_f32_16x16x32_bf16 v[72:75], v[164:167], v[214:217], v[72:75]
	s_setprio 0
	s_setprio 1
	v_mfma_f32_16x16x32_bf16 v[116:119], v[168:171], v[186:189], v[116:119]
	v_mfma_f32_16x16x32_bf16 v[112:115], v[178:181], v[186:189], v[112:115]
	v_mfma_f32_16x16x32_bf16 v[100:103], v[168:171], v[194:197], v[100:103]
	v_mfma_f32_16x16x32_bf16 v[96:99], v[178:181], v[194:197], v[96:99]
	v_mfma_f32_16x16x32_bf16 v[84:87], v[168:171], v[202:205], v[84:87]
	v_mfma_f32_16x16x32_bf16 v[80:83], v[178:181], v[202:205], v[80:83]
	v_mfma_f32_16x16x32_bf16 v[68:71], v[168:171], v[210:213], v[68:71]
	v_mfma_f32_16x16x32_bf16 v[64:67], v[178:181], v[210:213], v[64:67]
	v_mfma_f32_16x16x32_bf16 v[116:119], v[174:177], v[190:193], v[116:119]
	v_mfma_f32_16x16x32_bf16 v[112:115], v[182:185], v[190:193], v[112:115]
	v_mfma_f32_16x16x32_bf16 v[100:103], v[174:177], v[198:201], v[100:103]
	v_mfma_f32_16x16x32_bf16 v[96:99], v[182:185], v[198:201], v[96:99]
	v_mfma_f32_16x16x32_bf16 v[84:87], v[174:177], v[206:209], v[84:87]
	v_mfma_f32_16x16x32_bf16 v[80:83], v[182:185], v[206:209], v[80:83]
	v_mfma_f32_16x16x32_bf16 v[68:71], v[174:177], v[214:217], v[68:71]
	v_mfma_f32_16x16x32_bf16 v[64:67], v[182:185], v[214:217], v[64:67]
	s_setprio 0
	s_barrier
; #define PG8_STAGE(bufoff, gbase, voff) do { _Pragma("unroll") for (int _i = 0; _i < 2; ++_i) \
;         __builtin_amdgcn_global_load_lds((const unsigned*)((const char*)(gbase) + (voff)[_i]), (PG8_LAS unsigned*)(lds + (bufoff) + ldsw + _i * 8192), 16, 0, 0); } while (0)
; #define PG8_LDA(dst, b, h) do { _Pragma("unroll") for (int m = 0; m < 4; ++m) _Pragma("unroll") for (int k = 0; k < 2; ++k) dst[m][k] = *(const PG8_LAS bf16x8*)(lds + PG8_SA(b, h) + aoff + m * 2048 + k * 1024); } while (0)
; #define PG8_LDB(dst, b, h) do { _Pragma("unroll") for (int n = 0; n < 2; ++n) _Pragma("unroll") for (int k = 0; k < 2; ++k) dst[n][k] = *(const PG8_LAS bf16x8*)(lds + PG8_SB(b, h) + boff + n * 2048 + k * 1024); } while (0)
; template <class Epi, class Sched, bool ALIGN_EPI = false, bool SP2 = false>
; __device__ __forceinline__ void gemm_phase(PG8_LAS unsigned char* lds, const Gemm g, const Sched& S, const Epi& E) {
;     ...
;         for (int t = 0; t < nt; t += 2) {
;             const bool last = (t == nt - 2);
;             const char* a1 = cA + (size_t)(t + 1) * kstep;
;             const char* a2 = last ? nA : cA + (size_t)(t + 2) * kstep; const char* b2 = last ? nB : cB + (size_t)(t + 2) * kstep;
;             const char* a3 = a2 + kstep; const char* b3 = b2 + kstep;
;             if (last && has_next) S.a_ready(nxt);
;             if constexpr (SP2) {
;             PG8_LDB(B0, 0, 0); PG8_LDB(B1, 0, 1); PG8_SCHED; PG8_LDA(At, 0, 0); PG8_STAGE(PG8_SA(1, 1), a1 + hstep, voffA);
;             PG8_WAIT_V(8); PG8_WAIT_L(0); PG8_BAR; PG8_MMA(0, 0, At, B0); PG8_MMA(0, 1, At, B1); PG8_BAR; PG8_SCHED;
;             PG8_LDA(At, 0, 1); PG8_STAGE(PG8_SB(0, 0), b2, voffB); PG8_STAGE(PG8_SB(0, 1), b2 + hstep, voffB); PG8_STAGE(PG8_SA(0, 0), a2, voffA);
;             PG8_WAIT_V(8); PG8_WAIT_L(0); PG8_BAR; PG8_MMA(1, 0, At, B0); PG8_MMA(1, 1, At, B1); PG8_BAR; PG8_SCHED;
;             PG8_LDB(B0, 1, 0); PG8_LDB(B1, 1, 1); PG8_SCHED; PG8_LDA(At, 1, 0); PG8_STAGE(PG8_SA(0, 1), a2 + hstep, voffA);
;             PG8_WAIT_V(8); PG8_WAIT_L(0); PG8_BAR; PG8_MMA(0, 0, At, B0); PG8_MMA(0, 1, At, B1); PG8_BAR; PG8_SCHED;
;             PG8_LDA(At, 1, 1); PG8_STAGE(PG8_SB(1, 0), b3, voffB); PG8_STAGE(PG8_SB(1, 1), b3 + hstep, voffB); PG8_STAGE(PG8_SA(1, 0), a3, voffA);
;             PG8_WAIT_V(8); PG8_WAIT_L(0); PG8_BAR; PG8_MMA(1, 0, At, B0); PG8_MMA(1, 1, At, B1); PG8_BAR; PG8_SCHED;
	s_add_i32 s22, s45, s26
	v_lshl_add_u64 v[218:219], v[218:219], 0, s[2:3]
	s_mov_b32 m0, s22
	ds_read_b128 v[186:189], v158 offset:49152
	ds_read_b128 v[190:193], v158 offset:50176
	ds_read_b128 v[194:197], v158 offset:51200
	ds_read_b128 v[198:201], v158 offset:52224
	ds_read_b128 v[202:205], v158 offset:53248
	ds_read_b128 v[206:209], v158 offset:54272
	ds_read_b128 v[210:213], v158 offset:55296
	ds_read_b128 v[214:217], v158 offset:56320
	global_load_lds_dwordx4 v[218:219], off
	s_add_i32 m0, s22, 0x2000
	s_add_u32 s20, s20, 0x80080
	v_lshl_add_u64 v[218:219], v[220:221], 0, s[2:3]
	s_addc_u32 s21, s21, 0
	s_add_i32 s22, s46, s26
	global_load_lds_dwordx4 v[218:219], off
	v_lshl_add_u64 v[218:219], s[20:21], 0, v[132:133]
	s_mov_b32 m0, s22
	s_nop 0
	global_load_lds_dwordx4 v[218:219], off
	v_lshl_add_u64 v[218:219], s[20:21], 0, v[128:129]
	s_add_i32 m0, s22, 0x2000
	s_nop 0
	global_load_lds_dwordx4 v[218:219], off
	v_lshl_add_u64 v[218:219], v[222:223], 0, s[2:3]
	s_mov_b32 m0, s31
	s_nop 0
	global_load_lds_dwordx4 v[218:219], off
	v_lshl_add_u64 v[218:219], v[224:225], 0, s[2:3]
	s_mov_b32 m0, s33
	s_nop 0
	global_load_lds_dwordx4 v[218:219], off
	s_waitcnt vmcnt(8)
	s_waitcnt lgkmcnt(0)
	s_barrier
	s_setprio 1
	s_waitcnt lgkmcnt(0)
	v_mfma_f32_16x16x32_bf16 v[60:63], v[144:147], v[186:189], v[60:63]
	v_mfma_f32_16x16x32_bf16 v[56:59], v[160:163], v[186:189], v[56:59]
	v_mfma_f32_16x16x32_bf16 v[44:47], v[144:147], v[194:197], v[44:47]
	v_mfma_f32_16x16x32_bf16 v[40:43], v[160:163], v[194:197], v[40:43]
	v_mfma_f32_16x16x32_bf16 v[28:31], v[144:147], v[202:205], v[28:31]
	v_mfma_f32_16x16x32_bf16 v[24:27], v[160:163], v[202:205], v[24:27]
	v_mfma_f32_16x16x32_bf16 v[12:15], v[144:147], v[210:213], v[12:15]
	v_mfma_f32_16x16x32_bf16 v[8:11], v[160:163], v[210:213], v[8:11]
	v_mfma_f32_16x16x32_bf16 v[60:63], v[148:151], v[190:193], v[60:63]
	v_mfma_f32_16x16x32_bf16 v[56:59], v[164:167], v[190:193], v[56:59]
	v_mfma_f32_16x16x32_bf16 v[44:47], v[148:151], v[198:201], v[44:47]
	v_mfma_f32_16x16x32_bf16 v[40:43], v[164:167], v[198:201], v[40:43]
	v_mfma_f32_16x16x32_bf16 v[28:31], v[148:151], v[206:209], v[28:31]
	v_mfma_f32_16x16x32_bf16 v[24:27], v[164:167], v[206:209], v[24:27]
	v_mfma_f32_16x16x32_bf16 v[12:15], v[148:151], v[214:217], v[12:15]
	v_mfma_f32_16x16x32_bf16 v[8:11], v[164:167], v[214:217], v[8:11]
	s_setprio 0
	s_setprio 1
	v_mfma_f32_16x16x32_bf16 v[52:55], v[168:171], v[186:189], v[52:55]
	v_mfma_f32_16x16x32_bf16 v[48:51], v[178:181], v[186:189], v[48:51]
	v_mfma_f32_16x16x32_bf16 v[36:39], v[168:171], v[194:197], v[36:39]
	v_mfma_f32_16x16x32_bf16 v[32:35], v[178:181], v[194:197], v[32:35]
	v_mfma_f32_16x16x32_bf16 v[20:23], v[168:171], v[202:205], v[20:23]
	v_mfma_f32_16x16x32_bf16 v[16:19], v[178:181], v[202:205], v[16:19]
	v_mfma_f32_16x16x32_bf16 v[4:7], v[168:171], v[210:213], v[4:7]
	v_mfma_f32_16x16x32_bf16 v[0:3], v[178:181], v[210:213], v[0:3]
	v_mfma_f32_16x16x32_bf16 v[52:55], v[174:177], v[190:193], v[52:55]
	v_mfma_f32_16x16x32_bf16 v[48:51], v[182:185], v[190:193], v[48:51]
	v_mfma_f32_16x16x32_bf16 v[36:39], v[174:177], v[198:201], v[36:39]
	v_mfma_f32_16x16x32_bf16 v[32:35], v[182:185], v[198:201], v[32:35]
	v_mfma_f32_16x16x32_bf16 v[20:23], v[174:177], v[206:209], v[20:23]
	v_mfma_f32_16x16x32_bf16 v[16:19], v[182:185], v[206:209], v[16:19]
	v_mfma_f32_16x16x32_bf16 v[4:7], v[174:177], v[214:217], v[4:7]
	v_mfma_f32_16x16x32_bf16 v[0:3], v[182:185], v[214:217], v[0:3]
	s_setprio 0
	s_barrier
	s_add_i32 s44, s44, 2
	s_add_u32 s18, s18, 0x100
	s_addc_u32 s19, s19, 0
	s_add_u32 s42, s42, 0x100
	s_addc_u32 s43, s43, 0
	s_cmp_gt_u32 s44, 29
	s_cbranch_scc0 .LBB0_1712
	s_nop 0
	v_readfirstlane_b32 s9, v172
	s_nop 3
	s_lshr_b32 s9, s9, 6
	s_cmp_lt_u32 s9, 4
	s_cbranch_scc0 .Lprio_k6
	s_setprio 1

; #define PG8_STAGE(bufoff, gbase, voff) do { _Pragma("unroll") for (int _i = 0; _i < 2; ++_i) \
;         __builtin_amdgcn_global_load_lds((const unsigned*)((const char*)(gbase) + (voff)[_i]), (PG8_LAS unsigned*)(lds + (bufoff) + ldsw + _i * 8192), 16, 0, 0); } while (0)
; #define PG8_LDA(dst, b, h) do { _Pragma("unroll") for (int m = 0; m < 4; ++m) _Pragma("unroll") for (int k = 0; k < 2; ++k) dst[m][k] = *(const PG8_LAS bf16x8*)(lds + PG8_SA(b, h) + aoff + m * 2048 + k * 1024); } while (0)
; #define PG8_LDB(dst, b, h) do { _Pragma("unroll") for (int n = 0; n < 2; ++n) _Pragma("unroll") for (int k = 0; k < 2; ++k) dst[n][k] = *(const PG8_LAS bf16x8*)(lds + PG8_SB(b, h) + boff + n * 2048 + k * 1024); } while (0)
; #define PG8_MMA(ai, bj, At, Bt) do { __builtin_amdgcn_s_setprio(1); _Pragma("unroll") for (int m = 0; m < 4; ++m) _Pragma("unroll") for (int n = 0; n < 2; ++n) _Pragma("unroll") for (int k = 0; k < 2; ++k) \
;         acc[ai][bj][m][n] = __builtin_amdgcn_mfma_f32_16x16x32_bf16(Bt[n][k], At[m][k], acc[ai][bj][m][n], 0, 0, 0); __builtin_amdgcn_s_setprio(0); } while (0)
; #define PG8_WAIT_V(n) asm volatile("s_waitcnt vmcnt(" #n ")" ::: "memory")
; #define PG8_WAIT_L(n) asm volatile("s_waitcnt lgkmcnt(" #n ")" ::: "memory")
; template <class Epi, class Sched, bool ALIGN_EPI = false, bool SP2 = false>
; __device__ __forceinline__ void gemm_phase(PG8_LAS unsigned char* lds, const Gemm g, const Sched& S, const Epi& E) {
;     ...
;             const bool last = (t == nt - 2);
;             const char* a1 = cA + (size_t)(t + 1) * kstep;
;             const char* a2 = last ? nA : cA + (size_t)(t + 2) * kstep; const char* b2 = last ? nB : cB + (size_t)(t + 2) * kstep;
;             const char* a3 = a2 + kstep; const char* b3 = b2 + kstep;
;             if (last && has_next) S.a_ready(nxt);
;             if constexpr (SP2) {
;             PG8_LDB(B0, 0, 0); PG8_LDB(B1, 0, 1); PG8_SCHED; PG8_LDA(At, 0, 0); PG8_STAGE(PG8_SA(1, 1), a1 + hstep, voffA);
;             PG8_WAIT_V(8); PG8_WAIT_L(0); PG8_BAR; PG8_MMA(0, 0, At, B0); PG8_MMA(0, 1, At, B1); PG8_BAR; PG8_SCHED;
;             PG8_LDA(At, 0, 1); PG8_STAGE(PG8_SB(0, 0), b2, voffB); PG8_STAGE(PG8_SB(0, 1), b2 + hstep, voffB); PG8_STAGE(PG8_SA(0, 0), a2, voffA);
;             PG8_WAIT_V(8); PG8_WAIT_L(0); PG8_BAR; PG8_MMA(1, 0, At, B0); PG8_MMA(1, 1, At, B1); PG8_BAR; PG8_SCHED;
.LBB0_1956:
	ds_read_b128 v[140:143], v149
	ds_read_b128 v[152:155], v149 offset:1024
	ds_read_b128 v[156:159], v149 offset:2048
	ds_read_b128 v[160:163], v149 offset:3072
	ds_read_b128 v[164:167], v150
	ds_read_b128 v[168:171], v150 offset:1024
	ds_read_b128 v[172:175], v150 offset:2048
	ds_read_b128 v[176:179], v150 offset:3072
	s_add_u32 s22, s20, 0x100
	s_addc_u32 s23, s21, 0
	s_cmpk_eq_i32 s47, 0x54
	s_cselect_b32 s27, s5, s23
	s_cselect_b32 s26, s4, s22
	s_cselect_b32 s25, s19, s46
	s_cselect_b32 s24, s18, s45
	v_lshl_add_u64 v[144:145], s[20:21], 0, v[132:133]
	s_add_i32 m0, s31, 0xc000
	ds_read_b128 v[180:183], v151
	ds_read_b128 v[184:187], v151 offset:1024
	ds_read_b128 v[188:191], v151 offset:2048
	ds_read_b128 v[192:195], v151 offset:3072
	ds_read_b128 v[196:199], v151 offset:4096
	ds_read_b128 v[200:203], v151 offset:5120
	ds_read_b128 v[204:207], v151 offset:6144
	ds_read_b128 v[208:211], v151 offset:7168
	global_load_lds_dwordx4 v[144:145], off
	v_lshl_add_u64 v[144:145], s[20:21], 0, v[134:135]
	s_add_i32 m0, s31, 0xe000
	s_nop 0
	global_load_lds_dwordx4 v[144:145], off
	s_waitcnt vmcnt(8)
	s_waitcnt lgkmcnt(0)
	s_barrier
	s_setprio 1
	s_waitcnt lgkmcnt(0)
	v_mfma_f32_16x16x32_bf16 v[124:127], v[140:143], v[180:183], v[124:127]
	v_mfma_f32_16x16x32_bf16 v[120:123], v[156:159], v[180:183], v[120:123]
	v_mfma_f32_16x16x32_bf16 v[108:111], v[140:143], v[188:191], v[108:111]
	v_mfma_f32_16x16x32_bf16 v[104:107], v[156:159], v[188:191], v[104:107]
	v_mfma_f32_16x16x32_bf16 v[92:95], v[140:143], v[196:199], v[92:95]
	v_mfma_f32_16x16x32_bf16 v[88:91], v[156:159], v[196:199], v[88:91]
	v_mfma_f32_16x16x32_bf16 v[76:79], v[140:143], v[204:207], v[76:79]
	v_mfma_f32_16x16x32_bf16 v[72:75], v[156:159], v[204:207], v[72:75]
	v_mfma_f32_16x16x32_bf16 v[124:127], v[152:155], v[184:187], v[124:127]
	v_mfma_f32_16x16x32_bf16 v[120:123], v[160:163], v[184:187], v[120:123]
	v_mfma_f32_16x16x32_bf16 v[108:111], v[152:155], v[192:195], v[108:111]
	v_mfma_f32_16x16x32_bf16 v[104:107], v[160:163], v[192:195], v[104:107]
	v_mfma_f32_16x16x32_bf16 v[92:95], v[152:155], v[200:203], v[92:95]
	v_mfma_f32_16x16x32_bf16 v[88:91], v[160:163], v[200:203], v[88:91]
	v_mfma_f32_16x16x32_bf16 v[76:79], v[152:155], v[208:211], v[76:79]
	v_mfma_f32_16x16x32_bf16 v[72:75], v[160:163], v[208:211], v[72:75]
	s_setprio 0
	s_setprio 1
	v_mfma_f32_16x16x32_bf16 v[116:119], v[164:167], v[180:183], v[116:119]
	v_mfma_f32_16x16x32_bf16 v[112:115], v[172:175], v[180:183], v[112:115]
	v_mfma_f32_16x16x32_bf16 v[100:103], v[164:167], v[188:191], v[100:103]
	v_mfma_f32_16x16x32_bf16 v[96:99], v[172:175], v[188:191], v[96:99]
	v_mfma_f32_16x16x32_bf16 v[84:87], v[164:167], v[196:199], v[84:87]
	v_mfma_f32_16x16x32_bf16 v[80:83], v[172:175], v[196:199], v[80:83]
	v_mfma_f32_16x16x32_bf16 v[68:71], v[164:167], v[204:207], v[68:71]
	v_mfma_f32_16x16x32_bf16 v[64:67], v[172:175], v[204:207], v[64:67]
	v_mfma_f32_16x16x32_bf16 v[116:119], v[168:171], v[184:187], v[116:119]
	v_mfma_f32_16x16x32_bf16 v[112:115], v[176:179], v[184:187], v[112:115]
	v_mfma_f32_16x16x32_bf16 v[100:103], v[168:171], v[192:195], v[100:103]
	v_mfma_f32_16x16x32_bf16 v[96:99], v[176:179], v[192:195], v[96:99]
	v_mfma_f32_16x16x32_bf16 v[84:87], v[168:171], v[200:203], v[84:87]
	v_mfma_f32_16x16x32_bf16 v[80:83], v[176:179], v[200:203], v[80:83]
	v_mfma_f32_16x16x32_bf16 v[68:71], v[168:171], v[208:211], v[68:71]
	v_mfma_f32_16x16x32_bf16 v[64:67], v[176:179], v[208:211], v[64:67]
	s_setprio 0
	s_barrier
	s_add_i32 s20, s39, s30
	v_lshl_add_u64 v[144:145], s[24:25], 0, v[128:129]
	s_mov_b32 m0, s20
	ds_read_b128 v[180:183], v151 offset:16384
	ds_read_b128 v[184:187], v151 offset:17408
	ds_read_b128 v[188:191], v151 offset:18432
	ds_read_b128 v[192:195], v151 offset:19456
	ds_read_b128 v[196:199], v151 offset:20480
	ds_read_b128 v[200:203], v151 offset:21504
	ds_read_b128 v[204:207], v151 offset:22528
	ds_read_b128 v[208:211], v151 offset:23552
	global_load_lds_dwordx4 v[144:145], off
	s_add_i32 m0, s20, 0x2000
	s_add_u32 s20, s24, 0x160000
	v_lshl_add_u64 v[212:213], s[24:25], 0, v[130:131]
	s_addc_u32 s21, s25, 0
	s_add_i32 s48, s40, s30
	global_load_lds_dwordx4 v[212:213], off
	v_lshl_add_u64 v[214:215], s[20:21], 0, v[128:129]
	s_mov_b32 m0, s48
	v_lshl_add_u64 v[216:217], s[26:27], 0, v[130:131]
	global_load_lds_dwordx4 v[214:215], off
	v_lshl_add_u64 v[214:215], s[20:21], 0, v[130:131]
	s_add_i32 m0, s48, 0x2000
	s_nop 0
	global_load_lds_dwordx4 v[214:215], off
	v_lshl_add_u64 v[214:215], s[26:27], 0, v[128:129]
	s_mov_b32 m0, s31
	s_nop 0
	global_load_lds_dwordx4 v[214:215], off
	s_mov_b32 m0, s33
	s_nop 0
	global_load_lds_dwordx4 v[216:217], off
	s_waitcnt vmcnt(8)
	s_waitcnt lgkmcnt(0)
	s_barrier
; #define PG8_STAGE(bufoff, gbase, voff) do { _Pragma("unroll") for (int _i = 0; _i < 2; ++_i) \
;         __builtin_amdgcn_global_load_lds((const unsigned*)((const char*)(gbase) + (voff)[_i]), (PG8_LAS unsigned*)(lds + (bufoff) + ldsw + _i * 8192), 16, 0, 0); } while (0)
; #define PG8_LDA(dst, b, h) do { _Pragma("unroll") for (int m = 0; m < 4; ++m) _Pragma("unroll") for (int k = 0; k < 2; ++k) dst[m][k] = *(const PG8_LAS bf16x8*)(lds + PG8_SA(b, h) + aoff + m * 2048 + k * 1024); } while (0)
; #define PG8_LDB(dst, b, h) do { _Pragma("unroll") for (int n = 0; n < 2; ++n) _Pragma("unroll") for (int k = 0; k < 2; ++k) dst[n][k] = *(const PG8_LAS bf16x8*)(lds + PG8_SB(b, h) + boff + n * 2048 + k * 1024); } while (0)
; #define PG8_MMA(ai, bj, At, Bt) do { __builtin_amdgcn_s_setprio(1); _Pragma("unroll") for (int m = 0; m < 4; ++m) _Pragma("unroll") for (int n = 0; n < 2; ++n) _Pragma("unroll") for (int k = 0; k < 2; ++k) \
;         acc[ai][bj][m][n] = __builtin_amdgcn_mfma_f32_16x16x32_bf16(Bt[n][k], At[m][k], acc[ai][bj][m][n], 0, 0, 0); __builtin_amdgcn_s_setprio(0); } while (0)
; #define PG8_WAIT_V(n) asm volatile("s_waitcnt vmcnt(" #n ")" ::: "memory")
; #define PG8_WAIT_L(n) asm volatile("s_waitcnt lgkmcnt(" #n ")" ::: "memory")
; #define PG8_BAR __builtin_amdgcn_s_barrier()
; #define PG8_SCHED __builtin_amdgcn_sched_barrier(0)
; template <class Epi, class Sched, bool ALIGN_EPI = false, bool SP2 = false>
; __device__ __forceinline__ void gemm_phase(PG8_LAS unsigned char* lds, const Gemm g, const Sched& S, const Epi& E) {
;     ...
;             PG8_WAIT_V(8); PG8_WAIT_L(0); PG8_BAR; PG8_MMA(1, 0, At, B0); PG8_MMA(1, 1, At, B1); PG8_BAR; PG8_SCHED;
;             PG8_LDB(B0, 1, 0); PG8_LDB(B1, 1, 1); PG8_SCHED; PG8_LDA(At, 1, 0); PG8_STAGE(PG8_SA(0, 1), a2 + hstep, voffA);
;             PG8_WAIT_V(8); PG8_WAIT_L(0); PG8_BAR; PG8_MMA(0, 0, At, B0); PG8_MMA(0, 1, At, B1); PG8_BAR; PG8_SCHED;
;             PG8_LDA(At, 1, 1); PG8_STAGE(PG8_SB(1, 0), b3, voffB); PG8_STAGE(PG8_SB(1, 1), b3 + hstep, voffB); PG8_STAGE(PG8_SA(1, 0), a3, voffA);
	s_setprio 1
	s_waitcnt lgkmcnt(0)
	v_mfma_f32_16x16x32_bf16 v[60:63], v[140:143], v[180:183], v[60:63]
	v_mfma_f32_16x16x32_bf16 v[56:59], v[156:159], v[180:183], v[56:59]
	v_mfma_f32_16x16x32_bf16 v[44:47], v[140:143], v[188:191], v[44:47]
	v_mfma_f32_16x16x32_bf16 v[40:43], v[156:159], v[188:191], v[40:43]
	v_mfma_f32_16x16x32_bf16 v[28:31], v[140:143], v[196:199], v[28:31]
	v_mfma_f32_16x16x32_bf16 v[24:27], v[156:159], v[196:199], v[24:27]
	v_mfma_f32_16x16x32_bf16 v[12:15], v[140:143], v[204:207], v[12:15]
	v_mfma_f32_16x16x32_bf16 v[8:11], v[156:159], v[204:207], v[8:11]
	v_mfma_f32_16x16x32_bf16 v[60:63], v[152:155], v[184:187], v[60:63]
	v_mfma_f32_16x16x32_bf16 v[56:59], v[160:163], v[184:187], v[56:59]
	v_mfma_f32_16x16x32_bf16 v[44:47], v[152:155], v[192:195], v[44:47]
	v_mfma_f32_16x16x32_bf16 v[40:43], v[160:163], v[192:195], v[40:43]
	v_mfma_f32_16x16x32_bf16 v[28:31], v[152:155], v[200:203], v[28:31]
	v_mfma_f32_16x16x32_bf16 v[24:27], v[160:163], v[200:203], v[24:27]
	v_mfma_f32_16x16x32_bf16 v[12:15], v[152:155], v[208:211], v[12:15]
	v_mfma_f32_16x16x32_bf16 v[8:11], v[160:163], v[208:211], v[8:11]
	s_setprio 0
	s_setprio 1
	v_mfma_f32_16x16x32_bf16 v[52:55], v[164:167], v[180:183], v[52:55]
	v_mfma_f32_16x16x32_bf16 v[48:51], v[172:175], v[180:183], v[48:51]
	v_mfma_f32_16x16x32_bf16 v[36:39], v[164:167], v[188:191], v[36:39]
	v_mfma_f32_16x16x32_bf16 v[32:35], v[172:175], v[188:191], v[32:35]
	v_mfma_f32_16x16x32_bf16 v[20:23], v[164:167], v[196:199], v[20:23]
	v_mfma_f32_16x16x32_bf16 v[16:19], v[172:175], v[196:199], v[16:19]
	v_mfma_f32_16x16x32_bf16 v[4:7], v[164:167], v[204:207], v[4:7]
	v_mfma_f32_16x16x32_bf16 v[0:3], v[172:175], v[204:207], v[0:3]
	v_mfma_f32_16x16x32_bf16 v[52:55], v[168:171], v[184:187], v[52:55]
	v_mfma_f32_16x16x32_bf16 v[48:51], v[176:179], v[184:187], v[48:51]
	v_mfma_f32_16x16x32_bf16 v[36:39], v[168:171], v[192:195], v[36:39]
	v_mfma_f32_16x16x32_bf16 v[32:35], v[176:179], v[192:195], v[32:35]
	v_mfma_f32_16x16x32_bf16 v[20:23], v[168:171], v[200:203], v[20:23]
	v_mfma_f32_16x16x32_bf16 v[16:19], v[176:179], v[200:203], v[16:19]
	v_mfma_f32_16x16x32_bf16 v[4:7], v[168:171], v[208:211], v[4:7]
	v_mfma_f32_16x16x32_bf16 v[0:3], v[176:179], v[208:211], v[0:3]
	s_setprio 0
	s_barrier
	s_add_i32 s48, 0, 0x18000
	s_add_i32 s49, 0, 0x1c000
	v_add_u32_e32 v160, s48, v147
	v_add_u32_e32 v176, s49, v147
	ds_read_b128 v[140:143], v160
	ds_read_b128 v[152:155], v160 offset:1024
	ds_read_b128 v[156:159], v160 offset:2048
	ds_read_b128 v[160:163], v160 offset:3072
	ds_read_b128 v[164:167], v176
	ds_read_b128 v[168:171], v176 offset:1024
	ds_read_b128 v[172:175], v176 offset:2048
	ds_read_b128 v[176:179], v176 offset:3072
	s_add_u32 s20, s26, 0x160000
	s_addc_u32 s21, s27, 0
	s_mov_b32 m0, s34
	v_lshl_add_u64 v[218:219], s[20:21], 0, v[128:129]
	ds_read_b128 v[180:183], v151 offset:32768
	ds_read_b128 v[184:187], v151 offset:33792
	ds_read_b128 v[188:191], v151 offset:34816
	ds_read_b128 v[192:195], v151 offset:35840
	ds_read_b128 v[196:199], v151 offset:36864
	ds_read_b128 v[200:203], v151 offset:37888
	ds_read_b128 v[204:207], v151 offset:38912
	ds_read_b128 v[208:211], v151 offset:39936
	global_load_lds_dwordx4 v[218:219], off
	v_lshl_add_u64 v[218:219], s[20:21], 0, v[130:131]
	s_mov_b32 m0, s35
	s_nop 0
	global_load_lds_dwordx4 v[218:219], off
	s_waitcnt vmcnt(8)
	s_waitcnt lgkmcnt(0)
	s_barrier
	s_setprio 1
	s_waitcnt lgkmcnt(0)
	v_mfma_f32_16x16x32_bf16 v[124:127], v[140:143], v[180:183], v[124:127]
	v_mfma_f32_16x16x32_bf16 v[120:123], v[156:159], v[180:183], v[120:123]
	v_mfma_f32_16x16x32_bf16 v[108:111], v[140:143], v[188:191], v[108:111]
	v_mfma_f32_16x16x32_bf16 v[104:107], v[156:159], v[188:191], v[104:107]
	v_mfma_f32_16x16x32_bf16 v[92:95], v[140:143], v[196:199], v[92:95]
	v_mfma_f32_16x16x32_bf16 v[88:91], v[156:159], v[196:199], v[88:91]
	v_mfma_f32_16x16x32_bf16 v[76:79], v[140:143], v[204:207], v[76:79]
	v_mfma_f32_16x16x32_bf16 v[72:75], v[156:159], v[204:207], v[72:75]
	v_mfma_f32_16x16x32_bf16 v[124:127], v[152:155], v[184:187], v[124:127]
	v_mfma_f32_16x16x32_bf16 v[120:123], v[160:163], v[184:187], v[120:123]
	v_mfma_f32_16x16x32_bf16 v[108:111], v[152:155], v[192:195], v[108:111]
	v_mfma_f32_16x16x32_bf16 v[104:107], v[160:163], v[192:195], v[104:107]
	v_mfma_f32_16x16x32_bf16 v[92:95], v[152:155], v[200:203], v[92:95]
	v_mfma_f32_16x16x32_bf16 v[88:91], v[160:163], v[200:203], v[88:91]
	v_mfma_f32_16x16x32_bf16 v[76:79], v[152:155], v[208:211], v[76:79]
	v_mfma_f32_16x16x32_bf16 v[72:75], v[160:163], v[208:211], v[72:75]
	s_setprio 0
	s_setprio 1
	v_mfma_f32_16x16x32_bf16 v[116:119], v[164:167], v[180:183], v[116:119]
	v_mfma_f32_16x16x32_bf16 v[112:115], v[172:175], v[180:183], v[112:115]
	v_mfma_f32_16x16x32_bf16 v[100:103], v[164:167], v[188:191], v[100:103]
	v_mfma_f32_16x16x32_bf16 v[96:99], v[172:175], v[188:191], v[96:99]
	v_mfma_f32_16x16x32_bf16 v[84:87], v[164:167], v[196:199], v[84:87]
	v_mfma_f32_16x16x32_bf16 v[80:83], v[172:175], v[196:199], v[80:83]
	v_mfma_f32_16x16x32_bf16 v[68:71], v[164:167], v[204:207], v[68:71]
	v_mfma_f32_16x16x32_bf16 v[64:67], v[172:175], v[204:207], v[64:67]
	v_mfma_f32_16x16x32_bf16 v[116:119], v[168:171], v[184:187], v[116:119]
	v_mfma_f32_16x16x32_bf16 v[112:115], v[176:179], v[184:187], v[112:115]
	v_mfma_f32_16x16x32_bf16 v[100:103], v[168:171], v[192:195], v[100:103]
	v_mfma_f32_16x16x32_bf16 v[96:99], v[176:179], v[192:195], v[96:99]
	v_mfma_f32_16x16x32_bf16 v[84:87], v[168:171], v[200:203], v[84:87]
	v_mfma_f32_16x16x32_bf16 v[80:83], v[176:179], v[200:203], v[80:83]
	v_mfma_f32_16x16x32_bf16 v[68:71], v[168:171], v[208:211], v[68:71]
	v_mfma_f32_16x16x32_bf16 v[64:67], v[176:179], v[208:211], v[64:67]
	s_setprio 0
	s_barrier
; #define PG8_STAGE(bufoff, gbase, voff) do { _Pragma("unroll") for (int _i = 0; _i < 2; ++_i) \
;         __builtin_amdgcn_global_load_lds((const unsigned*)((const char*)(gbase) + (voff)[_i]), (PG8_LAS unsigned*)(lds + (bufoff) + ldsw + _i * 8192), 16, 0, 0); } while (0)
; #define PG8_LDA(dst, b, h) do { _Pragma("unroll") for (int m = 0; m < 4; ++m) _Pragma("unroll") for (int k = 0; k < 2; ++k) dst[m][k] = *(const PG8_LAS bf16x8*)(lds + PG8_SA(b, h) + aoff + m * 2048 + k * 1024); } while (0)
; #define PG8_WAIT_V(n) asm volatile("s_waitcnt vmcnt(" #n ")" ::: "memory")
; template <class Epi, class Sched, bool ALIGN_EPI = false, bool SP2 = false>
; __device__ __forceinline__ void gemm_phase(PG8_LAS unsigned char* lds, const Gemm g, const Sched& S, const Epi& E) {
;     ...
;             PG8_LDA(At, 1, 1); PG8_STAGE(PG8_SB(1, 0), b3, voffB); PG8_STAGE(PG8_SB(1, 1), b3 + hstep, voffB); PG8_STAGE(PG8_SA(1, 0), a3, voffA);
;             PG8_WAIT_V(8); PG8_WAIT_L(0); PG8_BAR; PG8_MMA(1, 0, At, B0); PG8_MMA(1, 1, At, B1); PG8_BAR; PG8_SCHED;
;             } else {
;             PG8_LDB(B0, 0, 0); PG8_SCHED; PG8_LDA(At, 0, 0); PG8_STAGE(PG8_SA(1, 1), a1 + hstep, voffA);
;             PG8_WAIT_L(8); PG8_BAR; PG8_WAIT_L(0); PG8_MMA(0, 0, At, B0); PG8_BAR; PG8_SCHED;
;             PG8_LDB(B1, 0, 1); PG8_STAGE(PG8_SB(0, 0), b2, voffB);
;             PG8_BAR; PG8_WAIT_L(0); PG8_MMA(0, 1, At, B1); PG8_BAR;
;             PG8_LDA(At, 0, 1); PG8_STAGE(PG8_SA(0, 0), a2, voffA);
;             PG8_BAR; PG8_WAIT_L(0); PG8_MMA(1, 0, At, B0); PG8_BAR; PG8_SCHED;
;             PG8_STAGE(PG8_SB(0, 1), b2 + hstep, voffB);
;             PG8_WAIT_V(6); PG8_BAR; PG8_MMA(1, 1, At, B1); PG8_BAR;
;             PG8_LDB(B0, 1, 0); PG8_SCHED; PG8_LDA(At, 1, 0); PG8_STAGE(PG8_SA(0, 1), a2 + hstep, voffA);
;             PG8_WAIT_L(8); PG8_BAR; PG8_WAIT_L(0); PG8_MMA(0, 0, At, B0); PG8_BAR; PG8_SCHED;
;             PG8_LDB(B1, 1, 1); PG8_STAGE(PG8_SB(1, 0), b3, voffB);
;             PG8_BAR; PG8_WAIT_L(0); PG8_MMA(0, 1, At, B1); PG8_BAR;
;             PG8_LDA(At, 1, 1); PG8_STAGE(PG8_SA(1, 0), a3, voffA);
;             PG8_BAR; PG8_WAIT_L(0); PG8_MMA(1, 0, At, B0); PG8_BAR; PG8_SCHED;
;             PG8_STAGE(PG8_SB(1, 1), b3 + hstep, voffB);
;             PG8_WAIT_V(6); PG8_BAR; PG8_MMA(1, 1, At, B1); PG8_BAR;
;             }
;         }
;         if constexpr (ALIGN_EPI) { if (wr == 0) PG8_BAR; }
	s_add_i32 s20, s48, s30
	v_lshl_add_u64 v[144:145], v[144:145], 0, s[6:7]
	s_mov_b32 m0, s20
	ds_read_b128 v[180:183], v151 offset:49152
	ds_read_b128 v[184:187], v151 offset:50176
	ds_read_b128 v[188:191], v151 offset:51200
	ds_read_b128 v[192:195], v151 offset:52224
	ds_read_b128 v[196:199], v151 offset:53248
	ds_read_b128 v[200:203], v151 offset:54272
	ds_read_b128 v[204:207], v151 offset:55296
	ds_read_b128 v[208:211], v151 offset:56320
	global_load_lds_dwordx4 v[144:145], off
	s_add_i32 m0, s20, 0x2000
	s_add_u32 s20, s24, 0x160080
	v_lshl_add_u64 v[144:145], v[212:213], 0, s[6:7]
	s_addc_u32 s21, s25, 0
	s_add_i32 s24, s49, s30
	global_load_lds_dwordx4 v[144:145], off
	v_lshl_add_u64 v[144:145], s[20:21], 0, v[128:129]
	s_mov_b32 m0, s24
	s_nop 0
	global_load_lds_dwordx4 v[144:145], off
	v_lshl_add_u64 v[144:145], s[20:21], 0, v[130:131]
	s_add_i32 m0, s24, 0x2000
	s_nop 0
	global_load_lds_dwordx4 v[144:145], off
	v_lshl_add_u64 v[144:145], v[214:215], 0, s[6:7]
	s_mov_b32 m0, s37
	s_nop 0
	global_load_lds_dwordx4 v[144:145], off
	v_lshl_add_u64 v[144:145], v[216:217], 0, s[6:7]
	s_mov_b32 m0, s38
	s_nop 0
	global_load_lds_dwordx4 v[144:145], off
	s_waitcnt vmcnt(8)
	s_waitcnt lgkmcnt(0)
	s_barrier
	s_setprio 1
	s_waitcnt lgkmcnt(0)
	v_mfma_f32_16x16x32_bf16 v[60:63], v[140:143], v[180:183], v[60:63]
	v_mfma_f32_16x16x32_bf16 v[56:59], v[156:159], v[180:183], v[56:59]
	v_mfma_f32_16x16x32_bf16 v[44:47], v[140:143], v[188:191], v[44:47]
	v_mfma_f32_16x16x32_bf16 v[40:43], v[156:159], v[188:191], v[40:43]
	v_mfma_f32_16x16x32_bf16 v[28:31], v[140:143], v[196:199], v[28:31]
	v_mfma_f32_16x16x32_bf16 v[24:27], v[156:159], v[196:199], v[24:27]
	v_mfma_f32_16x16x32_bf16 v[12:15], v[140:143], v[204:207], v[12:15]
	v_mfma_f32_16x16x32_bf16 v[8:11], v[156:159], v[204:207], v[8:11]
	v_mfma_f32_16x16x32_bf16 v[60:63], v[152:155], v[184:187], v[60:63]
	v_mfma_f32_16x16x32_bf16 v[56:59], v[160:163], v[184:187], v[56:59]
	v_mfma_f32_16x16x32_bf16 v[44:47], v[152:155], v[192:195], v[44:47]
	v_mfma_f32_16x16x32_bf16 v[40:43], v[160:163], v[192:195], v[40:43]
	v_mfma_f32_16x16x32_bf16 v[28:31], v[152:155], v[200:203], v[28:31]
	v_mfma_f32_16x16x32_bf16 v[24:27], v[160:163], v[200:203], v[24:27]
	v_mfma_f32_16x16x32_bf16 v[12:15], v[152:155], v[208:211], v[12:15]
	v_mfma_f32_16x16x32_bf16 v[8:11], v[160:163], v[208:211], v[8:11]
	s_setprio 0
	s_setprio 1
	v_mfma_f32_16x16x32_bf16 v[52:55], v[164:167], v[180:183], v[52:55]
	v_mfma_f32_16x16x32_bf16 v[48:51], v[172:175], v[180:183], v[48:51]
	v_mfma_f32_16x16x32_bf16 v[36:39], v[164:167], v[188:191], v[36:39]
	v_mfma_f32_16x16x32_bf16 v[32:35], v[172:175], v[188:191], v[32:35]
	v_mfma_f32_16x16x32_bf16 v[20:23], v[164:167], v[196:199], v[20:23]
	v_mfma_f32_16x16x32_bf16 v[16:19], v[172:175], v[196:199], v[16:19]
	v_mfma_f32_16x16x32_bf16 v[4:7], v[164:167], v[204:207], v[4:7]
	v_mfma_f32_16x16x32_bf16 v[0:3], v[172:175], v[204:207], v[0:3]
	v_mfma_f32_16x16x32_bf16 v[52:55], v[168:171], v[184:187], v[52:55]
	v_mfma_f32_16x16x32_bf16 v[48:51], v[176:179], v[184:187], v[48:51]
	v_mfma_f32_16x16x32_bf16 v[36:39], v[168:171], v[192:195], v[36:39]
	v_mfma_f32_16x16x32_bf16 v[32:35], v[176:179], v[192:195], v[32:35]
	v_mfma_f32_16x16x32_bf16 v[20:23], v[168:171], v[200:203], v[20:23]
	v_mfma_f32_16x16x32_bf16 v[16:19], v[176:179], v[200:203], v[16:19]
	v_mfma_f32_16x16x32_bf16 v[4:7], v[168:171], v[208:211], v[4:7]
	v_mfma_f32_16x16x32_bf16 v[0:3], v[176:179], v[208:211], v[0:3]
	s_setprio 0
	s_barrier
	s_add_i32 s47, s47, 2
	s_add_u32 s45, s45, 0x100
	s_addc_u32 s46, s46, 0
	s_cmpk_gt_u32 s47, 0x55
	s_mov_b64 s[20:21], s[22:23]
	s_cbranch_scc0 .LBB0_1956
	s_nop 0
	v_readfirstlane_b32 s20, v172
	s_nop 3
	s_lshr_b32 s20, s20, 6
	s_cmp_lt_u32 s20, 4
	s_cbranch_scc0 .Lprio_k7
	s_setprio 1
.Lprio_k7:
	s_and_b64 vcc, exec, s[8:9]
	s_cbranch_vccz .LBB0_1959
	s_barrier
